# step4 rewrite plus L2 prefetch of next unit rows in rwkv_prep
# speedup vs baseline: 1.0067x; 1.0067x over previous
; #define LAS __attribute__((address_space(3)))
; #define PF_AR(N_) do { const size_t cq_ = CQ_(N_); const bf16* ua = AHb + cq_ * 1024; const bf16* ur = RHb + cq_ * 1024; pA[0] = GLD(bf16x8, ua, oA); pA[1] = GLD(bf16x8, ua, oA + 64u); pR[0] = GLD(bf16x8, ur, oA); pR[1] = GLD(bf16x8, ur, oA + 64u); } while (0)
; #define PF_BG(N_) do { const size_t cq_ = CQ_(N_); const bf16* ub = BKb + cq_ * 2048; _Pragma("unroll") for (int jb = 0; jb < 4; ++jb) pB[jb] = GLD(bf16x8, ub, oB + (unsigned)jb * 1024u); pG = GLD(float, G15b + cq_ * 64, oG); } while (0)
; __device__ __forceinline__ void rwkv_scan(const Args& c, int bx, int l, LAS unsigned char* lds, bool dry) {
;     int tid_ = threadIdx.x; asm volatile("" : "+v"(tid_)); unsigned char* wsl = c.ws; asm volatile("" : "+s"(wsl)); int z_ = 0; asm volatile("" : "+s"(z_));
;     const int tid = tid_, L = tid & 63, w = __builtin_amdgcn_readfirstlane(tid >> 6), r = L & 15, q4 = L >> 4;
;     const int hh = bx * 2 + (w >> 2), wq = w & 3, b = hh >> 3, h = hh & 7;
;     LAS unsigned char* wl = lds + w * 5376;
;     LAS bf16* St = (LAS bf16*)wl;
;     LAS bf16* UVl = (LAS bf16*)wl;
;     LAS float* Xl = (LAS float*)(wl + 2304);
;     LAS float* Nl = (LAS float*)(wl + 3392);
;     LAS float* Gl = (LAS float*)(wl + 4416);
;     LAS bf16* XRl = (LAS bf16*)(wl + 4672);
;     const bf16* AHb = (const bf16*)(wsl + WS_RW); const bf16* RHb = (const bf16*)(wsl + WS_RW + 16 * MiB); const bf16* BKb = (const bf16*)(wsl + WS_RW + 32 * MiB);
;     const float* NMb = (const float*)(wsl + WS_RW + 64 * MiB); const bf16* NRb = (const bf16*)(wsl + WS_RW + 98 * MiB); const float* G15b = (const float*)(wsl + WS_RW + 96 * MiB);
;     const bf16* VNb = (const bf16*)(wsl + WS_WR0); const bf16* VBb = (const bf16*)(wsl + WS_WR1);
;     float* Yb = (float*)(wsl + WS_P) + (size_t)b * T * (PW / 2) + h * 64 + 16 * wq;
;     f32x4 ST[4];
; #pragma unroll
;     for (int jb = 0; jb < 4; ++jb) ST[jb] = (f32x4){0.f, 0.f, 0.f, 0.f};
;     bf16x8 pA[2], pR[2], pB[4], pNR; f32x4 pN; u32x2v pC; u32x4v pVB[2]; float pG;
;     const int row = L & 15;
;     ...
;     const unsigned oA = (unsigned)(r * 64 + q4 * 8) * 2u, oB = (unsigned)(r * 32 + q4 * 8) * 2u, oC = (unsigned)(r * 64 + 16 * wq + 4 * q4) * 2u, oN = (unsigned)L * 16u, oV = (unsigned)(16 * wq + row) * 32u, oG = (unsigned)L * 4u;
;     ...
;     PF_AR(0); PF_C(0); PF_BG(0); PF_N(0); PF_NR(0); PF_VB(0);
.LBB0_230:
	s_andn2_b64 vcc, exec, s[2:3]
	s_cbranch_vccnz .LBB0_236
	v_readlane_b32 s0, v252, 57
	v_mov_b32_e32 v2, v179
	v_readlane_b32 s2, v252, 59
	v_readlane_b32 s3, v252, 60
	s_mov_b32 s0, s15
	v_readlane_b32 s4, v251, 60
	v_readfirstlane_b32 s14, v2
	s_ashr_i32 s0, s14, 8
	s_add_i32 s0, s0, s4
	s_ashr_i32 s4, s0, 3
	v_readlane_b32 s1, v252, 58
	s_ashr_i32 s5, s4, 31
	s_ashr_i32 s1, s14, 6
	s_and_b32 s22, s0, 7
	s_lshl_b64 s[12:13], s[4:5], 10
	v_and_b32_e32 v137, 15, v2
	s_mul_i32 s0, s1, 0x1500
	s_lshl_b32 s1, s1, 4
	v_bfe_u32 v45, v2, 4, 2
	s_or_b32 s12, s12, s22
	s_add_i32 s0, s0, 0
	s_and_b32 s1, s1, 48
	v_lshlrev_b32_e32 v3, 6, v137
	v_lshlrev_b32_e32 v154, 3, v45
	s_lshl_b64 s[16:17], s[12:13], 10
	s_lshl_b64 s[18:19], s[12:13], 11
	v_or_b32_e32 v0, v154, v3
	v_lshlrev_b32_e32 v141, 2, v45
	s_add_u32 s18, s2, s18
	v_and_b32_e32 v44, 63, v2
	v_lshlrev_b32_e32 v0, 1, v0
	v_and_b32_e32 v46, 48, v2
	v_or3_b32 v2, v3, s1, v141
	s_addc_u32 s19, s3, s19
	v_or_b32_e32 v34, v3, v46
	v_lshlrev_b32_e32 v36, 1, v2
	v_lshl_add_u64 v[2:3], s[18:19], 0, v[0:1]
	s_mov_b32 s11, 0x1d800000
	s_mov_b64 s[20:21], 0x1d800000
	v_add_co_u32_e32 v6, vcc, s11, v2
	v_lshl_add_u64 v[4:5], v[2:3], 0, s[20:21]
	s_nop 0
	v_addc_co_u32_e32 v7, vcc, 0, v3, vcc
	s_mov_b64 s[20:21], 0x1e800000
	s_mov_b32 s11, 0x1e800000
	flat_load_dwordx4 v[26:29], v[6:7]
	flat_load_dwordx4 v[22:25], v[4:5] offset:64
	v_lshl_add_u64 v[4:5], v[2:3], 0, s[20:21]
	v_add_co_u32_e32 v2, vcc, s11, v2
	v_mov_b32_e32 v37, v1
	s_nop 0
	v_addc_co_u32_e32 v3, vcc, 0, v3, vcc
	s_lshl_b64 s[20:21], s[12:13], 8
	flat_load_dwordx4 v[18:21], v[2:3]
	flat_load_dwordx4 v[14:17], v[4:5] offset:64
	v_lshl_add_u64 v[2:3], s[18:19], 0, v[36:37]
	s_mov_b32 s11, 0x25800000
	s_add_u32 s20, s2, s20
	v_lshlrev_b32_e32 v38, 2, v44
	v_add_co_u32_e32 v2, vcc, s11, v2
	s_addc_u32 s21, s3, s21
	v_mov_b32_e32 v39, v1
	s_lshl_b64 s[12:13], s[12:13], 12
	v_addc_co_u32_e32 v3, vcc, 0, v3, vcc
	v_lshl_add_u64 v[4:5], s[20:21], 0, v[38:39]
	s_mov_b32 s11, 0x23800000
	s_add_u32 s12, s2, s12
	v_lshlrev_b32_e32 v40, 4, v44
	v_add_co_u32_e32 v4, vcc, s11, v4
	s_addc_u32 s13, s3, s13
	v_mov_b32_e32 v41, v1
	v_addc_co_u32_e32 v5, vcc, 0, v5, vcc
	flat_load_dwordx2 v[114:115], v[2:3]
	flat_load_dword v153, v[4:5]
	v_lshl_add_u64 v[2:3], s[12:13], 0, v[40:41]
	s_mov_b32 s11, 0x21800000
	s_add_u32 s12, s2, s16
	v_mov_b32_e32 v35, v1
	v_add_co_u32_e32 v2, vcc, s11, v2
	s_addc_u32 s13, s3, s17
	v_or_b32_e32 v8, s1, v137
	v_addc_co_u32_e32 v3, vcc, 0, v3, vcc
	v_lshl_add_u64 v[4:5], s[12:13], 0, v[34:35]
	s_mov_b32 s11, 0x23a00000
	v_lshlrev_b32_e32 v42, 5, v8
	v_add_co_u32_e32 v4, vcc, s11, v4
	v_mov_b32_e32 v43, v1
	s_nop 0
	v_addc_co_u32_e32 v5, vcc, 0, v5, vcc
	v_lshl_add_u64 v[6:7], s[18:19], 0, v[42:43]
	s_mov_b64 s[12:13], 0x27800000
	s_mov_b32 s11, 0x27800000
	v_lshl_add_u64 v[8:9], v[6:7], 0, s[12:13]
	v_add_co_u32_e32 v6, vcc, s11, v6
	flat_load_dwordx4 v[30:33], v[2:3]
	s_nop 0
	flat_load_dwordx4 v[2:5], v[4:5]
	v_addc_co_u32_e32 v7, vcc, 0, v7, vcc
	flat_load_dwordx4 v[10:13], v[6:7]
	s_nop 0
	flat_load_dwordx4 v[6:9], v[8:9] offset:16
	v_mov_b32_e32 v37, s0
	s_movk_i32 s11, 0x90
	v_mad_u32_u24 v37, v137, s11, v37
	s_movk_i32 s12, 0xff74
	v_add_u32_e32 v155, v37, v154
	s_lshl_b32 s11, s22, 12
	v_mad_i32_i24 v37, v137, s12, v37
	s_lshl_b64 s[12:13], s[4:5], 22
	s_lshl_b32 s18, s22, 10
	s_or_b32 s11, s12, s11
	v_or_b32_e32 v116, s11, v34
	s_add_u32 s11, s11, 0x21808000
	s_mul_i32 s7, s4, 0x1c00000
	s_addc_u32 s12, s13, 0
	s_mul_hi_i32 s6, s4, 0x1c00000
	v_or_b32_e32 v118, s11, v40
	s_add_u32 s11, s7, 0xa800000
	v_add_u32_e32 v156, s0, v40
	v_mul_i32_i24_e32 v43, -12, v44
	v_mul_u32_u24_e32 v44, 0x110, v45
	v_mov_b32_e32 v119, s12
	s_addc_u32 s12, s6, 0
	v_mul_hi_u32_u24_e32 v40, 0x3800, v137
	v_mul_u32_u24_e32 v45, 0x3800, v137
	v_or_b32_e32 v121, s12, v40
	v_or_b32_e32 v40, s11, v45
	s_lshl_b32 s11, s22, 8
	v_or_b32_e32 v40, s11, v40
	s_and_b32 s12, s14, 0xc0
	v_mov_b32_e32 v117, s13
	v_or3_b32 v120, v40, s12, v46
	s_lshl_b64 s[12:13], s[4:5], 21
	s_lshl_b32 s14, s22, 11
	s_lshl_b64 s[16:17], s[4:5], 20
	s_or_b32 s12, s12, s14
	s_or_b32 s14, s16, s18
	s_add_u32 s14, s14, 0x23a02000
	s_addc_u32 s16, s17, 0
	s_lshl_b64 s[4:5], s[4:5], 18
	s_or_b32 s4, s4, s11
	s_add_u32 s4, s4, 0x23800800
	s_addc_u32 s5, s5, 0
	v_add_u32_e32 v157, s0, v46
	v_or_b32_e32 v126, s4, v38
	s_add_u32 s4, s12, 0x25804000
	v_mul_u32_u24_e32 v35, 0x90, v137
	v_sub_u32_e32 v158, v157, v154
	v_mul_u32_u24_e32 v39, 40, v137
	v_mul_u32_u24_e32 v41, 0x44, v137
	v_or_b32_e32 v124, s14, v34
	v_mov_b32_e32 v127, s5
	s_addc_u32 s5, s13, 0
	v_mov_b32_e32 v34, 0
	v_mul_u32_u24_e32 v160, 0x50, v137
	v_or_b32_e32 v122, s12, v42
	v_mov_b32_e32 v123, s13
	v_mov_b32_e32 v125, s16
	v_or_b32_e32 v128, s12, v0
	v_mov_b32_e32 v129, s13
	v_or_b32_e32 v130, s4, v36
	v_mov_b32_e32 v131, s5
	s_movk_i32 s4, 0x7f
	v_add_u32_e32 v159, v157, v35
	v_add_u32_e32 v161, v37, v44
	v_add_u32_e32 v147, v158, v39
	v_add_u32_e32 v162, s0, v41
	v_add_u32_e32 v151, v156, v43
	v_mov_b32_e32 v35, v34
	v_mov_b32_e32 v36, v34
	v_mov_b32_e32 v37, v34
	v_mov_b32_e32 v42, v34
	v_mov_b32_e32 v43, v34
	v_mov_b32_e32 v44, v34
	v_mov_b32_e32 v45, v34
	v_mov_b32_e32 v46, v34
	v_mov_b32_e32 v47, v34
	v_mov_b32_e32 v48, v34
	v_mov_b32_e32 v49, v34
	v_mov_b32_e32 v38, v34
	v_mov_b32_e32 v39, v34
	v_mov_b32_e32 v40, v34
	v_mov_b32_e32 v41, v34
	v_mov_b32_e32 v0, v34
	v_mov_b32_e32 v68, v34
	v_mov_b32_e32 v69, v34
	s_mov_b64 s[16:17], 0x2000
	s_mov_b64 s[18:19], 0x8000
	s_mov_b64 s[20:21], 0x4000
	s_waitcnt vmcnt(0)
; #define LAS __attribute__((address_space(3)))
; #define MFMA16(a, b, c) __builtin_amdgcn_mfma_f32_16x16x32_bf16(a, b, c, 0, 0, 0)
; __device__ __forceinline__ unsigned pk2(float lo, float hi) { f32x2_t v = {lo, hi}; bf16x2_t b = __builtin_convertvector(v, bf16x2_t); return __builtin_bit_cast(unsigned, b); }
; #define PF_AR(N_) do { const size_t cq_ = CQ_(N_); const bf16* ua = AHb + cq_ * 1024; const bf16* ur = RHb + cq_ * 1024; pA[0] = GLD(bf16x8, ua, oA); pA[1] = GLD(bf16x8, ua, oA + 64u); pR[0] = GLD(bf16x8, ur, oA); pR[1] = GLD(bf16x8, ur, oA + 64u); } while (0)
; #define PF_N(N_) do { pN = GLD(f32x4, NMb + CQ_(N_) * 1024, oN); } while (0)
; #define PF_C(N_) do { pC = GLD(u32x2v, VNb + CQ_(N_) * 1024, oC); } while (0)
; __device__ __forceinline__ void rwkv_scan(const Args& c, int bx, int l, LAS unsigned char* lds, bool dry) {
;     ...
;     for (int n = 0; n < T / 16; ++n) {
;         const bool more = (n + 1 < T / 16);
;         *(LAS f32x4*)(Nl + L * 4) = pN;
;         if (more) PF_N(n + 1);
; #pragma unroll
;         for (int jb = 0; jb < 4; ++jb) { u32x2v o; o.x = pk2(ST[jb][0], ST[jb][1]); o.y = pk2(ST[jb][2], ST[jb][3]); *(LAS u32x2v*)(St + r * 72 + 16 * jb + 4 * q4) = o; }
;         FENCE();
;         {
;             f32x4 xa = (f32x4){bflo(pC.x), bfhi(pC.x), bflo(pC.y), bfhi(pC.y)}, xr = (f32x4){0.f, 0.f, 0.f, 0.f};
; #pragma unroll
;             for (int ks = 0; ks < 2; ++ks) { const bf16x8 fs = *(const LAS bf16x8*)(St + r * 72 + ks * 32 + q4 * 8); xa = MFMA16(fs, pA[ks], xa); xr = MFMA16(fs, pR[ks], xr); }
; #pragma unroll
;             for (int e = 0; e < 4; ++e) Xl[(4 * q4 + e) * 17 + r] = xa[e];
;             u32x2v xo; xo.x = pk2(xr[0], xr[1]); xo.y = pk2(xr[2], xr[3]); *(LAS u32x2v*)(XRl + r * 20 + 4 * q4) = xo;
;         }
;         if (more) { PF_AR(n + 1); PF_C(n + 1); }
;         FENCE();
;         float uu[16];
;         {
;             const LAS float* xrow = Xl + row * 17;
; #pragma unroll
;             for (int t = 0; t < 16; ++t) uu[t] = xrow[t];
; #pragma unroll
;             for (int s0 = 0; s0 < 15; ++s0) {
; #pragma unroll
;                 for (int t4 = (s0 + 1) & ~3; t4 < 16; t4 += 4) {
;                     const f32x4 nab = *(const LAS f32x4*)(Nl + s0 * 16 + t4);
; #pragma unroll
;                     for (int e = 0; e < 4; ++e) if (t4 + e > s0) uu[t4 + e] += uu[s0] * nab[e];
;                 }
;             }
;         }
.LBB0_232:
	v_lshl_add_u64 v[50:51], s[2:3], 0, v[116:117]
	s_mov_b32 s5, 0x1f800000
	v_add_co_u32_e32 v50, vcc, s5, v50
	v_cvt_pk_bf16_f32 v66, v42, v43
	s_nop 0
	v_addc_co_u32_e32 v51, vcc, 0, v51, vcc
	global_load_dwordx4 v[62:65], v[50:51], off
	global_load_dwordx4 v[58:61], v[50:51], off offset:1024
	global_load_dwordx4 v[54:57], v[50:51], off offset:2048
	s_nop 0
	global_load_dwordx4 v[50:53], v[50:51], off offset:3072
	s_waitcnt vmcnt(14) lgkmcnt(0)
	ds_write_b128 v156, v[30:33] offset:3392
	v_lshl_add_u64 v[30:31], s[2:3], 0, v[118:119]
	v_cvt_pk_bf16_f32 v67, v44, v45
	v_cvt_pk_bf16_f32 v70, v46, v47
	v_cvt_pk_bf16_f32 v71, v48, v49
	global_load_dwordx4 v[30:33], v[30:31], off
	ds_write2_b64 v155, v[66:67], v[70:71] offset1:4
	v_cvt_pk_bf16_f32 v66, v38, v39
	v_cvt_pk_bf16_f32 v67, v40, v41
	v_cvt_pk_bf16_f32 v70, v34, v0
	v_cvt_pk_bf16_f32 v71, v68, v69
	ds_write2_b64 v155, v[66:67], v[70:71] offset0:8 offset1:12
	ds_read_b128 v[70:73], v159
	s_waitcnt vmcnt(10)
	v_lshlrev_b32_e32 v66, 16, v114
	v_and_b32_e32 v67, 0xffff0000, v114
	v_lshlrev_b32_e32 v68, 16, v115
	v_and_b32_e32 v69, 0xffff0000, v115
	s_waitcnt lgkmcnt(0)
	v_mfma_f32_16x16x32_bf16 v[18:21], v[70:73], v[18:21], 0
	v_add_u32_e32 v163, 0x800, v161
	s_mov_b32 s5, 0x1d804000
	v_add_u32_e32 v164, 0x900, v162
	v_mfma_f32_16x16x32_bf16 v[26:29], v[70:73], v[26:29], v[66:69]
	v_mov_b32_e32 v172, s0
	v_add_u32_e32 v165, 0x908, v162
	v_add_u32_e32 v166, 0x938, v162
	ds_read_b128 v[66:69], v159 offset:64
	s_waitcnt lgkmcnt(0)
	v_mfma_f32_16x16x32_bf16 v[14:17], v[66:69], v[14:17], v[18:21]
	v_add_u32_e32 v168, 0x910, v162
	v_add_u32_e32 v167, 0x918, v162
	v_add_u32_e32 v169, 0x920, v162
	v_mfma_f32_16x16x32_bf16 v[22:25], v[66:69], v[22:25], v[26:29]
	s_nop 3
	v_cvt_pk_bf16_f32 v14, v14, v15
	v_cvt_pk_bf16_f32 v15, v16, v17
	s_nop 1
	ds_write2_b32 v163, v22, v23 offset0:64 offset1:81
	ds_write2_b32 v163, v24, v25 offset0:98 offset1:115
	ds_write_b64 v147, v[14:15] offset:4672
	v_lshl_add_u64 v[14:15], s[2:3], 0, v[128:129]
	v_add_co_u32_e32 v16, vcc, s5, v14
	s_mov_b32 s5, 0x1e804000
	s_nop 0
	v_addc_co_u32_e32 v17, vcc, 0, v15, vcc
	v_add_co_u32_e32 v14, vcc, s5, v14
	v_lshl_add_u64 v[66:67], s[2:3], 0, v[130:131]
	s_nop 0
	v_addc_co_u32_e32 v15, vcc, 0, v15, vcc
	global_load_dwordx4 v[26:29], v[16:17], off
	global_load_dwordx4 v[22:25], v[16:17], off offset:64
	global_load_dwordx4 v[18:21], v[14:15], off
	s_nop 0
	global_load_dwordx4 v[14:17], v[14:15], off offset:64
	v_add_u32_e32 v170, 0x928, v162
	global_load_dwordx2 v[114:115], v[66:67], off
	ds_read2_b32 v[132:133], v164 offset1:1
	ds_read_b128 v[70:73], v172 offset:3392
	ds_read_b128 v[80:83], v172 offset:3408
	ds_read_b128 v[96:99], v172 offset:3424
	ds_read_b128 v[66:69], v172 offset:3440
	v_add_u32_e32 v171, 0x930, v162
	s_mov_b32 s5, 0x27804000
	s_mov_b64 s[12:13], 0x38000
	s_waitcnt lgkmcnt(0)
	v_fma_f32 v0, v132, v71, v133
	ds_read2_b32 v[70:71], v165 offset1:1
	s_add_i32 s4, s4, -1
	v_lshl_add_u64 v[116:117], v[116:117], 0, s[18:19]
	v_lshl_add_u64 v[118:119], v[118:119], 0, s[18:19]
	v_lshl_add_u64 v[128:129], v[128:129], 0, s[20:21]
	s_waitcnt lgkmcnt(0)
	v_pk_fma_f32 v[70:71], v[132:133], v[72:73], v[70:71] op_sel_hi:[0,1,1]
	v_add_u32_e32 v72, 0x800, v172
	ds_read2_b64 v[84:87], v72 offset0:177 offset1:211
	ds_read_b128 v[88:91], v172 offset:3472
	ds_read_b128 v[100:103], v172 offset:3488
	ds_read_b128 v[72:75], v172 offset:3504
	v_lshl_add_u64 v[130:131], v[130:131], 0, s[20:21]
	s_cmp_lg_u32 s4, 0
	s_waitcnt lgkmcnt(0)
	v_pk_fma_f32 v[134:135], v[0:1], v[84:85], v[70:71] op_sel_hi:[0,1,1]
	ds_read2_b32 v[70:71], v166 offset1:1
	s_waitcnt lgkmcnt(0)
	v_pk_fma_f32 v[68:69], v[132:133], v[68:69], v[70:71] op_sel_hi:[0,1,1]
	v_pk_fma_f32 v[142:143], v[0:1], v[74:75], v[68:69] op_sel_hi:[0,1,1]
	ds_read_b128 v[68:71], v172 offset:3520
	s_waitcnt lgkmcnt(0)
	v_fma_f32 v136, v134, v71, v135
	ds_read_b128 v[92:95], v172 offset:3536
	ds_read_b128 v[104:107], v172 offset:3552
	ds_read_b128 v[68:71], v172 offset:3568
	ds_read_b128 v[108:111], v172 offset:3600
	ds_read2_b32 v[74:75], v168 offset1:1
	s_waitcnt lgkmcnt(0)
	v_pk_fma_f32 v[74:75], v[132:133], v[80:81], v[74:75] op_sel_hi:[0,1,1]
	v_pk_fma_f32 v[74:75], v[0:1], v[88:89], v[74:75] op_sel_hi:[0,1,1]
	v_pk_fma_f32 v[74:75], v[134:135], v[92:93], v[74:75] op_sel_hi:[0,1,1]
	v_pk_fma_f32 v[138:139], v[136:137], v[108:109], v[74:75] op_sel_hi:[0,1,1]
	ds_read_b128 v[174:177], v172 offset:3616
	ds_read_b128 v[74:77], v172 offset:3632
	ds_read_b128 v[184:187], v172 offset:3664
	ds_read_b128 v[204:207], v172 offset:3680
	ds_read_b128 v[78:81], v172 offset:3696
	ds_read2_b32 v[84:85], v167 offset1:1
	s_waitcnt lgkmcnt(0)
	v_fma_f32 v140, v138, v185, v139
	v_pk_fma_f32 v[82:83], v[132:133], v[82:83], v[84:85] op_sel_hi:[0,1,1]
	v_pk_fma_f32 v[82:83], v[0:1], v[90:91], v[82:83] op_sel_hi:[0,1,1]
	v_pk_fma_f32 v[82:83], v[134:135], v[94:95], v[82:83] op_sel_hi:[0,1,1]
	v_pk_fma_f32 v[82:83], v[136:137], v[110:111], v[82:83] op_sel_hi:[0,1,1]
	v_pk_fma_f32 v[82:83], v[138:139], v[186:187], v[82:83] op_sel_hi:[0,1,1]
	v_pk_fma_f32 v[144:145], v[140:141], v[86:87], v[82:83] op_sel_hi:[0,1,1]
	ds_read_b128 v[108:111], v172 offset:3744
	ds_read_b128 v[82:85], v172 offset:3760
	ds_read_b128 v[86:89], v172 offset:3792
	s_waitcnt lgkmcnt(0)
	v_fma_f32 v146, v144, v89, v145
	ds_read_b128 v[184:187], v172 offset:3808
	ds_read_b128 v[86:89], v172 offset:3824
	ds_read_b128 v[208:211], v172 offset:3872
	ds_read2_b32 v[90:91], v169 offset1:1
	s_waitcnt lgkmcnt(0)
; #define LAS __attribute__((address_space(3)))
; #define MFMA16(a, b, c) __builtin_amdgcn_mfma_f32_16x16x32_bf16(a, b, c, 0, 0, 0)
; __device__ __forceinline__ unsigned pk2(float lo, float hi) { f32x2_t v = {lo, hi}; bf16x2_t b = __builtin_convertvector(v, bf16x2_t); return __builtin_bit_cast(unsigned, b); }
; #define PF_BG(N_) do { const size_t cq_ = CQ_(N_); const bf16* ub = BKb + cq_ * 2048; _Pragma("unroll") for (int jb = 0; jb < 4; ++jb) pB[jb] = GLD(bf16x8, ub, oB + (unsigned)jb * 1024u); pG = GLD(float, G15b + cq_ * 64, oG); } while (0)
; #define PF_NR(N_) do { pNR = GLD(bf16x8, NRb + CQ_(N_) * 512, oB); } while (0)
; #define PF_VB(N_) do { const bf16* uv = VBb + CQ_(N_) * 1024; pVB[0] = GLD(u32x4v, uv, oV); pVB[1] = GLD(u32x4v, uv, oV + 16u); } while (0)
; #define FENCE() asm volatile("" ::: "memory")
; __device__ __forceinline__ void rwkv_scan(const Args& c, int bx, int l, LAS unsigned char* lds, bool dry) {
;     ...
;             for (int s0 = 0; s0 < 15; ++s0) {
; #pragma unroll
;                 for (int t4 = (s0 + 1) & ~3; t4 < 16; t4 += 4) {
;                     const f32x4 nab = *(const LAS f32x4*)(Nl + s0 * 16 + t4);
; #pragma unroll
;                     for (int e = 0; e < 4; ++e) if (t4 + e > s0) uu[t4 + e] += uu[s0] * nab[e];
;                 }
;             }
;         }
;         FENCE();
; #pragma unroll
;         for (int g = 0; g < 2; ++g) { u32x4v o; o.x = pk2(uu[8 * g], uu[8 * g + 1]); o.y = pk2(uu[8 * g + 2], uu[8 * g + 3]); o.z = pk2(uu[8 * g + 4], uu[8 * g + 5]); o.w = pk2(uu[8 * g + 6], uu[8 * g + 7]); *(LAS u32x4v*)(UVl + row * 40 + 8 * g) = o;
;             *(LAS u32x4v*)(UVl + row * 40 + 16 + 8 * g) = pVB[g]; }
;         Gl[L] = pG;
;         FENCE();
;         {
;             const bf16x8 fu = *(const LAS bf16x8*)(UVl + r * 40 + q4 * 8);
; #pragma unroll
;             for (int jb = 0; jb < 4; ++jb) { const f32x4 cG = *(const LAS f32x4*)(Gl + 16 * jb + 4 * q4); ST[jb] = MFMA16(pB[jb], fu, ST[jb] * cG); }
;             const u32x2v xo = *(const LAS u32x2v*)(XRl + r * 20 + 4 * q4);
;             const f32x4 yv = MFMA16(fu, pNR, ((f32x4){bflo(xo.x), bfhi(xo.x), bflo(xo.y), bfhi(xo.y)}));
;             if (!dry) *(f32x4*)(Yb + ((size_t)n * 16 + r) * (PW / 2) + 4 * q4) = yv;
;         }
;         FENCE();
;         if (more) { PF_BG(n + 1); PF_NR(n + 1); PF_VB(n + 1); }
	v_pk_fma_f32 v[90:91], v[132:133], v[96:97], v[90:91] op_sel_hi:[0,1,1]
	v_pk_fma_f32 v[90:91], v[0:1], v[100:101], v[90:91] op_sel_hi:[0,1,1]
	v_pk_fma_f32 v[90:91], v[134:135], v[104:105], v[90:91] op_sel_hi:[0,1,1]
	v_pk_fma_f32 v[90:91], v[136:137], v[174:175], v[90:91] op_sel_hi:[0,1,1]
	v_pk_fma_f32 v[90:91], v[138:139], v[204:205], v[90:91] op_sel_hi:[0,1,1]
	v_pk_fma_f32 v[90:91], v[140:141], v[108:109], v[90:91] op_sel_hi:[0,1,1]
	v_pk_fma_f32 v[90:91], v[144:145], v[184:185], v[90:91] op_sel_hi:[0,1,1]
	v_pk_fma_f32 v[148:149], v[146:147], v[208:209], v[90:91] op_sel_hi:[0,1,1]
	ds_read_b128 v[90:93], v172 offset:3888
	ds_read_b128 v[212:215], v172 offset:3936
	ds_read_b128 v[94:97], v172 offset:3952
	ds_read2_b32 v[100:101], v170 offset1:1
	s_waitcnt lgkmcnt(0)
	v_fma_f32 v150, v148, v213, v149
	v_pk_fma_f32 v[98:99], v[132:133], v[98:99], v[100:101] op_sel_hi:[0,1,1]
	v_pk_fma_f32 v[98:99], v[0:1], v[102:103], v[98:99] op_sel_hi:[0,1,1]
	v_pk_fma_f32 v[98:99], v[134:135], v[106:107], v[98:99] op_sel_hi:[0,1,1]
	v_pk_fma_f32 v[98:99], v[136:137], v[176:177], v[98:99] op_sel_hi:[0,1,1]
	v_pk_fma_f32 v[98:99], v[138:139], v[206:207], v[98:99] op_sel_hi:[0,1,1]
	v_pk_fma_f32 v[98:99], v[140:141], v[110:111], v[98:99] op_sel_hi:[0,1,1]
	v_pk_fma_f32 v[98:99], v[144:145], v[186:187], v[98:99] op_sel_hi:[0,1,1]
	v_pk_fma_f32 v[98:99], v[146:147], v[210:211], v[98:99] op_sel_hi:[0,1,1]
	v_pk_fma_f32 v[102:103], v[148:149], v[214:215], v[98:99] op_sel_hi:[0,1,1]
	v_add_u32_e32 v98, 0xc00, v172
	ds_read2_b64 v[98:101], v98 offset0:117 offset1:151
	s_waitcnt lgkmcnt(0)
	v_pk_fma_f32 v[98:99], v[150:151], v[98:99], v[102:103] op_sel_hi:[0,1,1]
	ds_read_b128 v[102:105], v172 offset:4016
	ds_read_b128 v[106:109], v172 offset:4064
	s_waitcnt lgkmcnt(0)
	v_fma_f32 v152, v98, v109, v99
	ds_read_b128 v[106:109], v172 offset:4080
	ds_read_b128 v[110:113], v172 offset:4144
	ds_read2_b32 v[174:175], v171 offset1:1
	s_waitcnt lgkmcnt(0)
	v_pk_fma_f32 v[66:67], v[132:133], v[66:67], v[174:175] op_sel_hi:[0,1,1]
	v_pk_fma_f32 v[66:67], v[0:1], v[72:73], v[66:67] op_sel_hi:[0,1,1]
	v_pk_fma_f32 v[66:67], v[134:135], v[68:69], v[66:67] op_sel_hi:[0,1,1]
	v_pk_fma_f32 v[66:67], v[136:137], v[74:75], v[66:67] op_sel_hi:[0,1,1]
	v_pk_fma_f32 v[66:67], v[138:139], v[78:79], v[66:67] op_sel_hi:[0,1,1]
	v_pk_fma_f32 v[66:67], v[140:141], v[82:83], v[66:67] op_sel_hi:[0,1,1]
	v_pk_fma_f32 v[66:67], v[144:145], v[86:87], v[66:67] op_sel_hi:[0,1,1]
	v_pk_fma_f32 v[66:67], v[146:147], v[90:91], v[66:67] op_sel_hi:[0,1,1]
	v_pk_fma_f32 v[66:67], v[148:149], v[94:95], v[66:67] op_sel_hi:[0,1,1]
	v_pk_fma_f32 v[66:67], v[150:151], v[102:103], v[66:67] op_sel_hi:[0,1,1]
	v_pk_fma_f32 v[66:67], v[98:99], v[106:107], v[66:67] op_sel_hi:[0,1,1]
	v_pk_fma_f32 v[72:73], v[152:153], v[110:111], v[66:67] op_sel_hi:[0,1,1]
	ds_read_b128 v[66:69], v172 offset:4208
	s_waitcnt lgkmcnt(0)
	v_fma_f32 v74, v67, v72, v73
	v_pk_fma_f32 v[66:67], v[134:135], v[70:71], v[142:143] op_sel_hi:[0,1,1]
	v_pk_fma_f32 v[66:67], v[136:137], v[76:77], v[66:67] op_sel_hi:[0,1,1]
	v_pk_fma_f32 v[66:67], v[138:139], v[80:81], v[66:67] op_sel_hi:[0,1,1]
	v_pk_fma_f32 v[66:67], v[140:141], v[84:85], v[66:67] op_sel_hi:[0,1,1]
	v_pk_fma_f32 v[66:67], v[144:145], v[88:89], v[66:67] op_sel_hi:[0,1,1]
	v_pk_fma_f32 v[66:67], v[146:147], v[92:93], v[66:67] op_sel_hi:[0,1,1]
	v_pk_fma_f32 v[66:67], v[148:149], v[96:97], v[66:67] op_sel_hi:[0,1,1]
	v_pk_fma_f32 v[66:67], v[150:151], v[104:105], v[66:67] op_sel_hi:[0,1,1]
	v_pk_fma_f32 v[66:67], v[98:99], v[108:109], v[66:67] op_sel_hi:[0,1,1]
	v_pk_fma_f32 v[66:67], v[152:153], v[112:113], v[66:67] op_sel_hi:[0,1,1]
	v_pk_fma_f32 v[66:67], v[68:69], v[72:73], v[66:67] op_sel_hi:[1,0,1]
	v_cvt_pk_bf16_f32 v70, v138, v140
	v_pk_fma_f32 v[76:77], v[100:101], v[74:75], v[66:67] op_sel_hi:[1,0,1]
	ds_read_b128 v[66:69], v172 offset:4336
	s_waitcnt vmcnt(10) lgkmcnt(0)
	v_cvt_pk_bf16_f32 v68, v132, v0
	v_cvt_pk_bf16_f32 v71, v144, v146
	v_add_u32_e32 v66, s0, v160
	v_fma_f32 v67, v69, v76, v77
	v_cvt_pk_bf16_f32 v69, v134, v136
	ds_write_b128 v66, v[68:71]
	ds_write_b128 v66, v[10:13] offset:32
	v_cvt_pk_bf16_f32 v10, v148, v150
	v_cvt_pk_bf16_f32 v11, v98, v152
	v_cvt_pk_bf16_f32 v12, v72, v74
	v_cvt_pk_bf16_f32 v13, v76, v67
	ds_write_b128 v66, v[10:13] offset:16
	ds_write_b128 v66, v[6:9] offset:48
	ds_write_b32 v151, v153 offset:4416
	v_add_u32_e32 v67, v157, v160
	v_add_u32_e32 v0, v158, v154
	ds_read_b128 v[6:9], v67
	ds_read_b128 v[10:13], v0 offset:4416
	s_waitcnt vmcnt(6) lgkmcnt(0)
	v_pk_mul_f32 v[10:11], v[42:43], v[10:11]
	v_pk_mul_f32 v[12:13], v[44:45], v[12:13]
	s_nop 1
	v_mfma_f32_16x16x32_bf16 v[42:45], v[62:65], v[6:9], v[10:13]
	s_nop 2
	ds_read_b128 v[10:13], v0 offset:4480
	s_waitcnt lgkmcnt(0)
	v_pk_mul_f32 v[10:11], v[46:47], v[10:11]
	v_pk_mul_f32 v[12:13], v[48:49], v[12:13]
	s_nop 1
	v_mfma_f32_16x16x32_bf16 v[46:49], v[58:61], v[6:9], v[10:13]
	s_nop 2
	ds_read_b128 v[10:13], v0 offset:4544
	s_waitcnt lgkmcnt(0)
	v_pk_mul_f32 v[10:11], v[38:39], v[10:11]
	v_pk_mul_f32 v[12:13], v[40:41], v[12:13]
	s_nop 1
	v_mfma_f32_16x16x32_bf16 v[38:41], v[54:57], v[6:9], v[10:13]
	s_nop 2
	ds_read_b128 v[10:13], v0 offset:4608
	s_waitcnt lgkmcnt(0)
	v_pk_mul_f32 v[10:11], v[34:35], v[10:11]
	v_pk_mul_f32 v[12:13], v[36:37], v[12:13]
	s_nop 1
	v_mfma_f32_16x16x32_bf16 v[34:37], v[50:53], v[6:9], v[10:13]
	s_nop 2
	ds_read_b64 v[12:13], v147 offset:4672
	s_waitcnt lgkmcnt(0)
	v_lshlrev_b32_e32 v10, 16, v12
	v_and_b32_e32 v11, 0xffff0000, v12
	v_lshlrev_b32_e32 v12, 16, v13
	v_and_b32_e32 v13, 0xffff0000, v13
	v_mov_b32_e32 v0, v35
	v_mov_b32_e32 v68, v36
	v_mfma_f32_16x16x32_bf16 v[2:5], v[6:9], v[2:5], v[10:13]
	v_lshl_add_u64 v[6:7], s[2:3], 0, v[120:121]
	v_lshl_add_u64 v[120:121], v[120:121], 0, s[12:13]
	s_mov_b64 s[12:13], 0x800
	v_mov_b32_e32 v69, v37
	s_nop 3
	global_store_dwordx4 v[6:7], v[2:5], off
	v_lshl_add_u64 v[6:7], s[2:3], 0, v[122:123]
	v_add_co_u32_e32 v6, vcc, s5, v6
	v_lshl_add_u64 v[2:3], s[2:3], 0, v[126:127]
	global_load_dword v153, v[2:3], off
	v_lshl_add_u64 v[2:3], s[2:3], 0, v[124:125]
	v_addc_co_u32_e32 v7, vcc, 0, v7, vcc
	global_load_dwordx4 v[2:5], v[2:3], off
	s_nop 0
	global_load_dwordx4 v[10:13], v[6:7], off
	s_nop 0
	global_load_dwordx4 v[6:9], v[6:7], off offset:16
	v_lshl_add_u64 v[122:123], v[122:123], 0, s[20:21]
	v_lshl_add_u64 v[124:125], v[124:125], 0, s[16:17]
	v_lshl_add_u64 v[126:127], v[126:127], 0, s[12:13]
	s_cbranch_scc1 .LBB0_232
; #define LAS __attribute__((address_space(3)))
; #define MFMA16(a, b, c) __builtin_amdgcn_mfma_f32_16x16x32_bf16(a, b, c, 0, 0, 0)
; __device__ __forceinline__ unsigned pk2(float lo, float hi) { f32x2_t v = {lo, hi}; bf16x2_t b = __builtin_convertvector(v, bf16x2_t); return __builtin_bit_cast(unsigned, b); }
; #define PF_AR(N_) do { const size_t cq_ = CQ_(N_); const bf16* ua = AHb + cq_ * 1024; const bf16* ur = RHb + cq_ * 1024; pA[0] = GLD(bf16x8, ua, oA); pA[1] = GLD(bf16x8, ua, oA + 64u); pR[0] = GLD(bf16x8, ur, oA); pR[1] = GLD(bf16x8, ur, oA + 64u); } while (0)
; #define PF_N(N_) do { pN = GLD(f32x4, NMb + CQ_(N_) * 1024, oN); } while (0)
; #define PF_C(N_) do { pC = GLD(u32x2v, VNb + CQ_(N_) * 1024, oC); } while (0)
; __device__ __forceinline__ void rwkv_scan(const Args& c, int bx, int l, LAS unsigned char* lds, bool dry) {
;     ...
;     for (int n = 0; n < T / 16; ++n) {
;         const bool more = (n + 1 < T / 16);
;         *(LAS f32x4*)(Nl + L * 4) = pN;
;         if (more) PF_N(n + 1);
; #pragma unroll
;         for (int jb = 0; jb < 4; ++jb) { u32x2v o; o.x = pk2(ST[jb][0], ST[jb][1]); o.y = pk2(ST[jb][2], ST[jb][3]); *(LAS u32x2v*)(St + r * 72 + 16 * jb + 4 * q4) = o; }
;         FENCE();
;         {
;             f32x4 xa = (f32x4){bflo(pC.x), bfhi(pC.x), bflo(pC.y), bfhi(pC.y)}, xr = (f32x4){0.f, 0.f, 0.f, 0.f};
; #pragma unroll
;             for (int ks = 0; ks < 2; ++ks) { const bf16x8 fs = *(const LAS bf16x8*)(St + r * 72 + ks * 32 + q4 * 8); xa = MFMA16(fs, pA[ks], xa); xr = MFMA16(fs, pR[ks], xr); }
; #pragma unroll
;             for (int e = 0; e < 4; ++e) Xl[(4 * q4 + e) * 17 + r] = xa[e];
;             u32x2v xo; xo.x = pk2(xr[0], xr[1]); xo.y = pk2(xr[2], xr[3]); *(LAS u32x2v*)(XRl + r * 20 + 4 * q4) = xo;
;         }
;         if (more) { PF_AR(n + 1); PF_C(n + 1); }
;         FENCE();
;         float uu[16];
;         {
;             const LAS float* xrow = Xl + row * 17;
; #pragma unroll
;             for (int t = 0; t < 16; ++t) uu[t] = xrow[t];
; #pragma unroll
;             for (int s0 = 0; s0 < 15; ++s0) {
; #pragma unroll
;                 for (int t4 = (s0 + 1) & ~3; t4 < 16; t4 += 4) {
;                     const f32x4 nab = *(const LAS f32x4*)(Nl + s0 * 16 + t4);
; #pragma unroll
;                     for (int e = 0; e < 4; ++e) if (t4 + e > s0) uu[t4 + e] += uu[s0] * nab[e];
;                 }
;             }
;         }
	s_waitcnt vmcnt(0)
	ds_write_b128 v156, v[30:33] offset:3392
	v_cvt_pk_bf16_f32 v30, v42, v43
	v_cvt_pk_bf16_f32 v31, v44, v45
	v_cvt_pk_bf16_f32 v32, v46, v47
	v_cvt_pk_bf16_f32 v33, v48, v49
	ds_write2_b64 v155, v[30:31], v[32:33] offset1:4
	v_cvt_pk_bf16_f32 v30, v38, v39
	v_cvt_pk_bf16_f32 v31, v40, v41
	v_cvt_pk_bf16_f32 v32, v34, v35
	v_cvt_pk_bf16_f32 v33, v36, v37
	ds_write2_b64 v155, v[30:31], v[32:33] offset0:8 offset1:12
	ds_read_b128 v[30:33], v159
	v_lshlrev_b32_e32 v34, 16, v114
	v_and_b32_e32 v35, 0xffff0000, v114
	v_lshlrev_b32_e32 v36, 16, v115
	v_and_b32_e32 v37, 0xffff0000, v115
	s_waitcnt lgkmcnt(0)
	v_mfma_f32_16x16x32_bf16 v[18:21], v[30:33], v[18:21], 0
	v_mov_b32_e32 v51, s0
	v_add_u32_e32 v0, 0x800, v51
	s_add_u32 s2, s2, s7
	v_mfma_f32_16x16x32_bf16 v[26:29], v[30:33], v[26:29], v[34:37]
	s_addc_u32 s3, s3, s6
	s_add_u32 s2, s2, s11
	s_addc_u32 s3, s3, 0
	ds_read_b128 v[34:37], v159 offset:64
	s_waitcnt lgkmcnt(0)
	v_mfma_f32_16x16x32_bf16 v[14:17], v[34:37], v[14:17], v[18:21]
	s_lshl_b32 s1, s1, 2
	s_add_u32 s0, s2, s1
	s_addc_u32 s1, s3, 0
	v_mfma_f32_16x16x32_bf16 v[22:25], v[34:37], v[22:25], v[26:29]
	s_nop 3
	v_cvt_pk_bf16_f32 v14, v14, v15
	v_cvt_pk_bf16_f32 v15, v16, v17
	s_nop 1
	ds_write2_b32 v163, v22, v23 offset0:64 offset1:81
	ds_write2_b32 v163, v24, v25 offset0:98 offset1:115
	ds_write_b64 v147, v[14:15] offset:4672
	ds_read2_b32 v[44:45], v164 offset1:1
	ds_read_b128 v[18:21], v51 offset:3392
	ds_read_b128 v[30:33], v51 offset:3408
	ds_read2_b32 v[22:23], v165 offset1:1
	ds_read2_b64 v[40:43], v0 offset0:177 offset1:211
	ds_read_b128 v[36:39], v51 offset:3424
	ds_read_b128 v[14:17], v51 offset:3440
	s_waitcnt lgkmcnt(5)
	v_fma_f32 v0, v44, v19, v45
	s_waitcnt lgkmcnt(3)
	v_pk_fma_f32 v[18:19], v[44:45], v[20:21], v[22:23] op_sel_hi:[0,1,1]
	s_waitcnt lgkmcnt(2)
	v_pk_fma_f32 v[46:47], v[0:1], v[40:41], v[18:19] op_sel_hi:[0,1,1]
	ds_read2_b32 v[26:27], v166 offset1:1
	ds_read_b128 v[18:21], v51 offset:3504
	ds_read_b128 v[22:25], v51 offset:3520
	ds_read_b128 v[54:57], v51 offset:3472
	ds_read_b128 v[60:63], v51 offset:3488
	s_waitcnt lgkmcnt(4)
	v_pk_fma_f32 v[16:17], v[44:45], v[16:17], v[26:27] op_sel_hi:[0,1,1]
	s_waitcnt lgkmcnt(3)
	v_pk_fma_f32 v[52:53], v[0:1], v[20:21], v[16:17] op_sel_hi:[0,1,1]
	s_waitcnt lgkmcnt(2)
	v_fma_f32 v16, v46, v25, v47
	ds_read2_b32 v[24:25], v168 offset1:1
	ds_read_b128 v[68:71], v51 offset:3536
	ds_read_b128 v[72:75], v51 offset:3552
	ds_read_b128 v[20:23], v51 offset:3568
	ds_read_b128 v[76:79], v51 offset:3600
	s_waitcnt lgkmcnt(4)
	v_pk_fma_f32 v[24:25], v[44:45], v[30:31], v[24:25] op_sel_hi:[0,1,1]
	v_pk_fma_f32 v[24:25], v[0:1], v[54:55], v[24:25] op_sel_hi:[0,1,1]
	s_waitcnt lgkmcnt(3)
	v_pk_fma_f32 v[24:25], v[46:47], v[68:69], v[24:25] op_sel_hi:[0,1,1]
	ds_read_b128 v[80:83], v51 offset:3664
	s_waitcnt lgkmcnt(1)
	v_pk_fma_f32 v[48:49], v[16:17], v[76:77], v[24:25] op_sel_hi:[0,1,1]
	ds_read_b128 v[84:87], v51 offset:3616
	ds_read2_b32 v[34:35], v167 offset1:1
	ds_read_b128 v[24:27], v51 offset:3632
	ds_read_b128 v[88:91], v51 offset:3680
	ds_read_b128 v[28:31], v51 offset:3696
	s_waitcnt lgkmcnt(5)
	v_fma_f32 v50, v48, v81, v49
	s_waitcnt lgkmcnt(3)
	v_pk_fma_f32 v[32:33], v[44:45], v[32:33], v[34:35] op_sel_hi:[0,1,1]
	v_pk_fma_f32 v[32:33], v[0:1], v[56:57], v[32:33] op_sel_hi:[0,1,1]
	v_pk_fma_f32 v[32:33], v[46:47], v[70:71], v[32:33] op_sel_hi:[0,1,1]
	v_pk_fma_f32 v[32:33], v[16:17], v[78:79], v[32:33] op_sel_hi:[0,1,1]
	v_pk_fma_f32 v[32:33], v[48:49], v[82:83], v[32:33] op_sel_hi:[0,1,1]
	ds_read_b128 v[54:57], v51 offset:3792
	s_waitcnt lgkmcnt(0)
	v_pk_fma_f32 v[54:55], v[50:51], v[42:43], v[32:33] op_sel_hi:[0,1,1]
	ds_read_b128 v[68:71], v51 offset:3744
	ds_read_b128 v[32:35], v51 offset:3760
	ds_read2_b32 v[58:59], v169 offset1:1
	ds_read_b128 v[76:79], v51 offset:3808
	ds_read_b128 v[40:43], v51 offset:3824
	ds_read_b128 v[80:83], v51 offset:3872
	ds_read2_b32 v[64:65], v170 offset1:1
	v_fma_f32 v56, v54, v57, v55
	ds_read_b128 v[92:95], v51 offset:3936
	ds_read_b128 v[96:99], v51 offset:3888
	s_waitcnt lgkmcnt(6)
	v_pk_fma_f32 v[36:37], v[44:45], v[36:37], v[58:59] op_sel_hi:[0,1,1]
	v_pk_fma_f32 v[36:37], v[0:1], v[60:61], v[36:37] op_sel_hi:[0,1,1]
	v_pk_fma_f32 v[36:37], v[46:47], v[72:73], v[36:37] op_sel_hi:[0,1,1]
	v_pk_fma_f32 v[36:37], v[16:17], v[84:85], v[36:37] op_sel_hi:[0,1,1]
	v_pk_fma_f32 v[36:37], v[48:49], v[88:89], v[36:37] op_sel_hi:[0,1,1]
	v_pk_fma_f32 v[36:37], v[50:51], v[68:69], v[36:37] op_sel_hi:[0,1,1]
	s_waitcnt lgkmcnt(5)
; #define LAS __attribute__((address_space(3)))
; #define MFMA16(a, b, c) __builtin_amdgcn_mfma_f32_16x16x32_bf16(a, b, c, 0, 0, 0)
; __device__ __forceinline__ unsigned pk2(float lo, float hi) { f32x2_t v = {lo, hi}; bf16x2_t b = __builtin_convertvector(v, bf16x2_t); return __builtin_bit_cast(unsigned, b); }
; #define FENCE() asm volatile("" ::: "memory")
; __device__ __forceinline__ void rwkv_scan(const Args& c, int bx, int l, LAS unsigned char* lds, bool dry) {
;     ...
;             for (int s0 = 0; s0 < 15; ++s0) {
; #pragma unroll
;                 for (int t4 = (s0 + 1) & ~3; t4 < 16; t4 += 4) {
;                     const f32x4 nab = *(const LAS f32x4*)(Nl + s0 * 16 + t4);
; #pragma unroll
;                     for (int e = 0; e < 4; ++e) if (t4 + e > s0) uu[t4 + e] += uu[s0] * nab[e];
;                 }
;             }
;         }
;         FENCE();
; #pragma unroll
;         for (int g = 0; g < 2; ++g) { u32x4v o; o.x = pk2(uu[8 * g], uu[8 * g + 1]); o.y = pk2(uu[8 * g + 2], uu[8 * g + 3]); o.z = pk2(uu[8 * g + 4], uu[8 * g + 5]); o.w = pk2(uu[8 * g + 6], uu[8 * g + 7]); *(LAS u32x4v*)(UVl + row * 40 + 8 * g) = o;
;             *(LAS u32x4v*)(UVl + row * 40 + 16 + 8 * g) = pVB[g]; }
;         Gl[L] = pG;
;         FENCE();
;         {
;             const bf16x8 fu = *(const LAS bf16x8*)(UVl + r * 40 + q4 * 8);
; #pragma unroll
;             for (int jb = 0; jb < 4; ++jb) { const f32x4 cG = *(const LAS f32x4*)(Gl + 16 * jb + 4 * q4); ST[jb] = MFMA16(pB[jb], fu, ST[jb] * cG); }
;             const u32x2v xo = *(const LAS u32x2v*)(XRl + r * 20 + 4 * q4);
;             const f32x4 yv = MFMA16(fu, pNR, ((f32x4){bflo(xo.x), bfhi(xo.x), bflo(xo.y), bfhi(xo.y)}));
;             if (!dry) *(f32x4*)(Yb + ((size_t)n * 16 + r) * (PW / 2) + 4 * q4) = yv;
; __device__ __forceinline__ void m2_phase(const Args& c, int l, LAS unsigned char* lds, int G, int mode, bool dry, int cidx) {
;     ...
;     if (bx < 32) { if (mode & 1) { rwkv_scan(c, bx, l, lds, dry);
;             __threadfence(); __syncthreads(); if (tid_ == 0) __hip_atomic_fetch_add(rdone, 1u, __ATOMIC_RELAXED, __HIP_MEMORY_SCOPE_AGENT); } }
	v_pk_fma_f32 v[36:37], v[54:55], v[76:77], v[36:37] op_sel_hi:[0,1,1]
	s_waitcnt lgkmcnt(3)
	v_pk_fma_f32 v[58:59], v[56:57], v[80:81], v[36:37] op_sel_hi:[0,1,1]
	s_waitcnt lgkmcnt(2)
	v_pk_fma_f32 v[36:37], v[44:45], v[38:39], v[64:65] op_sel_hi:[0,1,1]
	v_pk_fma_f32 v[36:37], v[0:1], v[62:63], v[36:37] op_sel_hi:[0,1,1]
	v_pk_fma_f32 v[36:37], v[46:47], v[74:75], v[36:37] op_sel_hi:[0,1,1]
	v_pk_fma_f32 v[36:37], v[16:17], v[86:87], v[36:37] op_sel_hi:[0,1,1]
	v_pk_fma_f32 v[36:37], v[48:49], v[90:91], v[36:37] op_sel_hi:[0,1,1]
	v_pk_fma_f32 v[62:63], v[50:51], v[70:71], v[36:37] op_sel_hi:[0,1,1]
	v_pk_fma_f32 v[62:63], v[54:55], v[78:79], v[62:63] op_sel_hi:[0,1,1]
	ds_read_b128 v[100:103], v51 offset:3952
	v_add_u32_e32 v17, 0xc00, v51
	v_pk_fma_f32 v[68:69], v[56:57], v[82:83], v[62:63] op_sel_hi:[0,1,1]
	ds_read_b128 v[62:65], v51 offset:4064
	ds_read2_b64 v[36:39], v17 offset0:117 offset1:151
	s_waitcnt lgkmcnt(1)
	v_pk_fma_f32 v[62:63], v[58:59], v[94:95], v[68:69] op_sel_hi:[0,1,1]
	ds_read2_b32 v[76:77], v171 offset1:1
	ds_read_b128 v[68:71], v51 offset:4016
	v_fma_f32 v60, v58, v93, v59
	s_waitcnt lgkmcnt(2)
	v_pk_fma_f32 v[36:37], v[60:61], v[36:37], v[62:63] op_sel_hi:[0,1,1]
	s_waitcnt lgkmcnt(1)
	v_pk_fma_f32 v[14:15], v[44:45], v[14:15], v[76:77] op_sel_hi:[0,1,1]
	v_pk_fma_f32 v[14:15], v[0:1], v[18:19], v[14:15] op_sel_hi:[0,1,1]
	v_pk_fma_f32 v[14:15], v[46:47], v[20:21], v[14:15] op_sel_hi:[0,1,1]
	v_pk_fma_f32 v[14:15], v[16:17], v[24:25], v[14:15] op_sel_hi:[0,1,1]
	v_pk_fma_f32 v[14:15], v[48:49], v[28:29], v[14:15] op_sel_hi:[0,1,1]
	v_pk_fma_f32 v[14:15], v[50:51], v[32:33], v[14:15] op_sel_hi:[0,1,1]
	v_fma_f32 v78, v36, v65, v37
	ds_read_b128 v[62:65], v51 offset:4080
	ds_read_b128 v[72:75], v51 offset:4144
	v_pk_fma_f32 v[14:15], v[54:55], v[40:41], v[14:15] op_sel_hi:[0,1,1]
	v_pk_fma_f32 v[14:15], v[56:57], v[96:97], v[14:15] op_sel_hi:[0,1,1]
	v_pk_fma_f32 v[14:15], v[58:59], v[100:101], v[14:15] op_sel_hi:[0,1,1]
	s_waitcnt lgkmcnt(2)
	v_pk_fma_f32 v[14:15], v[60:61], v[68:69], v[14:15] op_sel_hi:[0,1,1]
	s_waitcnt lgkmcnt(1)
	v_pk_fma_f32 v[14:15], v[36:37], v[62:63], v[14:15] op_sel_hi:[0,1,1]
	s_waitcnt lgkmcnt(0)
	v_pk_fma_f32 v[28:29], v[78:79], v[72:73], v[14:15] op_sel_hi:[0,1,1]
	v_pk_fma_f32 v[14:15], v[46:47], v[22:23], v[52:53] op_sel_hi:[0,1,1]
	v_pk_fma_f32 v[14:15], v[16:17], v[26:27], v[14:15] op_sel_hi:[0,1,1]
	v_pk_fma_f32 v[14:15], v[48:49], v[30:31], v[14:15] op_sel_hi:[0,1,1]
	v_pk_fma_f32 v[14:15], v[50:51], v[34:35], v[14:15] op_sel_hi:[0,1,1]
	v_pk_fma_f32 v[14:15], v[54:55], v[42:43], v[14:15] op_sel_hi:[0,1,1]
	ds_read_b128 v[18:21], v51 offset:4208
	ds_read_b128 v[22:25], v51 offset:4336
	v_pk_fma_f32 v[14:15], v[56:57], v[98:99], v[14:15] op_sel_hi:[0,1,1]
	v_pk_fma_f32 v[14:15], v[58:59], v[102:103], v[14:15] op_sel_hi:[0,1,1]
	v_pk_fma_f32 v[14:15], v[60:61], v[70:71], v[14:15] op_sel_hi:[0,1,1]
	v_pk_fma_f32 v[14:15], v[36:37], v[64:65], v[14:15] op_sel_hi:[0,1,1]
	v_pk_fma_f32 v[14:15], v[78:79], v[74:75], v[14:15] op_sel_hi:[0,1,1]
	s_waitcnt lgkmcnt(1)
	v_fma_f32 v18, v19, v28, v29
	v_pk_fma_f32 v[14:15], v[20:21], v[28:29], v[14:15] op_sel_hi:[1,0,1]
	v_cvt_pk_bf16_f32 v17, v54, v56
	v_pk_fma_f32 v[20:21], v[38:39], v[18:19], v[14:15] op_sel_hi:[1,0,1]
	v_cvt_pk_bf16_f32 v14, v44, v0
	s_waitcnt lgkmcnt(0)
	v_fma_f32 v19, v25, v20, v21
	v_cvt_pk_bf16_f32 v15, v46, v16
	v_cvt_pk_bf16_f32 v16, v48, v50
	ds_write_b128 v66, v[14:17]
	ds_write_b128 v66, v[10:13] offset:32
	v_cvt_pk_bf16_f32 v10, v58, v60
	v_cvt_pk_bf16_f32 v11, v36, v78
	v_cvt_pk_bf16_f32 v12, v28, v18
	v_cvt_pk_bf16_f32 v13, v20, v19
	ds_write_b128 v66, v[10:13] offset:16
	ds_write_b128 v66, v[6:9] offset:48
	ds_write_b32 v151, v153 offset:4416
	ds_read_b128 v[6:9], v67
	ds_read_b64 v[12:13], v147 offset:4672
	v_lshlrev_b32_e32 v0, 2, v141
	v_lshl_add_u64 v[14:15], s[0:1], 0, v[0:1]
	v_mul_u32_u24_e32 v0, 0xe00, v137
	v_lshlrev_b32_e32 v0, 2, v0
	s_waitcnt lgkmcnt(0)
	v_lshlrev_b32_e32 v10, 16, v12
	v_and_b32_e32 v11, 0xffff0000, v12
	v_lshlrev_b32_e32 v12, 16, v13
	v_and_b32_e32 v13, 0xffff0000, v13
	s_nop 1
	v_mfma_f32_16x16x32_bf16 v[2:5], v[6:9], v[2:5], v[10:13]
	v_lshl_add_u64 v[6:7], v[14:15], 0, v[0:1]
	v_add_co_u32_e32 v6, vcc, 0xc3c8000, v6
	s_nop 1
	v_addc_co_u32_e32 v7, vcc, 0, v7, vcc
	s_nop 2
	flat_store_dwordx4 v[6:7], v[2:5]
	v_cmp_eq_u32_e32 vcc, 0, v202
	buffer_wbl2 sc1
	s_waitcnt vmcnt(0) lgkmcnt(0)
	buffer_inv sc1
	s_barrier
	s_and_saveexec_b64 s[2:3], vcc
	s_cbranch_execz .LBB0_235
	v_mov_b64_e32 v[2:3], s[28:29]
	flat_atomic_add v[2:3], v191 offset:2048

; __device__ __forceinline__ unsigned f2bf(float f) { return pk2(f, f) & 0xffffu; }
; __device__ __forceinline__ float sigmoidf_(float x) { return __builtin_amdgcn_rcpf(1.0f + __expf(-x)); }
; __device__ __forceinline__ float tanhf_(float x) { const float e = __expf(-2.0f * fabsf(x)); const float t = (1.0f - e) * __builtin_amdgcn_rcpf(1.0f + e); return x < 0.f ? -t : t; }
; __device__ __forceinline__ void rwkv_prep_unit(const Args& c, int u, int l, LAS unsigned char* lds) {
;     ...
;     for (int it = 0; it < 9; ++it) {
;         const int idx = tid + it * NTHR;
;         const int t = idx / 288, j = idx % 288, tok = tok0 + t;
;         const bool use = (j < 256) || (l > 0);
;         const int col = (j < 256) ? 1536 + j : 1792 + (j - 256);
;         const float m_ = (j < 256) ? mu[1536 + j] : ((l > 0) ? c.in[5 + z_][(size_t)(l - 1) * 32 + (j - 256)] : 0.f);
;         const bool hp = (tok & (T - 1)) != 0;
;         const float cur = bf2f(P[(size_t)tok * PW + col]);
;         const float pv = bf2f(P[(size_t)(hp ? tok - 1 : tok) * PW + col]);
;         const float prev = hp ? pv : 0.f;
;         float x = cur + (prev - cur) * m_;
;         const float xt = tanhf_(x), xs_ = sigmoidf_(x);
;         x = (j < 64) ? xt : ((j >= 128 && j < 256) ? xs_ : x);
;         xs[t * 296 + j] = (bf16)f2bf(use ? x : 0.f);
;     }
.LBB0_313:
	s_or_b64 exec, exec, s[2:3]
	s_add_u32 s30, s24, 0xa800000
	v_add3_u32 v5, s14, v4, -3
	s_addc_u32 s31, s25, 0
	v_lshrrev_b32_e32 v204, 5, v179
	v_and_b32_e32 v205, 31, v179
	v_add3_u32 v204, s14, v204, -4
	v_max_i32_e32 v204, 0, v204
	v_mul_u32_u24_e32 v204, 0x3800, v204
	v_lshl_add_u32 v204, v205, 7, v204
	global_load_dword v206, v204, s[30:31]
	s_add_i32 s0, s14, 12
	s_mul_i32 s0, s0, 0x3800
	v_lshl_add_u32 v205, v205, 7, s0
	global_load_dword v207, v205, s[30:31]
	s_add_u32 s0, s24, 0x1c800000
	s_addc_u32 s1, s25, 0
	v_bfe_u32 v208, v179, 3, 4
	v_and_b32_e32 v209, 7, v179
	v_add3_u32 v208, s14, v208, -3
	v_lshlrev_b32_e32 v208, 10, v208
	v_lshl_add_u32 v208, v209, 7, v208
	global_load_dword v209, v208, s[0:1]
	v_readlane_b32 s0, v250, 46
	v_and_b32_e32 v6, 0x7ff, v5
	v_readlane_b32 s1, v250, 47
	v_cmp_ne_u32_e64 s[6:7], 0, v6
	v_mov_b64_e32 v[6:7], s[30:31]
	s_or_b64 vcc, s[0:1], s[44:45]
	v_mad_i64_i32 v[8:9], s[0:1], v5, s27, v[6:7]
	v_subbrev_co_u32_e64 v5, s[8:9], 0, v4, s[6:7]
	v_add_u32_e32 v0, 0x600, v2
	v_add3_u32 v5, s14, v5, -3
	v_lshlrev_b64 v[10:11], 1, v[0:1]
	v_mad_i64_i32 v[6:7], s[0:1], v5, s27, v[6:7]
	v_lshl_add_u64 v[8:9], v[8:9], 0, v[10:11]
	v_lshl_add_u64 v[6:7], v[6:7], 0, v[10:11]
	flat_load_ushort v0, v[8:9]
	flat_load_ushort v5, v[6:7]
	v_and_b32_e32 v6, 0x7fffff80, v2
	s_movk_i32 s0, 0x80
	v_cmp_eq_u32_e64 s[8:9], s0, v6
	s_waitcnt vmcnt(0) lgkmcnt(0)
	v_lshlrev_b32_e32 v0, 16, v0
	v_lshlrev_b32_e32 v5, 16, v5
	v_cndmask_b32_e64 v5, 0, v5, s[6:7]
	v_sub_f32_e32 v5, v5, v0
	v_fmac_f32_e32 v0, v3, v5
	v_mul_f32_e64 v3, |v0|, -2.0
	v_mul_f32_e32 v3, 0x3fb8aa3b, v3
	v_exp_f32_e32 v3, v3
	v_cmp_gt_f32_e64 s[6:7], 0, v0
	v_sub_f32_e32 v5, 1.0, v3
	v_add_f32_e32 v3, 1.0, v3
	v_rcp_f32_e32 v3, v3
	s_nop 0
	v_mul_f32_e32 v3, v5, v3
	v_mul_f32_e32 v5, 0xbfb8aa3b, v0
	v_exp_f32_e32 v5, v5
	v_cndmask_b32_e64 v3, v3, -v3, s[6:7]
	v_cmp_gt_i32_e64 s[6:7], 64, v2
	v_lshlrev_b32_e32 v2, 1, v2
	v_add_f32_e32 v5, 1.0, v5
	v_rcp_f32_e32 v5, v5
	s_nop 0
	v_cndmask_b32_e64 v0, v0, v5, s[8:9]
	v_cndmask_b32_e64 v0, v0, v3, s[6:7]
	v_cvt_pk_bf16_f32 v0, v0, s0
	v_mul_i32_i24_e32 v3, 0x250, v4
	v_cndmask_b32_e32 v0, 0, v0, vcc
	v_add3_u32 v2, 0, v3, v2
	ds_write_b16 v2, v0
	v_add_u32_e32 v0, 0x200, v116
	s_mov_b32 s0, 0x38e38e39
	v_mul_hi_i32 v2, v0, s0
	v_lshrrev_b32_e32 v3, 31, v2
	v_ashrrev_i32_e32 v2, 6, v2
	v_add_u32_e32 v4, v2, v3
	v_mul_i32_i24_e32 v5, 0x120, v4
	v_sub_u32_e32 v2, v0, v5
	s_movk_i32 s0, 0x100
	v_cmp_gt_i32_e64 s[44:45], s0, v2
	s_movk_i32 s0, 0xff
	v_cmp_lt_i32_e32 vcc, s0, v2
	s_and_saveexec_b64 s[0:1], vcc
	s_xor_b64 s[2:3], exec, s[0:1]
	s_cbranch_execz .LBB0_316
	s_and_b64 vcc, exec, s[42:43]
	v_mov_b32_e32 v3, 0
	s_cbranch_vccnz .LBB0_316
	s_load_dwordx2 s[0:1], s[12:13], 0x28
	v_readlane_b32 s4, v250, 48
	v_readlane_b32 s5, v250, 49
	v_mov_b32_e32 v3, v1
	s_waitcnt lgkmcnt(0)
	s_add_u32 s0, s0, s4
	s_addc_u32 s1, s1, s5
	v_lshl_add_u64 v[6:7], v[2:3], 2, s[0:1]
	global_load_dword v3, v[6:7], off offset:-1024

; #define LAS __attribute__((address_space(3)))
; #define MFMA16(a, b, c) __builtin_amdgcn_mfma_f32_16x16x32_bf16(a, b, c, 0, 0, 0)
; __device__ __forceinline__ unsigned f2bf(float f) { return pk2(f, f) & 0xffffu; }
; __device__ __forceinline__ void rwkv_prep_unit(const Args& c, int u, int l, LAS unsigned char* lds) {
;     ...
;         xs[t * 296 + j] = (bf16)f2bf(use ? x : 0.f);
;     }
;     __syncthreads();
;     f32x4 aw[4], aa[4], ag[4], av[4];
; #pragma unroll
;     for (int jb = 0; jb < 4; ++jb) { aw[jb] = (f32x4){0.f, 0.f, 0.f, 0.f}; aa[jb] = aw[jb]; ag[jb] = aw[jb]; av[jb] = aw[jb]; }
;     const bf16* Lt = ((bf16*)(wsl + WS_LORA)) + (size_t)(64 * w + r) * 288 + q4 * 8;
; #pragma unroll
;     for (int ks = 0; ks < 9; ++ks) {
;         const bf16x8 af = *(const LAS bf16x8*)(xs + r * 296 + ks * 32 + q4 * 8);
; #pragma unroll
;         for (int jb = 0; jb < 4; ++jb) {
;             const bf16x8 bf = *(const bf16x8*)(Lt + (size_t)jb * 16 * 288 + ks * 32);
;             if (ks < 2) aw[jb] = MFMA16(af, bf, aw[jb]); else if (ks < 4) aa[jb] = MFMA16(af, bf, aa[jb]); else if (ks < 8) ag[jb] = MFMA16(af, bf, ag[jb]); else av[jb] = MFMA16(af, bf, av[jb]);
.LBB0_353:
	s_or_b64 exec, exec, s[2:3]
	v_add3_u32 v8, s14, v4, -3
	v_readlane_b32 s0, v250, 46
	v_and_b32_e32 v6, 0x7ff, v8
	v_readlane_b32 s1, v250, 47
	v_add_u32_e32 v0, 0x600, v2
	v_cmp_ne_u32_e64 s[6:7], 0, v6
	v_mov_b64_e32 v[6:7], s[30:31]
	s_or_b64 vcc, s[0:1], s[44:45]
	v_mad_i64_i32 v[8:9], s[0:1], v8, s27, v[6:7]
	v_lshlrev_b64 v[10:11], 1, v[0:1]
	v_lshl_add_u64 v[8:9], v[8:9], 0, v[10:11]
	flat_load_ushort v0, v[8:9]
	v_subbrev_co_u32_e64 v8, s[8:9], 0, v4, s[6:7]
	v_add3_u32 v8, s14, v8, -3
	v_mad_i64_i32 v[6:7], s[0:1], v8, s27, v[6:7]
	v_lshl_add_u64 v[6:7], v[6:7], 0, v[10:11]
	flat_load_ushort v6, v[6:7]
	s_movk_i32 s0, 0x80
	v_and_b32_e32 v117, 15, v116
	v_mov_b32_e32 v103, 0
	s_waitcnt vmcnt(0) lgkmcnt(0)
	v_lshlrev_b32_e32 v0, 16, v0
	v_lshlrev_b32_e32 v6, 16, v6
	v_cndmask_b32_e64 v6, 0, v6, s[6:7]
	v_sub_f32_e32 v6, v6, v0
	v_fmac_f32_e32 v0, v3, v6
	v_mul_f32_e64 v3, |v0|, -2.0
	v_mul_f32_e32 v3, 0x3fb8aa3b, v3
	v_exp_f32_e32 v3, v3
	v_cmp_gt_f32_e64 s[6:7], 0, v0
	v_sub_f32_e32 v6, 1.0, v3
	v_add_f32_e32 v3, 1.0, v3
	v_rcp_f32_e32 v3, v3
	s_nop 0
	v_mul_f32_e32 v3, v6, v3
	v_mul_f32_e32 v6, 0xbfb8aa3b, v0
	v_exp_f32_e32 v6, v6
	v_cndmask_b32_e64 v3, v3, -v3, s[6:7]
	v_cmp_gt_i32_e64 s[6:7], 64, v2
	v_and_b32_e32 v2, 0x7fffff80, v2
	v_add_f32_e32 v6, 1.0, v6
	v_rcp_f32_e32 v6, v6
	v_cmp_eq_u32_e64 s[8:9], s0, v2
	v_mul_i32_i24_e32 v2, 0x250, v4
	v_mul_u32_u24_e32 v4, 0x250, v117
	v_cndmask_b32_e64 v0, v0, v6, s[8:9]
	v_cndmask_b32_e64 v0, v0, v3, s[6:7]
	v_sub_u32_e32 v3, v116, v5
	v_cvt_pk_bf16_f32 v0, v0, s0
	v_lshlrev_b32_e32 v3, 1, v3
	v_cndmask_b32_e32 v0, 0, v0, vcc
	v_add3_u32 v2, 0, v2, v3
	s_and_b32 s0, s16, 0xffffffc0
	ds_write_b16 v2, v0 offset:8192
	v_or_b32_e32 v68, s0, v117
	v_mov_b64_e32 v[2:3], s[24:25]
	s_movk_i32 s0, 0x240
	v_mad_i64_i32 v[2:3], s[0:1], v68, s0, v[2:3]
	v_and_b32_e32 v0, 48, v116
	v_lshl_add_u64 v[2:3], v[2:3], 0, v[0:1]
	s_mov_b64 s[0:1], 0x6700000
	v_lshl_add_u64 v[48:49], v[2:3], 0, s[0:1]
	s_mov_b32 s0, 0x6700000
	v_add_co_u32_e32 v8, vcc, s0, v2
	s_mov_b32 s0, 0x6702000
	s_nop 0
	v_addc_co_u32_e32 v9, vcc, 0, v3, vcc
	v_add_co_u32_e32 v56, vcc, s0, v2
	s_mov_b32 s0, 0x6704000
	s_nop 0
	v_addc_co_u32_e32 v57, vcc, 0, v3, vcc
	v_add_co_u32_e32 v50, vcc, s0, v2
	s_waitcnt lgkmcnt(0)
	s_nop 0
	v_addc_co_u32_e32 v51, vcc, 0, v3, vcc
	s_barrier
	v_add3_u32 v0, 0, v4, v0
	v_ashrrev_i32_e32 v69, 31, v68
	s_mov_b64 s[0:1], 0x6700000
	v_lshl_add_u64 v[86:87], v[2:3], 0, s[0:1]
	s_mov_b64 s[0:1], 0x6702000
	v_lshl_add_u64 v[88:89], v[2:3], 0, s[0:1]
	s_mov_b64 s[0:1], 0x6704000
	v_lshl_add_u64 v[90:91], v[2:3], 0, s[0:1]
	s_mov_b64 s[0:1], 0x6706000
	v_lshl_add_u64 v[188:189], v[2:3], 0, s[0:1]
	ds_read_b128 v[204:207], v0
	ds_read_b128 v[208:211], v0 offset:64
	ds_read_b128 v[212:215], v0 offset:128
	ds_read_b128 v[216:219], v0 offset:192
	ds_read_b128 v[220:223], v0 offset:256
	ds_read_b128 v[224:227], v0 offset:320
	ds_read_b128 v[228:231], v0 offset:384
	ds_read_b128 v[232:235], v0 offset:448
	ds_read_b128 v[236:239], v0 offset:512
	global_load_dwordx4 v[240:243], v[86:87], off
	global_load_dwordx4 v[94:97], v[88:89], off offset:1024
	global_load_dwordx4 v[98:101], v[90:91], off offset:2048
	global_load_dwordx4 v[104:107], v[188:189], off offset:3072
	global_load_dwordx4 v[108:111], v[86:87], off offset:64
	global_load_dwordx4 v[112:115], v[88:89], off offset:1088
	global_load_dwordx4 v[136:139], v[90:91], off offset:2112
	global_load_dwordx4 v[140:143], v[188:189], off offset:3136
	global_load_dwordx4 v[144:147], v[86:87], off offset:128
	global_load_dwordx4 v[148:151], v[88:89], off offset:1152
	global_load_dwordx4 v[152:155], v[90:91], off offset:2176
	global_load_dwordx4 v[156:159], v[188:189], off offset:3200
	global_load_dwordx4 v[160:163], v[86:87], off offset:192
	global_load_dwordx4 v[164:167], v[88:89], off offset:1216
	global_load_dwordx4 v[168:171], v[90:91], off offset:2240
	global_load_dwordx4 v[172:175], v[188:189], off offset:3264
	global_load_dwordx4 v[184:187], v[86:87], off offset:256
	global_load_dwordx4 v[70:73], v[88:89], off offset:1280
	v_lshl_add_u64 v[74:75], v[68:69], 2, s[40:41]
	s_waitcnt vmcnt(17) lgkmcnt(8)
	v_mfma_f32_16x16x32_bf16 v[16:19], v[204:207], v[240:243], 0
	global_load_dwordx4 v[240:243], v[90:91], off offset:2304
	s_waitcnt vmcnt(17)
	v_mfma_f32_16x16x32_bf16 v[12:15], v[204:207], v[94:97], 0
	global_load_dwordx4 v[94:97], v[188:189], off offset:3328
	s_waitcnt vmcnt(17)
	v_mfma_f32_16x16x32_bf16 v[8:11], v[204:207], v[98:101], 0
	global_load_dwordx4 v[98:101], v[86:87], off offset:320
	s_waitcnt vmcnt(17)
	v_mfma_f32_16x16x32_bf16 v[4:7], v[204:207], v[104:107], 0
	global_load_dwordx4 v[104:107], v[88:89], off offset:1344
	s_waitcnt vmcnt(17) lgkmcnt(7)
	v_mfma_f32_16x16x32_bf16 v[16:19], v[208:211], v[108:111], v[16:19]
	global_load_dwordx4 v[108:111], v[90:91], off offset:2368
	s_waitcnt vmcnt(17)
; #define LAS __attribute__((address_space(3)))
; #define MFMA16(a, b, c) __builtin_amdgcn_mfma_f32_16x16x32_bf16(a, b, c, 0, 0, 0)
; __device__ __forceinline__ void rwkv_prep_unit(const Args& c, int u, int l, LAS unsigned char* lds) {
;     ...
;     for (int ks = 0; ks < 9; ++ks) {
;         const bf16x8 af = *(const LAS bf16x8*)(xs + r * 296 + ks * 32 + q4 * 8);
; #pragma unroll
;         for (int jb = 0; jb < 4; ++jb) {
;             const bf16x8 bf = *(const bf16x8*)(Lt + (size_t)jb * 16 * 288 + ks * 32);
;             if (ks < 2) aw[jb] = MFMA16(af, bf, aw[jb]); else if (ks < 4) aa[jb] = MFMA16(af, bf, aa[jb]); else if (ks < 8) ag[jb] = MFMA16(af, bf, ag[jb]); else av[jb] = MFMA16(af, bf, av[jb]);
;         }
;     }
;     float rr[4][4], k2[4][4], vv[4][4], dec[4][4], asg[4][4], kkr[4][4], rkv[4];
; #pragma unroll
;     for (int jb = 0; jb < 4; ++jb) {
;         const int ch = 64 * w + 16 * jb + r;
;         const float mu_r = mu[ch], mu_k = mu[512 + ch], mu_v = mu[1024 + ch];
;         const float w0 = c.in[6 + z_][l * 512 + ch], a0 = c.in[8 + z_][l * 512 + ch], kk_ = c.in[13 + z_][l * 512 + ch], ka_ = c.in[14 + z_][l * 512 + ch];
;         rkv[jb] = c.in[15 + z_][l * 512 + ch];
	v_mfma_f32_16x16x32_bf16 v[12:15], v[208:211], v[112:115], v[12:15]
	global_load_dwordx4 v[112:115], v[188:189], off offset:3392
	s_waitcnt vmcnt(17)
	v_mfma_f32_16x16x32_bf16 v[8:11], v[208:211], v[136:139], v[8:11]
	global_load_dwordx4 v[136:139], v[86:87], off offset:384
	s_waitcnt vmcnt(17)
	v_mfma_f32_16x16x32_bf16 v[4:7], v[208:211], v[140:143], v[4:7]
	global_load_dwordx4 v[140:143], v[88:89], off offset:1408
	s_waitcnt vmcnt(17) lgkmcnt(6)
	v_mfma_f32_16x16x32_bf16 v[20:23], v[212:215], v[144:147], 0
	global_load_dwordx4 v[144:147], v[90:91], off offset:2432
	s_waitcnt vmcnt(17)
	v_mfma_f32_16x16x32_bf16 v[24:27], v[212:215], v[148:151], 0
	global_load_dwordx4 v[148:151], v[188:189], off offset:3456
	s_waitcnt vmcnt(17)
	v_mfma_f32_16x16x32_bf16 v[28:31], v[212:215], v[152:155], 0
	global_load_dwordx4 v[152:155], v[86:87], off offset:448
	s_waitcnt vmcnt(17)
	v_mfma_f32_16x16x32_bf16 v[32:35], v[212:215], v[156:159], 0
	global_load_dwordx4 v[156:159], v[88:89], off offset:1472
	s_waitcnt vmcnt(17) lgkmcnt(5)
	v_mfma_f32_16x16x32_bf16 v[20:23], v[216:219], v[160:163], v[20:23]
	global_load_dwordx4 v[160:163], v[90:91], off offset:2496
	s_waitcnt vmcnt(17)
	v_mfma_f32_16x16x32_bf16 v[24:27], v[216:219], v[164:167], v[24:27]
	global_load_dwordx4 v[164:167], v[188:189], off offset:3520
	s_waitcnt vmcnt(17)
	v_mfma_f32_16x16x32_bf16 v[28:31], v[216:219], v[168:171], v[28:31]
	global_load_dwordx4 v[168:171], v[86:87], off offset:512
	s_waitcnt vmcnt(17)
	v_mfma_f32_16x16x32_bf16 v[32:35], v[216:219], v[172:175], v[32:35]
	global_load_dwordx4 v[172:175], v[88:89], off offset:1536
	s_waitcnt vmcnt(17) lgkmcnt(4)
	v_mfma_f32_16x16x32_bf16 v[60:63], v[220:223], v[184:187], 0
	global_load_dwordx4 v[184:187], v[90:91], off offset:2560
	s_waitcnt vmcnt(17)
	v_mfma_f32_16x16x32_bf16 v[52:55], v[220:223], v[70:73], 0
	global_load_dwordx4 v[70:73], v[188:189], off offset:3584
	s_waitcnt vmcnt(17)
	v_mfma_f32_16x16x32_bf16 v[44:47], v[220:223], v[240:243], 0
	s_waitcnt vmcnt(16)
	v_mfma_f32_16x16x32_bf16 v[36:39], v[220:223], v[94:97], 0
	s_waitcnt vmcnt(15) lgkmcnt(3)
	v_mfma_f32_16x16x32_bf16 v[60:63], v[224:227], v[98:101], v[60:63]
	s_waitcnt vmcnt(14)
	v_mfma_f32_16x16x32_bf16 v[52:55], v[224:227], v[104:107], v[52:55]
	s_waitcnt vmcnt(13)
	v_mfma_f32_16x16x32_bf16 v[44:47], v[224:227], v[108:111], v[44:47]
	s_waitcnt vmcnt(12)
	v_mfma_f32_16x16x32_bf16 v[36:39], v[224:227], v[112:115], v[36:39]
	s_waitcnt vmcnt(11) lgkmcnt(2)
	v_mfma_f32_16x16x32_bf16 v[60:63], v[228:231], v[136:139], v[60:63]
	s_waitcnt vmcnt(10)
	v_mfma_f32_16x16x32_bf16 v[52:55], v[228:231], v[140:143], v[52:55]
	s_waitcnt vmcnt(9)
	v_mfma_f32_16x16x32_bf16 v[44:47], v[228:231], v[144:147], v[44:47]
	s_waitcnt vmcnt(8)
	v_mfma_f32_16x16x32_bf16 v[36:39], v[228:231], v[148:151], v[36:39]
	s_waitcnt vmcnt(7) lgkmcnt(1)
	v_mfma_f32_16x16x32_bf16 v[60:63], v[232:235], v[152:155], v[60:63]
	s_waitcnt vmcnt(6)
	v_mfma_f32_16x16x32_bf16 v[52:55], v[232:235], v[156:159], v[52:55]
	s_waitcnt vmcnt(5)
	v_mfma_f32_16x16x32_bf16 v[44:47], v[232:235], v[160:163], v[44:47]
	s_waitcnt vmcnt(4)
	v_mfma_f32_16x16x32_bf16 v[36:39], v[232:235], v[164:167], v[36:39]
	s_waitcnt vmcnt(3) lgkmcnt(0)
	v_mfma_f32_16x16x32_bf16 v[64:67], v[236:239], v[168:171], 0
	s_waitcnt vmcnt(2)
	v_mfma_f32_16x16x32_bf16 v[56:59], v[236:239], v[172:175], 0
	s_waitcnt vmcnt(1)
	v_mfma_f32_16x16x32_bf16 v[48:51], v[236:239], v[184:187], 0
	s_waitcnt vmcnt(0)
	v_mfma_f32_16x16x32_bf16 v[40:43], v[236:239], v[70:73], 0
	s_movk_i32 s0, 0x1000
	s_load_dwordx2 s[2:3], s[12:13], 0x78
	s_load_dwordx2 s[6:7], s[12:13], 0x30
	s_load_dwordx2 s[4:5], s[12:13], 0x40
	s_load_dwordx4 s[8:11], s[12:13], 0x68
	v_add_co_u32_e32 v2, vcc, s0, v74
	v_readlane_b32 s0, v250, 50
	s_nop 0
	v_addc_co_u32_e32 v3, vcc, 0, v75, vcc
	global_load_dword v129, v[74:75], off
	global_load_dword v130, v[74:75], off offset:2048
	global_load_dword v102, v[2:3], off
	v_add_u32_e32 v2, s0, v68
	v_ashrrev_i32_e32 v3, 31, v2
	v_lshlrev_b64 v[2:3], 2, v[2:3]
	s_waitcnt lgkmcnt(0)
	v_lshl_add_u64 v[76:77], s[6:7], 0, v[2:3]
	v_lshl_add_u64 v[78:79], s[4:5], 0, v[2:3]
	v_lshl_add_u64 v[80:81], s[8:9], 0, v[2:3]
	v_lshl_add_u64 v[82:83], s[10:11], 0, v[2:3]
	v_lshl_add_u64 v[84:85], s[2:3], 0, v[2:3]
	global_load_dword v131, v[76:77], off
	global_load_dword v133, v[78:79], off
	global_load_dword v132, v[80:81], off
	global_load_dword v135, v[82:83], off
	global_load_dword v134, v[84:85], off
	s_and_b64 vcc, exec, s[42:43]
	s_cbranch_vccnz .LBB0_355
	s_load_dwordx2 s[0:1], s[12:13], 0x58
	v_readlane_b32 s2, v247, 25
	v_readlane_b32 s3, v247, 26
	s_nop 0
	v_add_u32_e32 v2, s2, v68
	v_ashrrev_i32_e32 v3, 31, v2
	s_waitcnt lgkmcnt(0)
	v_lshl_add_u64 v[2:3], v[2:3], 2, s[0:1]
	global_load_dword v103, v[2:3], off

; __device__ __forceinline__ void rwkv_prep_unit(const Args& c, int u, int l, LAS unsigned char* lds) {
;     ...
;         for (int e = 0; e < 4; ++e) {
;             const int tok = tok0 + 4 * q4 + e; const bool hp = (tok & (T - 1)) != 0;
;             const bf16* pr = P + (size_t)tok * PW + ch;
;             const float cr = bf2f(pr[0]), ck = bf2f(pr[512]), cv = bf2f(pr[1024]);
;             const bf16* pp = hp ? pr - PW : pr;
;             const float lr_ = bf2f(pp[0]), lk_ = bf2f(pp[512]), lv_ = bf2f(pp[1024]);
;             const float pr_ = hp ? lr_ : 0.f, pk_ = hp ? lk_ : 0.f, pv_ = hp ? lv_ : 0.f;
;             const float r_ = cr + (pr_ - cr) * mu_r, k_ = ck + (pk_ - ck) * mu_k; float v_ = cv + (pv_ - cv) * mu_v;
;             const float wl = -softplusf_(-(w0 + aw[jb][e])) - 0.5f;
;             const float d_ = __expf(-__expf(wl));
;             const float a_ = sigmoidf_(a0 + aa[jb][e]);
;             if (l == 0) ((bf16*)(wsl + WS_VFIRST))[(size_t)tok * 512 + ch] = (bf16)f2bf(v_);
;             else { const float vf = bf2f(((bf16*)(wsl + WS_VFIRST))[(size_t)tok * 512 + ch]); v_ = v_ + (vf - v_) * sigmoidf_(v0 + av[jb][e]); }
;             rr[jb][e] = r_; vv[jb][e] = v_; dec[jb][e] = d_; asg[jb][e] = a_;
;             kkr[jb][e] = k_ * kk_; k2[jb][e] = k_ * (1.0f + (a_ - 1.0f) * ka_);
;             ((bf16*)(wsl + WS_MIXED))[(size_t)tok * 2048 + ch] = (bf16)f2bf(ag[jb][e]);
;         }
;     }
;     float kkn[4][4], bpn[4][4];
; #pragma unroll
;     for (int e = 0; e < 4; ++e) {
;         const int tok = tok0 + 4 * q4 + e;
;         float ss = 0.f;
; #pragma unroll
;         for (int jb = 0; jb < 4; ++jb) ss += kkr[jb][e] * kkr[jb][e];
;         ss += __shfl_xor(ss, 1); ss += __shfl_xor(ss, 2); ss += __shfl_xor(ss, 4); ss += __shfl_xor(ss, 8);
;         const float rn = rsqrtf(ss + 1e-6f);
;         float bs = 0.f;
; #pragma unroll
;         for (int jb = 0; jb < 4; ++jb) {
;             const int ch = 64 * w + 16 * jb + r;
;             kkn[jb][e] = kkr[jb][e] * rn; bpn[jb][e] = kkn[jb][e] * asg[jb][e];
;             ((float*)(wsl + WS_V))[(size_t)tok * 512 + ch] = vv[jb][e];
;             bs += rr[jb][e] * k2[jb][e] * rkv[jb];
;         }
; #pragma unroll
;         for (int o = 1; o < 16; o <<= 1) bs += __shfl_xor(bs, o);
;         if (r == 0) *(f32x4*)(rsc_ + ((size_t)tok * 8 + w) * 4) = (f32x4){0.f, 0.f, bs, 0.f};
.LBB0_425:
	s_add_i32 s2, s14, s49
	v_lshrrev_b32_e32 v204, 5, v179
	v_and_b32_e32 v205, 31, v179
	v_add3_u32 v204, s2, v204, -4
	v_max_i32_e32 v204, 0, v204
	v_mul_u32_u24_e32 v204, 0x3800, v204
	v_lshl_add_u32 v204, v205, 7, v204
	global_load_dword v206, v204, s[30:31]
	s_add_i32 s0, s2, 12
	s_mul_i32 s0, s0, 0x3800
	v_lshl_add_u32 v205, v205, 7, s0
	global_load_dword v207, v205, s[30:31]
	s_add_u32 s0, s24, 0x1c800000
	s_addc_u32 s1, s25, 0
	v_bfe_u32 v208, v179, 3, 4
	v_and_b32_e32 v209, 7, v179
	v_add3_u32 v208, s2, v208, -3
	v_lshlrev_b32_e32 v208, 10, v208
	v_lshl_add_u32 v208, v209, 7, v208
	global_load_dword v209, v208, s[0:1]
	v_add_f32_e32 v32, v32, v79
	v_mul_f32_e32 v32, 0xbfb8aa3b, v32
	v_exp_f32_e32 v32, v32
	v_lshlrev_b32_e32 v36, 16, v64
	v_cndmask_b32_e64 v36, v36, 0, s[44:45]
	v_add_f32_e32 v20, v20, v133
	v_sub_f32_e32 v36, v36, v66
	v_add_f32_e32 v32, 1.0, v32
	v_lshlrev_b32_e32 v38, 16, v190
	v_mul_f32_e32 v20, 0xbfb8aa3b, v20
	v_fmac_f32_e32 v66, v174, v36
	v_rcp_f32_e32 v57, v32
	v_lshlrev_b32_e32 v36, 16, v63
	v_lshlrev_b32_e32 v63, 16, v189
	v_cndmask_b32_e64 v38, v38, 0, s[44:45]
	v_exp_f32_e32 v20, v20
	v_sub_f32_e32 v38, v38, v63
	v_fmac_f32_e32 v63, v111, v38
	v_lshlrev_b32_e32 v38, 16, v172
	v_cndmask_b32_e64 v38, v38, 0, s[44:45]
	v_add_f32_e32 v32, -1.0, v57
	v_sub_f32_e32 v38, v38, v175
	v_add_f32_e32 v20, 1.0, v20
	v_fma_f32 v32, v77, v32, 1.0
	v_fmac_f32_e32 v175, v146, v38
	v_lshlrev_b32_e32 v38, 16, v171
	v_rcp_f32_e32 v83, v20
	v_mul_f32_e32 v37, v78, v66
	v_mul_f32_e32 v32, v32, v66
	v_lshlrev_b32_e32 v66, 16, v170
	v_cndmask_b32_e64 v38, v38, 0, s[44:45]
	v_sub_f32_e32 v38, v38, v66
	v_lshlrev_b32_e32 v40, 16, v125
	v_fmac_f32_e32 v66, v145, v38
	v_lshlrev_b32_e32 v38, 16, v123
	v_cndmask_b32_e64 v40, v40, 0, s[44:45]
	v_lshlrev_b32_e32 v81, 16, v0
	v_lshlrev_b32_e32 v0, 16, v119
	v_sub_f32_e32 v40, v40, v38
	v_add_f32_e32 v20, -1.0, v83
	v_cndmask_b32_e64 v0, v0, 0, s[44:45]
	v_fmac_f32_e32 v38, v130, v40
	v_fma_f32 v20, v135, v20, 1.0
	v_sub_f32_e32 v0, v0, v81
	v_readlane_b32 s0, v250, 34
	v_mul_f32_e32 v40, v132, v38
	v_mul_f32_e32 v44, v20, v38
	v_fmac_f32_e32 v81, v129, v0
	v_cvt_pk_bf16_f32 v0, v39, s0
	v_lshl_add_u64 v[38:39], v[46:47], 1, v[52:53]
	v_and_b32_e32 v52, 64, v195
	flat_store_short v[38:39], v0
	v_xor_b32_e32 v0, 1, v195
	v_add_u32_e32 v20, 64, v52
	v_cmp_lt_i32_e32 vcc, v0, v20
	v_lshlrev_b32_e32 v62, 16, v62
	v_cndmask_b32_e64 v36, v36, 0, s[44:45]
	v_cndmask_b32_e32 v0, v195, v0, vcc
	v_lshlrev_b32_e32 v119, 2, v0
	v_xor_b32_e32 v0, 2, v195
	v_cmp_lt_i32_e32 vcc, v0, v20
	v_sub_f32_e32 v36, v36, v62
	v_fmac_f32_e32 v62, v51, v36
	v_cndmask_b32_e32 v0, v195, v0, vcc
	v_lshlrev_b32_e32 v123, 2, v0
	v_xor_b32_e32 v0, 4, v195
	v_lshlrev_b32_e32 v36, 16, v192
	v_cmp_lt_i32_e32 vcc, v0, v20
	v_cndmask_b32_e64 v36, v36, 0, s[44:45]
	v_sub_f32_e32 v36, v36, v202
	v_cndmask_b32_e32 v0, v195, v0, vcc
	v_lshlrev_b32_e32 v125, 2, v0
	v_xor_b32_e32 v0, 8, v195
	v_fmac_f32_e32 v202, v112, v36
	v_mul_f32_e32 v41, v149, v175
	v_cmp_lt_i32_e32 vcc, v0, v20
	v_mul_f32_e32 v36, v160, v202
	v_pk_mul_f32 v[38:39], v[40:41], v[40:41]
	v_cndmask_b32_e32 v0, v195, v0, vcc
	v_lshlrev_b32_e32 v95, 2, v0
	v_pk_mul_f32 v[46:47], v[36:37], v[36:37]
	v_add_f32_e32 v0, v38, v39
	v_add_f32_e32 v0, v0, v46
	v_add_f32_e32 v0, v0, v47
	ds_bpermute_b32 v20, v119, v0
	v_add_f32_e32 v24, v24, v150
	v_add_f32_e32 v28, v28, v161
	v_mul_f32_e32 v24, 0xbfb8aa3b, v24
	v_mul_f32_e32 v28, 0xbfb8aa3b, v28
	s_waitcnt lgkmcnt(0)
	v_add_f32_e32 v0, v0, v20
	v_exp_f32_e32 v24, v24
	ds_bpermute_b32 v20, v123, v0
	v_exp_f32_e32 v28, v28
	s_ashr_i32 s2, s16, 6
	v_add_f32_e32 v24, 1.0, v24
	v_rcp_f32_e32 v67, v24
	v_add_f32_e32 v28, 1.0, v28
	s_waitcnt lgkmcnt(0)
	v_add_f32_e32 v0, v0, v20
	v_rcp_f32_e32 v64, v28
	ds_bpermute_b32 v20, v125, v0
	v_add_f32_e32 v24, -1.0, v67
	v_fma_f32 v24, v148, v24, 1.0
	v_add_f32_e32 v28, -1.0, v64
	v_fma_f32 v28, v113, v28, 1.0
	v_mul_f32_e32 v24, v24, v175
	s_waitcnt lgkmcnt(0)
	v_add_f32_e32 v87, v0, v20
	v_mul_f32_e32 v0, v81, v44
	v_mul_f32_e32 v28, v28, v202
	v_fma_f32 v0, v134, v0, 0
	v_mul_f32_e32 v20, v66, v24
	v_fmac_f32_e32 v0, v143, v20
	v_mul_f32_e32 v20, v63, v28
	v_fmac_f32_e32 v0, v110, v20
	v_mul_f32_e32 v20, v62, v32
	v_fmac_f32_e32 v0, v75, v20
	ds_bpermute_b32 v20, v119, v0
	s_add_u32 s4, s24, s0
	s_addc_u32 s5, s25, 0
	s_add_u32 s6, s24, 0x29800000
	ds_bpermute_b32 v91, v95, v87
	s_waitcnt lgkmcnt(0)
	v_add_f32_e32 v0, v0, v20
	ds_bpermute_b32 v20, v123, v0
	s_addc_u32 s7, s25, 0
	s_ashr_i32 s3, s2, 31
	s_lshl_b64 s[0:1], s[2:3], 4
	v_lshlrev_b64 v[38:39], 11, v[2:3]
	s_waitcnt lgkmcnt(0)
	v_add_f32_e32 v0, v0, v20
	ds_bpermute_b32 v20, v125, v0
	s_add_u32 s4, s4, s0
	v_lshl_add_u64 v[38:39], s[6:7], 0, v[38:39]
	v_cmp_eq_u32_e32 vcc, 0, v117
	s_addc_u32 s5, s5, s1
	s_waitcnt lgkmcnt(0)
	v_add_f32_e32 v0, v0, v20
	ds_bpermute_b32 v20, v95, v0
	v_lshl_add_u64 v[38:39], v[68:69], 2, v[38:39]
	flat_store_dword v[38:39], v120
	flat_store_dword v[38:39], v127 offset:64
	flat_store_dword v[38:39], v107 offset:128
	flat_store_dword v[38:39], v54 offset:192
	s_and_saveexec_b64 s[8:9], vcc
	s_cbranch_execz .LBB0_427
	v_lshlrev_b64 v[2:3], 7, v[2:3]
	v_lshl_add_u64 v[38:39], s[4:5], 0, v[2:3]
	s_waitcnt lgkmcnt(0)
	v_add_f32_e32 v2, v0, v20
	v_mov_b32_e32 v0, v1
	v_mov_b32_e32 v3, v1
	flat_store_dwordx4 v[38:39], v[0:3]

; #define LAS __attribute__((address_space(3)))
; __device__ __forceinline__ unsigned f2bf(float f) { return pk2(f, f) & 0xffffu; }
; __device__ __forceinline__ void gdn_prep_unit(const Args& c, int ug, int l, LAS unsigned char* lds) {
;     ...
;             const int j = 16 * jb + r; const float gj = gcs[j];
; #pragma unroll
;             for (int e = 0; e < 4; ++e) {
;                 const int i = 16 * ib + 4 * q4 + e;
;                 const float dcy = (i >= j) ? __expf(gcs[i] - gj) : 0.f;
;                 Mm[i * 68 + j] = (i > j) ? bet[i] * ckk[e] * dcy : 0.f;
;                 ((bf16*)(wsl + WS_AT))[(size_t)ug * 4096 + i * 64 + j] = (bf16)f2bf(cqk[e] * dcy);
;             }
;         }
;     }
;     __syncthreads();
;     if (tid < 256) {
;         const int col = tid & 127; const bool isw = tid >= 128;
;         int vz = 0; asm volatile("" : "+v"(vz));
;         const LAS float* Mz = Mm + vz; const LAS float* betz = bet + vz; const LAS float* egz = egs + vz;
;         float x[64];
; #pragma unroll
;         for (int i = 0; i < 64; ++i) x[i] = isw ? kf[i * 132 + col] * betz[i] * egz[i] : vf[i * 132 + col] * betz[i];
.LBB0_662:
	s_or_b64 exec, exec, s[2:3]
	v_add3_u32 v2, s0, v33, v6
	ds_write_b32 v2, v0
	v_mul_f32_e32 v0, v5, v3
	s_movk_i32 s1, 0x100
	v_cvt_pk_bf16_f32 v0, v0, s0
	v_cmp_gt_i32_e32 vcc, s1, v149
	flat_store_short v[16:17], v0 offset:32
	s_waitcnt lgkmcnt(0)
	s_barrier
	s_and_saveexec_b64 s[6:7], vcc
	s_cbranch_execz .LBB0_623
	v_readfirstlane_b32 s0, v149
	v_and_b32_e32 v68, 0x7f, v149
	v_lshlrev_b32_e32 v68, 2, v68
	v_mov_b32_e32 v2, 0x10800
	v_mov_b32_e32 v3, 0x14d00
	s_nop 3
	s_cmp_ge_u32 s0, 0x80
	s_cselect_b32 s1, 0, 0x8400
	s_cselect_b32 s2, 1, 0
	v_add_u32_e32 v68, s1, v68
	ds_read_b128 v[204:207], v3 offset:0
	ds_read_b128 v[208:211], v3 offset:16
	ds_read_b128 v[212:215], v3 offset:256
	ds_read_b128 v[216:219], v3 offset:272
	ds_read_b32 v4, v68
	ds_read_b32 v5, v68 offset:528
	ds_read_b32 v6, v68 offset:1056
	ds_read_b32 v7, v68 offset:1584
	ds_read_b32 v8, v68 offset:2112
	ds_read_b32 v9, v68 offset:2640
	ds_read_b32 v10, v68 offset:3168
	ds_read_b32 v11, v68 offset:3696
	s_waitcnt lgkmcnt(0)
	v_mul_f32_e32 v4, v204, v4
	v_mul_f32_e32 v5, v205, v5
	v_mul_f32_e32 v6, v206, v6
	v_mul_f32_e32 v7, v207, v7
	v_mul_f32_e32 v8, v208, v8
	v_mul_f32_e32 v9, v209, v9
	v_mul_f32_e32 v10, v210, v10
	v_mul_f32_e32 v11, v211, v11
	s_cmp_eq_u32 s2, 0
	s_cbranch_scc1 .Lgdn4_noeg_0
	v_mul_f32_e32 v4, v4, v212
	v_mul_f32_e32 v5, v5, v213
	v_mul_f32_e32 v6, v6, v214
	v_mul_f32_e32 v7, v7, v215
	v_mul_f32_e32 v8, v8, v216
	v_mul_f32_e32 v9, v9, v217
	v_mul_f32_e32 v10, v10, v218
	v_mul_f32_e32 v11, v11, v219
.Lgdn4_noeg_0:
	ds_read_b128 v[204:207], v3 offset:32
	ds_read_b128 v[208:211], v3 offset:48
	ds_read_b128 v[212:215], v3 offset:288
	ds_read_b128 v[216:219], v3 offset:304
	ds_read_b32 v12, v68 offset:4224
	ds_read_b32 v13, v68 offset:4752
	ds_read_b32 v14, v68 offset:5280
	ds_read_b32 v15, v68 offset:5808
	ds_read_b32 v16, v68 offset:6336
	ds_read_b32 v17, v68 offset:6864
	ds_read_b32 v18, v68 offset:7392
	ds_read_b32 v19, v68 offset:7920
	s_waitcnt lgkmcnt(0)
	v_mul_f32_e32 v12, v204, v12
	v_mul_f32_e32 v13, v205, v13
	v_mul_f32_e32 v14, v206, v14
	v_mul_f32_e32 v15, v207, v15
	v_mul_f32_e32 v16, v208, v16
	v_mul_f32_e32 v17, v209, v17
	v_mul_f32_e32 v18, v210, v18
	v_mul_f32_e32 v19, v211, v19
	s_cmp_eq_u32 s2, 0
	s_cbranch_scc1 .Lgdn4_noeg_1
	v_mul_f32_e32 v12, v12, v212
	v_mul_f32_e32 v13, v13, v213
	v_mul_f32_e32 v14, v14, v214
	v_mul_f32_e32 v15, v15, v215
	v_mul_f32_e32 v16, v16, v216
	v_mul_f32_e32 v17, v17, v217
	v_mul_f32_e32 v18, v18, v218
	v_mul_f32_e32 v19, v19, v219
.Lgdn4_noeg_1:
	ds_read_b128 v[204:207], v3 offset:64
	ds_read_b128 v[208:211], v3 offset:80
	ds_read_b128 v[212:215], v3 offset:320
	ds_read_b128 v[216:219], v3 offset:336
	ds_read_b32 v20, v68 offset:8448
	ds_read_b32 v21, v68 offset:8976
	ds_read_b32 v22, v68 offset:9504
	ds_read_b32 v23, v68 offset:10032
	ds_read_b32 v24, v68 offset:10560
	ds_read_b32 v25, v68 offset:11088
	ds_read_b32 v26, v68 offset:11616
	ds_read_b32 v27, v68 offset:12144
	s_waitcnt lgkmcnt(0)
	v_mul_f32_e32 v20, v204, v20
	v_mul_f32_e32 v21, v205, v21
	v_mul_f32_e32 v22, v206, v22
	v_mul_f32_e32 v23, v207, v23
	v_mul_f32_e32 v24, v208, v24
	v_mul_f32_e32 v25, v209, v25
	v_mul_f32_e32 v26, v210, v26
	v_mul_f32_e32 v27, v211, v27
	s_cmp_eq_u32 s2, 0
	s_cbranch_scc1 .Lgdn4_noeg_2
	v_mul_f32_e32 v20, v20, v212
	v_mul_f32_e32 v21, v21, v213
	v_mul_f32_e32 v22, v22, v214
	v_mul_f32_e32 v23, v23, v215
	v_mul_f32_e32 v24, v24, v216
	v_mul_f32_e32 v25, v25, v217
	v_mul_f32_e32 v26, v26, v218
	v_mul_f32_e32 v27, v27, v219
.Lgdn4_noeg_2:
	ds_read_b128 v[204:207], v3 offset:96
	ds_read_b128 v[208:211], v3 offset:112
	ds_read_b128 v[212:215], v3 offset:352
	ds_read_b128 v[216:219], v3 offset:368
	ds_read_b32 v28, v68 offset:12672
	ds_read_b32 v29, v68 offset:13200
	ds_read_b32 v30, v68 offset:13728
	ds_read_b32 v31, v68 offset:14256
	ds_read_b32 v32, v68 offset:14784
	ds_read_b32 v33, v68 offset:15312
	ds_read_b32 v34, v68 offset:15840
	ds_read_b32 v35, v68 offset:16368
	s_waitcnt lgkmcnt(0)
	v_mul_f32_e32 v28, v204, v28
	v_mul_f32_e32 v29, v205, v29
	v_mul_f32_e32 v30, v206, v30
	v_mul_f32_e32 v31, v207, v31
	v_mul_f32_e32 v32, v208, v32
	v_mul_f32_e32 v33, v209, v33
	v_mul_f32_e32 v34, v210, v34
	v_mul_f32_e32 v35, v211, v35
	s_cmp_eq_u32 s2, 0
	s_cbranch_scc1 .Lgdn4_noeg_3
	v_mul_f32_e32 v28, v28, v212
	v_mul_f32_e32 v29, v29, v213
	v_mul_f32_e32 v30, v30, v214
	v_mul_f32_e32 v31, v31, v215
	v_mul_f32_e32 v32, v32, v216
	v_mul_f32_e32 v33, v33, v217
	v_mul_f32_e32 v34, v34, v218
	v_mul_f32_e32 v35, v35, v219
.Lgdn4_noeg_3:
	ds_read_b128 v[204:207], v3 offset:128
	ds_read_b128 v[208:211], v3 offset:144
	ds_read_b128 v[212:215], v3 offset:384
	ds_read_b128 v[216:219], v3 offset:400
	ds_read_b32 v36, v68 offset:16896
	ds_read_b32 v37, v68 offset:17424
	ds_read_b32 v38, v68 offset:17952
	ds_read_b32 v39, v68 offset:18480
	ds_read_b32 v40, v68 offset:19008
	ds_read_b32 v41, v68 offset:19536
	ds_read_b32 v42, v68 offset:20064
	ds_read_b32 v43, v68 offset:20592
	s_waitcnt lgkmcnt(0)
	v_mul_f32_e32 v36, v204, v36
	v_mul_f32_e32 v37, v205, v37
	v_mul_f32_e32 v38, v206, v38
	v_mul_f32_e32 v39, v207, v39
	v_mul_f32_e32 v40, v208, v40
	v_mul_f32_e32 v41, v209, v41
	v_mul_f32_e32 v42, v210, v42
	v_mul_f32_e32 v43, v211, v43
	s_cmp_eq_u32 s2, 0
	s_cbranch_scc1 .Lgdn4_noeg_4
	v_mul_f32_e32 v36, v36, v212
	v_mul_f32_e32 v37, v37, v213
	v_mul_f32_e32 v38, v38, v214
	v_mul_f32_e32 v39, v39, v215
	v_mul_f32_e32 v40, v40, v216
	v_mul_f32_e32 v41, v41, v217
	v_mul_f32_e32 v42, v42, v218
	v_mul_f32_e32 v43, v43, v219
; #define LAS __attribute__((address_space(3)))
; __device__ __forceinline__ void gdn_prep_unit(const Args& c, int ug, int l, LAS unsigned char* lds) {
;     ...
;         for (int i = 0; i < 64; ++i) x[i] = isw ? kf[i * 132 + col] * betz[i] * egz[i] : vf[i * 132 + col] * betz[i];
; #pragma unroll
;         for (int i = 1; i < 64; ++i) {
;             float s0 = x[i], s1 = 0.f, s2 = 0.f, s3 = 0.f;
; #pragma unroll
;             for (int m4 = 0; m4 < i; m4 += 4) {
;                 const f32x4 mv = *(const LAS f32x4*)(Mz + i * 68 + m4);
;                 s0 -= mv.x * x[m4];
;                 if (m4 + 1 < i) s1 -= mv.y * x[m4 + 1];
;                 if (m4 + 2 < i) s2 -= mv.z * x[m4 + 2];
;                 if (m4 + 3 < i) s3 -= mv.w * x[m4 + 3];
;             }
;             const float s = (s0 + s1) + (s2 + s3);
;             x[i] = s;
.Lgdn4_noeg_4:
	ds_read_b128 v[204:207], v3 offset:160
	ds_read_b128 v[208:211], v3 offset:176
	ds_read_b128 v[212:215], v3 offset:416
	ds_read_b128 v[216:219], v3 offset:432
	ds_read_b32 v44, v68 offset:21120
	ds_read_b32 v45, v68 offset:21648
	ds_read_b32 v46, v68 offset:22176
	ds_read_b32 v47, v68 offset:22704
	ds_read_b32 v48, v68 offset:23232
	ds_read_b32 v49, v68 offset:23760
	ds_read_b32 v50, v68 offset:24288
	ds_read_b32 v51, v68 offset:24816
	s_waitcnt lgkmcnt(0)
	v_mul_f32_e32 v44, v204, v44
	v_mul_f32_e32 v45, v205, v45
	v_mul_f32_e32 v46, v206, v46
	v_mul_f32_e32 v47, v207, v47
	v_mul_f32_e32 v48, v208, v48
	v_mul_f32_e32 v49, v209, v49
	v_mul_f32_e32 v50, v210, v50
	v_mul_f32_e32 v51, v211, v51
	s_cmp_eq_u32 s2, 0
	s_cbranch_scc1 .Lgdn4_noeg_5
	v_mul_f32_e32 v44, v44, v212
	v_mul_f32_e32 v45, v45, v213
	v_mul_f32_e32 v46, v46, v214
	v_mul_f32_e32 v47, v47, v215
	v_mul_f32_e32 v48, v48, v216
	v_mul_f32_e32 v49, v49, v217
	v_mul_f32_e32 v50, v50, v218
	v_mul_f32_e32 v51, v51, v219
.Lgdn4_noeg_5:
	ds_read_b128 v[204:207], v3 offset:192
	ds_read_b128 v[208:211], v3 offset:208
	ds_read_b128 v[212:215], v3 offset:448
	ds_read_b128 v[216:219], v3 offset:464
	ds_read_b32 v52, v68 offset:25344
	ds_read_b32 v53, v68 offset:25872
	ds_read_b32 v54, v68 offset:26400
	ds_read_b32 v55, v68 offset:26928
	ds_read_b32 v56, v68 offset:27456
	ds_read_b32 v57, v68 offset:27984
	ds_read_b32 v58, v68 offset:28512
	ds_read_b32 v59, v68 offset:29040
	s_waitcnt lgkmcnt(0)
	v_mul_f32_e32 v52, v204, v52
	v_mul_f32_e32 v53, v205, v53
	v_mul_f32_e32 v54, v206, v54
	v_mul_f32_e32 v55, v207, v55
	v_mul_f32_e32 v56, v208, v56
	v_mul_f32_e32 v57, v209, v57
	v_mul_f32_e32 v58, v210, v58
	v_mul_f32_e32 v59, v211, v59
	s_cmp_eq_u32 s2, 0
	s_cbranch_scc1 .Lgdn4_noeg_6
	v_mul_f32_e32 v52, v52, v212
	v_mul_f32_e32 v53, v53, v213
	v_mul_f32_e32 v54, v54, v214
	v_mul_f32_e32 v55, v55, v215
	v_mul_f32_e32 v56, v56, v216
	v_mul_f32_e32 v57, v57, v217
	v_mul_f32_e32 v58, v58, v218
	v_mul_f32_e32 v59, v59, v219
.Lgdn4_noeg_6:
	ds_read_b128 v[204:207], v3 offset:224
	ds_read_b128 v[208:211], v3 offset:240
	ds_read_b128 v[212:215], v3 offset:480
	ds_read_b128 v[216:219], v3 offset:496
	ds_read_b32 v60, v68 offset:29568
	ds_read_b32 v61, v68 offset:30096
	ds_read_b32 v62, v68 offset:30624
	ds_read_b32 v63, v68 offset:31152
	ds_read_b32 v64, v68 offset:31680
	ds_read_b32 v65, v68 offset:32208
	ds_read_b32 v66, v68 offset:32736
	ds_read_b32 v67, v68 offset:33264
	s_waitcnt lgkmcnt(0)
	v_mul_f32_e32 v60, v204, v60
	v_mul_f32_e32 v61, v205, v61
	v_mul_f32_e32 v62, v206, v62
	v_mul_f32_e32 v63, v207, v63
	v_mul_f32_e32 v64, v208, v64
	v_mul_f32_e32 v65, v209, v65
	v_mul_f32_e32 v66, v210, v66
	v_mul_f32_e32 v67, v211, v67
	s_cmp_eq_u32 s2, 0
	s_cbranch_scc1 .Lgdn4_noeg_7
	v_mul_f32_e32 v60, v60, v212
	v_mul_f32_e32 v61, v61, v213
	v_mul_f32_e32 v62, v62, v214
	v_mul_f32_e32 v63, v63, v215
	v_mul_f32_e32 v64, v64, v216
	v_mul_f32_e32 v65, v65, v217
	v_mul_f32_e32 v66, v66, v218
	v_mul_f32_e32 v67, v67, v219
.Lgdn4_noeg_7:
	ds_read_b128 v[204:207], v2 offset:272
	ds_read_b128 v[208:211], v2 offset:544
	ds_read_b128 v[212:215], v2 offset:816
	ds_read_b128 v[216:219], v2 offset:1088
	ds_read_b128 v[220:223], v2 offset:1360
	ds_read_b128 v[224:227], v2 offset:1376
	ds_read_b128 v[228:231], v2 offset:1632
	ds_read_b128 v[232:235], v2 offset:1648
	ds_read_b128 v[236:239], v2 offset:1904
	ds_read_b128 v[240:243], v2 offset:1920
	ds_read_b128 v[180:183], v2 offset:2176
	ds_read_b128 v[70:73], v2 offset:2192
	s_waitcnt lgkmcnt(11)
	v_fma_f32 v74, -v204, v4, v5
	ds_read_b128 v[204:207], v2 offset:2448
	v_mov_b32_e32 v5, v74
	s_waitcnt lgkmcnt(11)
	v_fma_f32 v74, -v208, v4, v6
	v_fma_f32 v75, -v209, v5, 0
	ds_read_b128 v[208:211], v2 offset:2464
	v_add_f32_e32 v6, v74, v75
	s_waitcnt lgkmcnt(11)
	v_fma_f32 v74, -v212, v4, v7
	v_fma_f32 v75, -v213, v5, 0
	v_fma_f32 v0, -v214, v6, 0
	ds_read_b128 v[212:215], v2 offset:2480
	v_add_f32_e32 v74, v74, v75
	v_add_f32_e32 v7, v74, v0
	s_waitcnt lgkmcnt(11)
	v_fma_f32 v74, -v216, v4, v8
	v_fma_f32 v75, -v217, v5, 0
	v_fma_f32 v0, -v218, v6, 0
	v_fma_f32 v69, -v219, v7, 0
	ds_read_b128 v[216:219], v2 offset:2720
	v_add_f32_e32 v74, v74, v75
	v_add_f32_e32 v0, v0, v69
	v_add_f32_e32 v8, v74, v0
	s_waitcnt lgkmcnt(11)
	v_fma_f32 v74, -v220, v4, v9
	v_fma_f32 v75, -v221, v5, 0
	v_fma_f32 v0, -v222, v6, 0
	v_fma_f32 v69, -v223, v7, 0
	ds_read_b128 v[220:223], v2 offset:2736
	s_waitcnt lgkmcnt(11)
	v_fma_f32 v74, -v224, v8, v74
	ds_read_b128 v[224:227], v2 offset:2752
	v_add_f32_e32 v74, v74, v75
	v_add_f32_e32 v0, v0, v69
	v_add_f32_e32 v9, v74, v0
	s_waitcnt lgkmcnt(11)
	v_fma_f32 v74, -v228, v4, v10
	v_fma_f32 v75, -v229, v5, 0
	v_fma_f32 v0, -v230, v6, 0
	v_fma_f32 v69, -v231, v7, 0
	ds_read_b128 v[228:231], v2 offset:2992
	s_waitcnt lgkmcnt(11)
	v_fma_f32 v74, -v232, v8, v74
	v_fma_f32 v75, -v233, v9, v75
	ds_read_b128 v[232:235], v2 offset:3008
	v_add_f32_e32 v74, v74, v75
	v_add_f32_e32 v0, v0, v69
	v_add_f32_e32 v10, v74, v0
	s_waitcnt lgkmcnt(11)
	v_fma_f32 v74, -v236, v4, v11
	v_fma_f32 v75, -v237, v5, 0
	v_fma_f32 v0, -v238, v6, 0
	v_fma_f32 v69, -v239, v7, 0
	ds_read_b128 v[236:239], v2 offset:3024
	s_waitcnt lgkmcnt(11)
	v_fma_f32 v74, -v240, v8, v74
	v_fma_f32 v75, -v241, v9, v75
	v_fma_f32 v0, -v242, v10, v0
	ds_read_b128 v[240:243], v2 offset:3264
	v_add_f32_e32 v74, v74, v75
	v_add_f32_e32 v0, v0, v69
	v_add_f32_e32 v11, v74, v0
	s_waitcnt lgkmcnt(11)
	v_fma_f32 v74, -v180, v4, v12
	v_fma_f32 v75, -v181, v5, 0
	v_fma_f32 v0, -v182, v6, 0
	v_fma_f32 v69, -v183, v7, 0
	ds_read_b128 v[180:183], v2 offset:3280
	s_waitcnt lgkmcnt(11)
; #define LAS __attribute__((address_space(3)))
; __device__ __forceinline__ void gdn_prep_unit(const Args& c, int ug, int l, LAS unsigned char* lds) {
;     ...
;         for (int i = 1; i < 64; ++i) {
;             float s0 = x[i], s1 = 0.f, s2 = 0.f, s3 = 0.f;
; #pragma unroll
;             for (int m4 = 0; m4 < i; m4 += 4) {
;                 const f32x4 mv = *(const LAS f32x4*)(Mz + i * 68 + m4);
;                 s0 -= mv.x * x[m4];
;                 if (m4 + 1 < i) s1 -= mv.y * x[m4 + 1];
;                 if (m4 + 2 < i) s2 -= mv.z * x[m4 + 2];
;                 if (m4 + 3 < i) s3 -= mv.w * x[m4 + 3];
;             }
;             const float s = (s0 + s1) + (s2 + s3);
;             x[i] = s;
	v_fma_f32 v74, -v70, v8, v74
	v_fma_f32 v75, -v71, v9, v75
	v_fma_f32 v0, -v72, v10, v0
	v_fma_f32 v69, -v73, v11, v69
	ds_read_b128 v[70:73], v2 offset:3296
	v_add_f32_e32 v74, v74, v75
	v_add_f32_e32 v0, v0, v69
	v_add_f32_e32 v12, v74, v0
	s_waitcnt lgkmcnt(11)
	v_fma_f32 v74, -v204, v4, v13
	v_fma_f32 v75, -v205, v5, 0
	v_fma_f32 v0, -v206, v6, 0
	v_fma_f32 v69, -v207, v7, 0
	ds_read_b128 v[204:207], v2 offset:3536
	s_waitcnt lgkmcnt(11)
	v_fma_f32 v74, -v208, v8, v74
	v_fma_f32 v75, -v209, v9, v75
	v_fma_f32 v0, -v210, v10, v0
	v_fma_f32 v69, -v211, v11, v69
	ds_read_b128 v[208:211], v2 offset:3552
	s_waitcnt lgkmcnt(11)
	v_fma_f32 v74, -v212, v12, v74
	ds_read_b128 v[212:215], v2 offset:3568
	v_add_f32_e32 v74, v74, v75
	v_add_f32_e32 v0, v0, v69
	v_add_f32_e32 v13, v74, v0
	s_waitcnt lgkmcnt(11)
	v_fma_f32 v74, -v216, v4, v14
	v_fma_f32 v75, -v217, v5, 0
	v_fma_f32 v0, -v218, v6, 0
	v_fma_f32 v69, -v219, v7, 0
	ds_read_b128 v[216:219], v2 offset:3584
	s_waitcnt lgkmcnt(11)
	v_fma_f32 v74, -v220, v8, v74
	v_fma_f32 v75, -v221, v9, v75
	v_fma_f32 v0, -v222, v10, v0
	v_fma_f32 v69, -v223, v11, v69
	ds_read_b128 v[220:223], v2 offset:3808
	s_waitcnt lgkmcnt(11)
	v_fma_f32 v74, -v224, v12, v74
	v_fma_f32 v75, -v225, v13, v75
	ds_read_b128 v[224:227], v2 offset:3824
	v_add_f32_e32 v74, v74, v75
	v_add_f32_e32 v0, v0, v69
	v_add_f32_e32 v14, v74, v0
	s_waitcnt lgkmcnt(11)
	v_fma_f32 v74, -v228, v4, v15
	v_fma_f32 v75, -v229, v5, 0
	v_fma_f32 v0, -v230, v6, 0
	v_fma_f32 v69, -v231, v7, 0
	ds_read_b128 v[228:231], v2 offset:3840
	s_waitcnt lgkmcnt(11)
	v_fma_f32 v74, -v232, v8, v74
	v_fma_f32 v75, -v233, v9, v75
	v_fma_f32 v0, -v234, v10, v0
	v_fma_f32 v69, -v235, v11, v69
	ds_read_b128 v[232:235], v2 offset:3856
	s_waitcnt lgkmcnt(11)
	v_fma_f32 v74, -v236, v12, v74
	v_fma_f32 v75, -v237, v13, v75
	v_fma_f32 v0, -v238, v14, v0
	ds_read_b128 v[236:239], v2 offset:4080
	v_add_f32_e32 v74, v74, v75
	v_add_f32_e32 v0, v0, v69
	v_add_f32_e32 v15, v74, v0
	s_waitcnt lgkmcnt(11)
	v_fma_f32 v74, -v240, v4, v16
	v_fma_f32 v75, -v241, v5, 0
	v_fma_f32 v0, -v242, v6, 0
	v_fma_f32 v69, -v243, v7, 0
	ds_read_b128 v[240:243], v2 offset:4096
	s_waitcnt lgkmcnt(11)
	v_fma_f32 v74, -v180, v8, v74
	v_fma_f32 v75, -v181, v9, v75
	v_fma_f32 v0, -v182, v10, v0
	v_fma_f32 v69, -v183, v11, v69
	ds_read_b128 v[180:183], v2 offset:4112
	s_waitcnt lgkmcnt(11)
	v_fma_f32 v74, -v70, v12, v74
	v_fma_f32 v75, -v71, v13, v75
	v_fma_f32 v0, -v72, v14, v0
	v_fma_f32 v69, -v73, v15, v69
	ds_read_b128 v[70:73], v2 offset:4128
	v_add_f32_e32 v74, v74, v75
	v_add_f32_e32 v0, v0, v69
	v_add_f32_e32 v16, v74, v0
	s_waitcnt lgkmcnt(11)
	v_fma_f32 v74, -v204, v4, v17
	v_fma_f32 v75, -v205, v5, 0
	v_fma_f32 v0, -v206, v6, 0
	v_fma_f32 v69, -v207, v7, 0
	ds_read_b128 v[204:207], v2 offset:4352
	s_waitcnt lgkmcnt(11)
	v_fma_f32 v74, -v208, v8, v74
	v_fma_f32 v75, -v209, v9, v75
	v_fma_f32 v0, -v210, v10, v0
	v_fma_f32 v69, -v211, v11, v69
	ds_read_b128 v[208:211], v2 offset:4368
	s_waitcnt lgkmcnt(11)
	v_fma_f32 v74, -v212, v12, v74
	v_fma_f32 v75, -v213, v13, v75
	v_fma_f32 v0, -v214, v14, v0
	v_fma_f32 v69, -v215, v15, v69
	ds_read_b128 v[212:215], v2 offset:4384
	s_waitcnt lgkmcnt(11)
	v_fma_f32 v74, -v216, v16, v74
	ds_read_b128 v[216:219], v2 offset:4400
	v_add_f32_e32 v74, v74, v75
	v_add_f32_e32 v0, v0, v69
	v_add_f32_e32 v17, v74, v0
	s_waitcnt lgkmcnt(11)
	v_fma_f32 v74, -v220, v4, v18
	v_fma_f32 v75, -v221, v5, 0
	v_fma_f32 v0, -v222, v6, 0
	v_fma_f32 v69, -v223, v7, 0
	ds_read_b128 v[220:223], v2 offset:4624
	s_waitcnt lgkmcnt(11)
	v_fma_f32 v74, -v224, v8, v74
	v_fma_f32 v75, -v225, v9, v75
	v_fma_f32 v0, -v226, v10, v0
	v_fma_f32 v69, -v227, v11, v69
	ds_read_b128 v[224:227], v2 offset:4640
	s_waitcnt lgkmcnt(11)
	v_fma_f32 v74, -v228, v12, v74
	v_fma_f32 v75, -v229, v13, v75
	v_fma_f32 v0, -v230, v14, v0
	v_fma_f32 v69, -v231, v15, v69
	ds_read_b128 v[228:231], v2 offset:4656
	s_waitcnt lgkmcnt(11)
	v_fma_f32 v74, -v232, v16, v74
	v_fma_f32 v75, -v233, v17, v75
	ds_read_b128 v[232:235], v2 offset:4672
	v_add_f32_e32 v74, v74, v75
	v_add_f32_e32 v0, v0, v69
	v_add_f32_e32 v18, v74, v0
	s_waitcnt lgkmcnt(11)
	v_fma_f32 v74, -v236, v4, v19
	v_fma_f32 v75, -v237, v5, 0
	v_fma_f32 v0, -v238, v6, 0
	v_fma_f32 v69, -v239, v7, 0
	ds_read_b128 v[236:239], v2 offset:4688
	s_waitcnt lgkmcnt(11)
	v_fma_f32 v74, -v240, v8, v74
	v_fma_f32 v75, -v241, v9, v75
	v_fma_f32 v0, -v242, v10, v0
	v_fma_f32 v69, -v243, v11, v69
	ds_read_b128 v[240:243], v2 offset:4896
	s_waitcnt lgkmcnt(11)
	v_fma_f32 v74, -v180, v12, v74
	v_fma_f32 v75, -v181, v13, v75
	v_fma_f32 v0, -v182, v14, v0
	v_fma_f32 v69, -v183, v15, v69
	ds_read_b128 v[180:183], v2 offset:4912
	s_waitcnt lgkmcnt(11)
	v_fma_f32 v74, -v70, v16, v74
	v_fma_f32 v75, -v71, v17, v75
	v_fma_f32 v0, -v72, v18, v0
	ds_read_b128 v[70:73], v2 offset:4928
	v_add_f32_e32 v74, v74, v75
	v_add_f32_e32 v0, v0, v69
	v_add_f32_e32 v19, v74, v0
	s_waitcnt lgkmcnt(11)
	v_fma_f32 v74, -v204, v4, v20
	v_fma_f32 v75, -v205, v5, 0
	v_fma_f32 v0, -v206, v6, 0
	v_fma_f32 v69, -v207, v7, 0
	ds_read_b128 v[204:207], v2 offset:4944
	s_waitcnt lgkmcnt(11)
	v_fma_f32 v74, -v208, v8, v74
	v_fma_f32 v75, -v209, v9, v75
	v_fma_f32 v0, -v210, v10, v0
	v_fma_f32 v69, -v211, v11, v69
	ds_read_b128 v[208:211], v2 offset:4960
	s_waitcnt lgkmcnt(11)
	v_fma_f32 v74, -v212, v12, v74
	v_fma_f32 v75, -v213, v13, v75
	v_fma_f32 v0, -v214, v14, v0
	v_fma_f32 v69, -v215, v15, v69
	ds_read_b128 v[212:215], v2 offset:5168
	s_waitcnt lgkmcnt(11)
; #define LAS __attribute__((address_space(3)))
; __device__ __forceinline__ void gdn_prep_unit(const Args& c, int ug, int l, LAS unsigned char* lds) {
;     ...
;         for (int i = 1; i < 64; ++i) {
;             float s0 = x[i], s1 = 0.f, s2 = 0.f, s3 = 0.f;
; #pragma unroll
;             for (int m4 = 0; m4 < i; m4 += 4) {
;                 const f32x4 mv = *(const LAS f32x4*)(Mz + i * 68 + m4);
;                 s0 -= mv.x * x[m4];
;                 if (m4 + 1 < i) s1 -= mv.y * x[m4 + 1];
;                 if (m4 + 2 < i) s2 -= mv.z * x[m4 + 2];
;                 if (m4 + 3 < i) s3 -= mv.w * x[m4 + 3];
;             }
;             const float s = (s0 + s1) + (s2 + s3);
;             x[i] = s;
	v_fma_f32 v74, -v216, v16, v74
	v_fma_f32 v75, -v217, v17, v75
	v_fma_f32 v0, -v218, v18, v0
	v_fma_f32 v69, -v219, v19, v69
	ds_read_b128 v[216:219], v2 offset:5184
	v_add_f32_e32 v74, v74, v75
	v_add_f32_e32 v0, v0, v69
	v_add_f32_e32 v20, v74, v0
	s_waitcnt lgkmcnt(11)
	v_fma_f32 v74, -v220, v4, v21
	v_fma_f32 v75, -v221, v5, 0
	v_fma_f32 v0, -v222, v6, 0
	v_fma_f32 v69, -v223, v7, 0
	ds_read_b128 v[220:223], v2 offset:5200
	s_waitcnt lgkmcnt(11)
	v_fma_f32 v74, -v224, v8, v74
	v_fma_f32 v75, -v225, v9, v75
	v_fma_f32 v0, -v226, v10, v0
	v_fma_f32 v69, -v227, v11, v69
	ds_read_b128 v[224:227], v2 offset:5216
	s_waitcnt lgkmcnt(11)
	v_fma_f32 v74, -v228, v12, v74
	v_fma_f32 v75, -v229, v13, v75
	v_fma_f32 v0, -v230, v14, v0
	v_fma_f32 v69, -v231, v15, v69
	ds_read_b128 v[228:231], v2 offset:5232
	s_waitcnt lgkmcnt(11)
	v_fma_f32 v74, -v232, v16, v74
	v_fma_f32 v75, -v233, v17, v75
	v_fma_f32 v0, -v234, v18, v0
	v_fma_f32 v69, -v235, v19, v69
	ds_read_b128 v[232:235], v2 offset:5440
	s_waitcnt lgkmcnt(11)
	v_fma_f32 v74, -v236, v20, v74
	ds_read_b128 v[236:239], v2 offset:5456
	v_add_f32_e32 v74, v74, v75
	v_add_f32_e32 v0, v0, v69
	v_add_f32_e32 v21, v74, v0
	s_waitcnt lgkmcnt(11)
	v_fma_f32 v74, -v240, v4, v22
	v_fma_f32 v75, -v241, v5, 0
	v_fma_f32 v0, -v242, v6, 0
	v_fma_f32 v69, -v243, v7, 0
	ds_read_b128 v[240:243], v2 offset:5472
	s_waitcnt lgkmcnt(11)
	v_fma_f32 v74, -v180, v8, v74
	v_fma_f32 v75, -v181, v9, v75
	v_fma_f32 v0, -v182, v10, v0
	v_fma_f32 v69, -v183, v11, v69
	ds_read_b128 v[180:183], v2 offset:5488
	s_waitcnt lgkmcnt(11)
	v_fma_f32 v74, -v70, v12, v74
	v_fma_f32 v75, -v71, v13, v75
	v_fma_f32 v0, -v72, v14, v0
	v_fma_f32 v69, -v73, v15, v69
	ds_read_b128 v[70:73], v2 offset:5504
	s_waitcnt lgkmcnt(11)
	v_fma_f32 v74, -v204, v16, v74
	v_fma_f32 v75, -v205, v17, v75
	v_fma_f32 v0, -v206, v18, v0
	v_fma_f32 v69, -v207, v19, v69
	ds_read_b128 v[204:207], v2 offset:5712
	s_waitcnt lgkmcnt(11)
	v_fma_f32 v74, -v208, v20, v74
	v_fma_f32 v75, -v209, v21, v75
	ds_read_b128 v[208:211], v2 offset:5728
	v_add_f32_e32 v74, v74, v75
	v_add_f32_e32 v0, v0, v69
	v_add_f32_e32 v22, v74, v0
	s_waitcnt lgkmcnt(11)
	v_fma_f32 v74, -v212, v4, v23
	v_fma_f32 v75, -v213, v5, 0
	v_fma_f32 v0, -v214, v6, 0
	v_fma_f32 v69, -v215, v7, 0
	ds_read_b128 v[212:215], v2 offset:5744
	s_waitcnt lgkmcnt(11)
	v_fma_f32 v74, -v216, v8, v74
	v_fma_f32 v75, -v217, v9, v75
	v_fma_f32 v0, -v218, v10, v0
	v_fma_f32 v69, -v219, v11, v69
	ds_read_b128 v[216:219], v2 offset:5760
	s_waitcnt lgkmcnt(11)
	v_fma_f32 v74, -v220, v12, v74
	v_fma_f32 v75, -v221, v13, v75
	v_fma_f32 v0, -v222, v14, v0
	v_fma_f32 v69, -v223, v15, v69
	ds_read_b128 v[220:223], v2 offset:5776
	s_waitcnt lgkmcnt(11)
	v_fma_f32 v74, -v224, v16, v74
	v_fma_f32 v75, -v225, v17, v75
	v_fma_f32 v0, -v226, v18, v0
	v_fma_f32 v69, -v227, v19, v69
	ds_read_b128 v[224:227], v2 offset:5792
	s_waitcnt lgkmcnt(11)
	v_fma_f32 v74, -v228, v20, v74
	v_fma_f32 v75, -v229, v21, v75
	v_fma_f32 v0, -v230, v22, v0
	ds_read_b128 v[228:231], v2 offset:5984
	v_add_f32_e32 v74, v74, v75
	v_add_f32_e32 v0, v0, v69
	v_add_f32_e32 v23, v74, v0
	s_waitcnt lgkmcnt(11)
	v_fma_f32 v74, -v232, v4, v24
	v_fma_f32 v75, -v233, v5, 0
	v_fma_f32 v0, -v234, v6, 0
	v_fma_f32 v69, -v235, v7, 0
	ds_read_b128 v[232:235], v2 offset:6000
	s_waitcnt lgkmcnt(11)
	v_fma_f32 v74, -v236, v8, v74
	v_fma_f32 v75, -v237, v9, v75
	v_fma_f32 v0, -v238, v10, v0
	v_fma_f32 v69, -v239, v11, v69
	ds_read_b128 v[236:239], v2 offset:6016
	s_waitcnt lgkmcnt(11)
	v_fma_f32 v74, -v240, v12, v74
	v_fma_f32 v75, -v241, v13, v75
	v_fma_f32 v0, -v242, v14, v0
	v_fma_f32 v69, -v243, v15, v69
	ds_read_b128 v[240:243], v2 offset:6032
	s_waitcnt lgkmcnt(11)
	v_fma_f32 v74, -v180, v16, v74
	v_fma_f32 v75, -v181, v17, v75
	v_fma_f32 v0, -v182, v18, v0
	v_fma_f32 v69, -v183, v19, v69
	ds_read_b128 v[180:183], v2 offset:6048
	s_waitcnt lgkmcnt(11)
	v_fma_f32 v74, -v70, v20, v74
	v_fma_f32 v75, -v71, v21, v75
	v_fma_f32 v0, -v72, v22, v0
	v_fma_f32 v69, -v73, v23, v69
	ds_read_b128 v[70:73], v2 offset:6064
	v_add_f32_e32 v74, v74, v75
	v_add_f32_e32 v0, v0, v69
	v_add_f32_e32 v24, v74, v0
	s_waitcnt lgkmcnt(11)
	v_fma_f32 v74, -v204, v4, v25
	v_fma_f32 v75, -v205, v5, 0
	v_fma_f32 v0, -v206, v6, 0
	v_fma_f32 v69, -v207, v7, 0
	ds_read_b128 v[204:207], v2 offset:6256
	s_waitcnt lgkmcnt(11)
	v_fma_f32 v74, -v208, v8, v74
	v_fma_f32 v75, -v209, v9, v75
	v_fma_f32 v0, -v210, v10, v0
	v_fma_f32 v69, -v211, v11, v69
	ds_read_b128 v[208:211], v2 offset:6272
	s_waitcnt lgkmcnt(11)
	v_fma_f32 v74, -v212, v12, v74
	v_fma_f32 v75, -v213, v13, v75
	v_fma_f32 v0, -v214, v14, v0
	v_fma_f32 v69, -v215, v15, v69
	ds_read_b128 v[212:215], v2 offset:6288
	s_waitcnt lgkmcnt(11)
	v_fma_f32 v74, -v216, v16, v74
	v_fma_f32 v75, -v217, v17, v75
	v_fma_f32 v0, -v218, v18, v0
	v_fma_f32 v69, -v219, v19, v69
	ds_read_b128 v[216:219], v2 offset:6304
	s_waitcnt lgkmcnt(11)
	v_fma_f32 v74, -v220, v20, v74
	v_fma_f32 v75, -v221, v21, v75
	v_fma_f32 v0, -v222, v22, v0
	v_fma_f32 v69, -v223, v23, v69
	ds_read_b128 v[220:223], v2 offset:6320
	s_waitcnt lgkmcnt(11)
	v_fma_f32 v74, -v224, v24, v74
	ds_read_b128 v[224:227], v2 offset:6336
	v_add_f32_e32 v74, v74, v75
	v_add_f32_e32 v0, v0, v69
	v_add_f32_e32 v25, v74, v0
	s_waitcnt lgkmcnt(11)
	v_fma_f32 v74, -v228, v4, v26
	v_fma_f32 v75, -v229, v5, 0
	v_fma_f32 v0, -v230, v6, 0
	v_fma_f32 v69, -v231, v7, 0
	ds_read_b128 v[228:231], v2 offset:6528
	s_waitcnt lgkmcnt(11)
	v_fma_f32 v74, -v232, v8, v74
	v_fma_f32 v75, -v233, v9, v75
	v_fma_f32 v0, -v234, v10, v0
	v_fma_f32 v69, -v235, v11, v69
	ds_read_b128 v[232:235], v2 offset:6544
	s_waitcnt lgkmcnt(11)
; #define LAS __attribute__((address_space(3)))
; __device__ __forceinline__ void gdn_prep_unit(const Args& c, int ug, int l, LAS unsigned char* lds) {
;     ...
;         for (int i = 1; i < 64; ++i) {
;             float s0 = x[i], s1 = 0.f, s2 = 0.f, s3 = 0.f;
; #pragma unroll
;             for (int m4 = 0; m4 < i; m4 += 4) {
;                 const f32x4 mv = *(const LAS f32x4*)(Mz + i * 68 + m4);
;                 s0 -= mv.x * x[m4];
;                 if (m4 + 1 < i) s1 -= mv.y * x[m4 + 1];
;                 if (m4 + 2 < i) s2 -= mv.z * x[m4 + 2];
;                 if (m4 + 3 < i) s3 -= mv.w * x[m4 + 3];
;             }
;             const float s = (s0 + s1) + (s2 + s3);
;             x[i] = s;
	v_fma_f32 v74, -v236, v12, v74
	v_fma_f32 v75, -v237, v13, v75
	v_fma_f32 v0, -v238, v14, v0
	v_fma_f32 v69, -v239, v15, v69
	ds_read_b128 v[236:239], v2 offset:6560
	s_waitcnt lgkmcnt(11)
	v_fma_f32 v74, -v240, v16, v74
	v_fma_f32 v75, -v241, v17, v75
	v_fma_f32 v0, -v242, v18, v0
	v_fma_f32 v69, -v243, v19, v69
	ds_read_b128 v[240:243], v2 offset:6576
	s_waitcnt lgkmcnt(11)
	v_fma_f32 v74, -v180, v20, v74
	v_fma_f32 v75, -v181, v21, v75
	v_fma_f32 v0, -v182, v22, v0
	v_fma_f32 v69, -v183, v23, v69
	ds_read_b128 v[180:183], v2 offset:6592
	s_waitcnt lgkmcnt(11)
	v_fma_f32 v74, -v70, v24, v74
	v_fma_f32 v75, -v71, v25, v75
	ds_read_b128 v[70:73], v2 offset:6608
	v_add_f32_e32 v74, v74, v75
	v_add_f32_e32 v0, v0, v69
	v_add_f32_e32 v26, v74, v0
	s_waitcnt lgkmcnt(11)
	v_fma_f32 v74, -v204, v4, v27
	v_fma_f32 v75, -v205, v5, 0
	v_fma_f32 v0, -v206, v6, 0
	v_fma_f32 v69, -v207, v7, 0
	ds_read_b128 v[204:207], v2 offset:6800
	s_waitcnt lgkmcnt(11)
	v_fma_f32 v74, -v208, v8, v74
	v_fma_f32 v75, -v209, v9, v75
	v_fma_f32 v0, -v210, v10, v0
	v_fma_f32 v69, -v211, v11, v69
	ds_read_b128 v[208:211], v2 offset:6816
	s_waitcnt lgkmcnt(11)
	v_fma_f32 v74, -v212, v12, v74
	v_fma_f32 v75, -v213, v13, v75
	v_fma_f32 v0, -v214, v14, v0
	v_fma_f32 v69, -v215, v15, v69
	ds_read_b128 v[212:215], v2 offset:6832
	s_waitcnt lgkmcnt(11)
	v_fma_f32 v74, -v216, v16, v74
	v_fma_f32 v75, -v217, v17, v75
	v_fma_f32 v0, -v218, v18, v0
	v_fma_f32 v69, -v219, v19, v69
	ds_read_b128 v[216:219], v2 offset:6848
	s_waitcnt lgkmcnt(11)
	v_fma_f32 v74, -v220, v20, v74
	v_fma_f32 v75, -v221, v21, v75
	v_fma_f32 v0, -v222, v22, v0
	v_fma_f32 v69, -v223, v23, v69
	ds_read_b128 v[220:223], v2 offset:6864
	s_waitcnt lgkmcnt(11)
	v_fma_f32 v74, -v224, v24, v74
	v_fma_f32 v75, -v225, v25, v75
	v_fma_f32 v0, -v226, v26, v0
	ds_read_b128 v[224:227], v2 offset:6880
	v_add_f32_e32 v74, v74, v75
	v_add_f32_e32 v0, v0, v69
	v_add_f32_e32 v27, v74, v0
	s_waitcnt lgkmcnt(11)
	v_fma_f32 v74, -v228, v4, v28
	v_fma_f32 v75, -v229, v5, 0
	v_fma_f32 v0, -v230, v6, 0
	v_fma_f32 v69, -v231, v7, 0
	ds_read_b128 v[228:231], v2 offset:6896
	s_waitcnt lgkmcnt(11)
	v_fma_f32 v74, -v232, v8, v74
	v_fma_f32 v75, -v233, v9, v75
	v_fma_f32 v0, -v234, v10, v0
	v_fma_f32 v69, -v235, v11, v69
	ds_read_b128 v[232:235], v2 offset:7072
	s_waitcnt lgkmcnt(11)
	v_fma_f32 v74, -v236, v12, v74
	v_fma_f32 v75, -v237, v13, v75
	v_fma_f32 v0, -v238, v14, v0
	v_fma_f32 v69, -v239, v15, v69
	ds_read_b128 v[236:239], v2 offset:7088
	s_waitcnt lgkmcnt(11)
	v_fma_f32 v74, -v240, v16, v74
	v_fma_f32 v75, -v241, v17, v75
	v_fma_f32 v0, -v242, v18, v0
	v_fma_f32 v69, -v243, v19, v69
	ds_read_b128 v[240:243], v2 offset:7104
	s_waitcnt lgkmcnt(11)
	v_fma_f32 v74, -v180, v20, v74
	v_fma_f32 v75, -v181, v21, v75
	v_fma_f32 v0, -v182, v22, v0
	v_fma_f32 v69, -v183, v23, v69
	ds_read_b128 v[180:183], v2 offset:7120
	s_waitcnt lgkmcnt(11)
	v_fma_f32 v74, -v70, v24, v74
	v_fma_f32 v75, -v71, v25, v75
	v_fma_f32 v0, -v72, v26, v0
	v_fma_f32 v69, -v73, v27, v69
	ds_read_b128 v[70:73], v2 offset:7136
	v_add_f32_e32 v74, v74, v75
	v_add_f32_e32 v0, v0, v69
	v_add_f32_e32 v28, v74, v0
	s_waitcnt lgkmcnt(11)
	v_fma_f32 v74, -v204, v4, v29
	v_fma_f32 v75, -v205, v5, 0
	v_fma_f32 v0, -v206, v6, 0
	v_fma_f32 v69, -v207, v7, 0
	ds_read_b128 v[204:207], v2 offset:7152
	s_waitcnt lgkmcnt(11)
	v_fma_f32 v74, -v208, v8, v74
	v_fma_f32 v75, -v209, v9, v75
	v_fma_f32 v0, -v210, v10, v0
	v_fma_f32 v69, -v211, v11, v69
	ds_read_b128 v[208:211], v2 offset:7168
	s_waitcnt lgkmcnt(11)
	v_fma_f32 v74, -v212, v12, v74
	v_fma_f32 v75, -v213, v13, v75
	v_fma_f32 v0, -v214, v14, v0
	v_fma_f32 v69, -v215, v15, v69
	ds_read_b128 v[212:215], v2 offset:7344
	s_waitcnt lgkmcnt(11)
	v_fma_f32 v74, -v216, v16, v74
	v_fma_f32 v75, -v217, v17, v75
	v_fma_f32 v0, -v218, v18, v0
	v_fma_f32 v69, -v219, v19, v69
	ds_read_b128 v[216:219], v2 offset:7360
	s_waitcnt lgkmcnt(11)
	v_fma_f32 v74, -v220, v20, v74
	v_fma_f32 v75, -v221, v21, v75
	v_fma_f32 v0, -v222, v22, v0
	v_fma_f32 v69, -v223, v23, v69
	ds_read_b128 v[220:223], v2 offset:7376
	s_waitcnt lgkmcnt(11)
	v_fma_f32 v74, -v224, v24, v74
	v_fma_f32 v75, -v225, v25, v75
	v_fma_f32 v0, -v226, v26, v0
	v_fma_f32 v69, -v227, v27, v69
	ds_read_b128 v[224:227], v2 offset:7392
	s_waitcnt lgkmcnt(11)
	v_fma_f32 v74, -v228, v28, v74
	ds_read_b128 v[228:231], v2 offset:7408
	v_add_f32_e32 v74, v74, v75
	v_add_f32_e32 v0, v0, v69
	v_add_f32_e32 v29, v74, v0
	s_waitcnt lgkmcnt(11)
	v_fma_f32 v74, -v232, v4, v30
	v_fma_f32 v75, -v233, v5, 0
	v_fma_f32 v0, -v234, v6, 0
	v_fma_f32 v69, -v235, v7, 0
	ds_read_b128 v[232:235], v2 offset:7424
	s_waitcnt lgkmcnt(11)
	v_fma_f32 v74, -v236, v8, v74
	v_fma_f32 v75, -v237, v9, v75
	v_fma_f32 v0, -v238, v10, v0
	v_fma_f32 v69, -v239, v11, v69
	ds_read_b128 v[236:239], v2 offset:7440
	s_waitcnt lgkmcnt(11)
	v_fma_f32 v74, -v240, v12, v74
	v_fma_f32 v75, -v241, v13, v75
	v_fma_f32 v0, -v242, v14, v0
	v_fma_f32 v69, -v243, v15, v69
	ds_read_b128 v[240:243], v2 offset:7616
	s_waitcnt lgkmcnt(11)
	v_fma_f32 v74, -v180, v16, v74
	v_fma_f32 v75, -v181, v17, v75
	v_fma_f32 v0, -v182, v18, v0
	v_fma_f32 v69, -v183, v19, v69
	ds_read_b128 v[180:183], v2 offset:7632
	s_waitcnt lgkmcnt(11)
	v_fma_f32 v74, -v70, v20, v74
	v_fma_f32 v75, -v71, v21, v75
	v_fma_f32 v0, -v72, v22, v0
	v_fma_f32 v69, -v73, v23, v69
	ds_read_b128 v[70:73], v2 offset:7648
	s_waitcnt lgkmcnt(11)
	v_fma_f32 v74, -v204, v24, v74
	v_fma_f32 v75, -v205, v25, v75
	v_fma_f32 v0, -v206, v26, v0
	v_fma_f32 v69, -v207, v27, v69
	ds_read_b128 v[204:207], v2 offset:7664
	s_waitcnt lgkmcnt(11)
; #define LAS __attribute__((address_space(3)))
; __device__ __forceinline__ void gdn_prep_unit(const Args& c, int ug, int l, LAS unsigned char* lds) {
;     ...
;         for (int i = 1; i < 64; ++i) {
;             float s0 = x[i], s1 = 0.f, s2 = 0.f, s3 = 0.f;
; #pragma unroll
;             for (int m4 = 0; m4 < i; m4 += 4) {
;                 const f32x4 mv = *(const LAS f32x4*)(Mz + i * 68 + m4);
;                 s0 -= mv.x * x[m4];
;                 if (m4 + 1 < i) s1 -= mv.y * x[m4 + 1];
;                 if (m4 + 2 < i) s2 -= mv.z * x[m4 + 2];
;                 if (m4 + 3 < i) s3 -= mv.w * x[m4 + 3];
;             }
;             const float s = (s0 + s1) + (s2 + s3);
;             x[i] = s;
	v_fma_f32 v74, -v208, v28, v74
	v_fma_f32 v75, -v209, v29, v75
	ds_read_b128 v[208:211], v2 offset:7680
	v_add_f32_e32 v74, v74, v75
	v_add_f32_e32 v0, v0, v69
	v_add_f32_e32 v30, v74, v0
	s_waitcnt lgkmcnt(11)
	v_fma_f32 v74, -v212, v4, v31
	v_fma_f32 v75, -v213, v5, 0
	v_fma_f32 v0, -v214, v6, 0
	v_fma_f32 v69, -v215, v7, 0
	ds_read_b128 v[212:215], v2 offset:7696
	s_waitcnt lgkmcnt(11)
	v_fma_f32 v74, -v216, v8, v74
	v_fma_f32 v75, -v217, v9, v75
	v_fma_f32 v0, -v218, v10, v0
	v_fma_f32 v69, -v219, v11, v69
	ds_read_b128 v[216:219], v2 offset:7712
	s_waitcnt lgkmcnt(11)
	v_fma_f32 v74, -v220, v12, v74
	v_fma_f32 v75, -v221, v13, v75
	v_fma_f32 v0, -v222, v14, v0
	v_fma_f32 v69, -v223, v15, v69
	ds_read_b128 v[220:223], v2 offset:7888
	s_waitcnt lgkmcnt(11)
	v_fma_f32 v74, -v224, v16, v74
	v_fma_f32 v75, -v225, v17, v75
	v_fma_f32 v0, -v226, v18, v0
	v_fma_f32 v69, -v227, v19, v69
	ds_read_b128 v[224:227], v2 offset:7904
	s_waitcnt lgkmcnt(11)
	v_fma_f32 v74, -v228, v20, v74
	v_fma_f32 v75, -v229, v21, v75
	v_fma_f32 v0, -v230, v22, v0
	v_fma_f32 v69, -v231, v23, v69
	ds_read_b128 v[228:231], v2 offset:7920
	s_waitcnt lgkmcnt(11)
	v_fma_f32 v74, -v232, v24, v74
	v_fma_f32 v75, -v233, v25, v75
	v_fma_f32 v0, -v234, v26, v0
	v_fma_f32 v69, -v235, v27, v69
	ds_read_b128 v[232:235], v2 offset:7936
	s_waitcnt lgkmcnt(11)
	v_fma_f32 v74, -v236, v28, v74
	v_fma_f32 v75, -v237, v29, v75
	v_fma_f32 v0, -v238, v30, v0
	ds_read_b128 v[236:239], v2 offset:7952
	v_add_f32_e32 v74, v74, v75
	v_add_f32_e32 v0, v0, v69
	v_add_f32_e32 v31, v74, v0
	s_waitcnt lgkmcnt(11)
	v_fma_f32 v74, -v240, v4, v32
	v_fma_f32 v75, -v241, v5, 0
	v_fma_f32 v0, -v242, v6, 0
	v_fma_f32 v69, -v243, v7, 0
	ds_read_b128 v[240:243], v2 offset:7968
	s_waitcnt lgkmcnt(11)
	v_fma_f32 v74, -v180, v8, v74
	v_fma_f32 v75, -v181, v9, v75
	v_fma_f32 v0, -v182, v10, v0
	v_fma_f32 v69, -v183, v11, v69
	ds_read_b128 v[180:183], v2 offset:7984
	s_waitcnt lgkmcnt(11)
	v_fma_f32 v74, -v70, v12, v74
	v_fma_f32 v75, -v71, v13, v75
	v_fma_f32 v0, -v72, v14, v0
	v_fma_f32 v69, -v73, v15, v69
	ds_read_b128 v[70:73], v2 offset:8000
	s_waitcnt lgkmcnt(11)
	v_fma_f32 v74, -v204, v16, v74
	v_fma_f32 v75, -v205, v17, v75
	v_fma_f32 v0, -v206, v18, v0
	v_fma_f32 v69, -v207, v19, v69
	ds_read_b128 v[204:207], v2 offset:8160
	s_waitcnt lgkmcnt(11)
	v_fma_f32 v74, -v208, v20, v74
	v_fma_f32 v75, -v209, v21, v75
	v_fma_f32 v0, -v210, v22, v0
	v_fma_f32 v69, -v211, v23, v69
	ds_read_b128 v[208:211], v2 offset:8176
	s_waitcnt lgkmcnt(11)
	v_fma_f32 v74, -v212, v24, v74
	v_fma_f32 v75, -v213, v25, v75
	v_fma_f32 v0, -v214, v26, v0
	v_fma_f32 v69, -v215, v27, v69
	ds_read_b128 v[212:215], v2 offset:8192
	s_waitcnt lgkmcnt(11)
	v_fma_f32 v74, -v216, v28, v74
	v_fma_f32 v75, -v217, v29, v75
	v_fma_f32 v0, -v218, v30, v0
	v_fma_f32 v69, -v219, v31, v69
	ds_read_b128 v[216:219], v2 offset:8208
	v_add_f32_e32 v74, v74, v75
	v_add_f32_e32 v0, v0, v69
	v_add_f32_e32 v32, v74, v0
	s_waitcnt lgkmcnt(11)
	v_fma_f32 v74, -v220, v4, v33
	v_fma_f32 v75, -v221, v5, 0
	v_fma_f32 v0, -v222, v6, 0
	v_fma_f32 v69, -v223, v7, 0
	ds_read_b128 v[220:223], v2 offset:8224
	s_waitcnt lgkmcnt(11)
	v_fma_f32 v74, -v224, v8, v74
	v_fma_f32 v75, -v225, v9, v75
	v_fma_f32 v0, -v226, v10, v0
	v_fma_f32 v69, -v227, v11, v69
	ds_read_b128 v[224:227], v2 offset:8240
	s_waitcnt lgkmcnt(11)
	v_fma_f32 v74, -v228, v12, v74
	v_fma_f32 v75, -v229, v13, v75
	v_fma_f32 v0, -v230, v14, v0
	v_fma_f32 v69, -v231, v15, v69
	ds_read_b128 v[228:231], v2 offset:8256
	s_waitcnt lgkmcnt(11)
	v_fma_f32 v74, -v232, v16, v74
	v_fma_f32 v75, -v233, v17, v75
	v_fma_f32 v0, -v234, v18, v0
	v_fma_f32 v69, -v235, v19, v69
	ds_read_b128 v[232:235], v2 offset:8272
	s_waitcnt lgkmcnt(11)
	v_fma_f32 v74, -v236, v20, v74
	v_fma_f32 v75, -v237, v21, v75
	v_fma_f32 v0, -v238, v22, v0
	v_fma_f32 v69, -v239, v23, v69
	ds_read_b128 v[236:239], v2 offset:8432
	s_waitcnt lgkmcnt(11)
	v_fma_f32 v74, -v240, v24, v74
	v_fma_f32 v75, -v241, v25, v75
	v_fma_f32 v0, -v242, v26, v0
	v_fma_f32 v69, -v243, v27, v69
	ds_read_b128 v[240:243], v2 offset:8448
	s_waitcnt lgkmcnt(11)
	v_fma_f32 v74, -v180, v28, v74
	v_fma_f32 v75, -v181, v29, v75
	v_fma_f32 v0, -v182, v30, v0
	v_fma_f32 v69, -v183, v31, v69
	ds_read_b128 v[180:183], v2 offset:8464
	s_waitcnt lgkmcnt(11)
	v_fma_f32 v74, -v70, v32, v74
	ds_read_b128 v[70:73], v2 offset:8480
	v_add_f32_e32 v74, v74, v75
	v_add_f32_e32 v0, v0, v69
	v_add_f32_e32 v33, v74, v0
	s_waitcnt lgkmcnt(11)
	v_fma_f32 v74, -v204, v4, v34
	v_fma_f32 v75, -v205, v5, 0
	v_fma_f32 v0, -v206, v6, 0
	v_fma_f32 v69, -v207, v7, 0
	ds_read_b128 v[204:207], v2 offset:8496
	s_waitcnt lgkmcnt(11)
	v_fma_f32 v74, -v208, v8, v74
	v_fma_f32 v75, -v209, v9, v75
	v_fma_f32 v0, -v210, v10, v0
	v_fma_f32 v69, -v211, v11, v69
	ds_read_b128 v[208:211], v2 offset:8512
	s_waitcnt lgkmcnt(11)
	v_fma_f32 v74, -v212, v12, v74
	v_fma_f32 v75, -v213, v13, v75
	v_fma_f32 v0, -v214, v14, v0
	v_fma_f32 v69, -v215, v15, v69
	ds_read_b128 v[212:215], v2 offset:8528
	s_waitcnt lgkmcnt(11)
	v_fma_f32 v74, -v216, v16, v74
	v_fma_f32 v75, -v217, v17, v75
	v_fma_f32 v0, -v218, v18, v0
	v_fma_f32 v69, -v219, v19, v69
	ds_read_b128 v[216:219], v2 offset:8544
	s_waitcnt lgkmcnt(11)
	v_fma_f32 v74, -v220, v20, v74
	v_fma_f32 v75, -v221, v21, v75
	v_fma_f32 v0, -v222, v22, v0
	v_fma_f32 v69, -v223, v23, v69
	ds_read_b128 v[220:223], v2 offset:8704
	s_waitcnt lgkmcnt(11)
	v_fma_f32 v74, -v224, v24, v74
	v_fma_f32 v75, -v225, v25, v75
	v_fma_f32 v0, -v226, v26, v0
	v_fma_f32 v69, -v227, v27, v69
	ds_read_b128 v[224:227], v2 offset:8720
	s_waitcnt lgkmcnt(11)
; #define LAS __attribute__((address_space(3)))
; __device__ __forceinline__ void gdn_prep_unit(const Args& c, int ug, int l, LAS unsigned char* lds) {
;     ...
;         for (int i = 1; i < 64; ++i) {
;             float s0 = x[i], s1 = 0.f, s2 = 0.f, s3 = 0.f;
; #pragma unroll
;             for (int m4 = 0; m4 < i; m4 += 4) {
;                 const f32x4 mv = *(const LAS f32x4*)(Mz + i * 68 + m4);
;                 s0 -= mv.x * x[m4];
;                 if (m4 + 1 < i) s1 -= mv.y * x[m4 + 1];
;                 if (m4 + 2 < i) s2 -= mv.z * x[m4 + 2];
;                 if (m4 + 3 < i) s3 -= mv.w * x[m4 + 3];
;             }
;             const float s = (s0 + s1) + (s2 + s3);
;             x[i] = s;
	v_fma_f32 v74, -v228, v28, v74
	v_fma_f32 v75, -v229, v29, v75
	v_fma_f32 v0, -v230, v30, v0
	v_fma_f32 v69, -v231, v31, v69
	ds_read_b128 v[228:231], v2 offset:8736
	s_waitcnt lgkmcnt(11)
	v_fma_f32 v74, -v232, v32, v74
	v_fma_f32 v75, -v233, v33, v75
	ds_read_b128 v[232:235], v2 offset:8752
	v_add_f32_e32 v74, v74, v75
	v_add_f32_e32 v0, v0, v69
	v_add_f32_e32 v34, v74, v0
	s_waitcnt lgkmcnt(11)
	v_fma_f32 v74, -v236, v4, v35
	v_fma_f32 v75, -v237, v5, 0
	v_fma_f32 v0, -v238, v6, 0
	v_fma_f32 v69, -v239, v7, 0
	ds_read_b128 v[236:239], v2 offset:8768
	s_waitcnt lgkmcnt(11)
	v_fma_f32 v74, -v240, v8, v74
	v_fma_f32 v75, -v241, v9, v75
	v_fma_f32 v0, -v242, v10, v0
	v_fma_f32 v69, -v243, v11, v69
	ds_read_b128 v[240:243], v2 offset:8784
	s_waitcnt lgkmcnt(11)
	v_fma_f32 v74, -v180, v12, v74
	v_fma_f32 v75, -v181, v13, v75
	v_fma_f32 v0, -v182, v14, v0
	v_fma_f32 v69, -v183, v15, v69
	ds_read_b128 v[180:183], v2 offset:8800
	s_waitcnt lgkmcnt(11)
	v_fma_f32 v74, -v70, v16, v74
	v_fma_f32 v75, -v71, v17, v75
	v_fma_f32 v0, -v72, v18, v0
	v_fma_f32 v69, -v73, v19, v69
	ds_read_b128 v[70:73], v2 offset:8816
	s_waitcnt lgkmcnt(11)
	v_fma_f32 v74, -v204, v20, v74
	v_fma_f32 v75, -v205, v21, v75
	v_fma_f32 v0, -v206, v22, v0
	v_fma_f32 v69, -v207, v23, v69
	ds_read_b128 v[204:207], v2 offset:8976
	s_waitcnt lgkmcnt(11)
	v_fma_f32 v74, -v208, v24, v74
	v_fma_f32 v75, -v209, v25, v75
	v_fma_f32 v0, -v210, v26, v0
	v_fma_f32 v69, -v211, v27, v69
	ds_read_b128 v[208:211], v2 offset:8992
	s_waitcnt lgkmcnt(11)
	v_fma_f32 v74, -v212, v28, v74
	v_fma_f32 v75, -v213, v29, v75
	v_fma_f32 v0, -v214, v30, v0
	v_fma_f32 v69, -v215, v31, v69
	ds_read_b128 v[212:215], v2 offset:9008
	s_waitcnt lgkmcnt(11)
	v_fma_f32 v74, -v216, v32, v74
	v_fma_f32 v75, -v217, v33, v75
	v_fma_f32 v0, -v218, v34, v0
	ds_read_b128 v[216:219], v2 offset:9024
	v_add_f32_e32 v74, v74, v75
	v_add_f32_e32 v0, v0, v69
	v_add_f32_e32 v35, v74, v0
	s_waitcnt lgkmcnt(11)
	v_fma_f32 v74, -v220, v4, v36
	v_fma_f32 v75, -v221, v5, 0
	v_fma_f32 v0, -v222, v6, 0
	v_fma_f32 v69, -v223, v7, 0
	ds_read_b128 v[220:223], v2 offset:9040
	s_waitcnt lgkmcnt(11)
	v_fma_f32 v74, -v224, v8, v74
	v_fma_f32 v75, -v225, v9, v75
	v_fma_f32 v0, -v226, v10, v0
	v_fma_f32 v69, -v227, v11, v69
	ds_read_b128 v[224:227], v2 offset:9056
	s_waitcnt lgkmcnt(11)
	v_fma_f32 v74, -v228, v12, v74
	v_fma_f32 v75, -v229, v13, v75
	v_fma_f32 v0, -v230, v14, v0
	v_fma_f32 v69, -v231, v15, v69
	ds_read_b128 v[228:231], v2 offset:9072
	s_waitcnt lgkmcnt(11)
	v_fma_f32 v74, -v232, v16, v74
	v_fma_f32 v75, -v233, v17, v75
	v_fma_f32 v0, -v234, v18, v0
	v_fma_f32 v69, -v235, v19, v69
	ds_read_b128 v[232:235], v2 offset:9088
	s_waitcnt lgkmcnt(11)
	v_fma_f32 v74, -v236, v20, v74
	v_fma_f32 v75, -v237, v21, v75
	v_fma_f32 v0, -v238, v22, v0
	v_fma_f32 v69, -v239, v23, v69
	ds_read_b128 v[236:239], v2 offset:9104
	s_waitcnt lgkmcnt(11)
	v_fma_f32 v74, -v240, v24, v74
	v_fma_f32 v75, -v241, v25, v75
	v_fma_f32 v0, -v242, v26, v0
	v_fma_f32 v69, -v243, v27, v69
	ds_read_b128 v[240:243], v2 offset:9248
	s_waitcnt lgkmcnt(11)
	v_fma_f32 v74, -v180, v28, v74
	v_fma_f32 v75, -v181, v29, v75
	v_fma_f32 v0, -v182, v30, v0
	v_fma_f32 v69, -v183, v31, v69
	ds_read_b128 v[180:183], v2 offset:9264
	s_waitcnt lgkmcnt(11)
	v_fma_f32 v74, -v70, v32, v74
	v_fma_f32 v75, -v71, v33, v75
	v_fma_f32 v0, -v72, v34, v0
	v_fma_f32 v69, -v73, v35, v69
	ds_read_b128 v[70:73], v2 offset:9280
	v_add_f32_e32 v74, v74, v75
	v_add_f32_e32 v0, v0, v69
	v_add_f32_e32 v36, v74, v0
	s_waitcnt lgkmcnt(11)
	v_fma_f32 v74, -v204, v4, v37
	v_fma_f32 v75, -v205, v5, 0
	v_fma_f32 v0, -v206, v6, 0
	v_fma_f32 v69, -v207, v7, 0
	ds_read_b128 v[204:207], v2 offset:9296
	s_waitcnt lgkmcnt(11)
	v_fma_f32 v74, -v208, v8, v74
	v_fma_f32 v75, -v209, v9, v75
	v_fma_f32 v0, -v210, v10, v0
	v_fma_f32 v69, -v211, v11, v69
	ds_read_b128 v[208:211], v2 offset:9312
	s_waitcnt lgkmcnt(11)
	v_fma_f32 v74, -v212, v12, v74
	v_fma_f32 v75, -v213, v13, v75
	v_fma_f32 v0, -v214, v14, v0
	v_fma_f32 v69, -v215, v15, v69
	ds_read_b128 v[212:215], v2 offset:9328
	s_waitcnt lgkmcnt(11)
	v_fma_f32 v74, -v216, v16, v74
	v_fma_f32 v75, -v217, v17, v75
	v_fma_f32 v0, -v218, v18, v0
	v_fma_f32 v69, -v219, v19, v69
	ds_read_b128 v[216:219], v2 offset:9344
	s_waitcnt lgkmcnt(11)
	v_fma_f32 v74, -v220, v20, v74
	v_fma_f32 v75, -v221, v21, v75
	v_fma_f32 v0, -v222, v22, v0
	v_fma_f32 v69, -v223, v23, v69
	ds_read_b128 v[220:223], v2 offset:9360
	s_waitcnt lgkmcnt(11)
	v_fma_f32 v74, -v224, v24, v74
	v_fma_f32 v75, -v225, v25, v75
	v_fma_f32 v0, -v226, v26, v0
	v_fma_f32 v69, -v227, v27, v69
	ds_read_b128 v[224:227], v2 offset:9376
	s_waitcnt lgkmcnt(11)
	v_fma_f32 v74, -v228, v28, v74
	v_fma_f32 v75, -v229, v29, v75
	v_fma_f32 v0, -v230, v30, v0
	v_fma_f32 v69, -v231, v31, v69
	ds_read_b128 v[228:231], v2 offset:9520
	s_waitcnt lgkmcnt(11)
	v_fma_f32 v74, -v232, v32, v74
	v_fma_f32 v75, -v233, v33, v75
	v_fma_f32 v0, -v234, v34, v0
	v_fma_f32 v69, -v235, v35, v69
	ds_read_b128 v[232:235], v2 offset:9536
	s_waitcnt lgkmcnt(11)
	v_fma_f32 v74, -v236, v36, v74
	ds_read_b128 v[236:239], v2 offset:9552
	v_add_f32_e32 v74, v74, v75
	v_add_f32_e32 v0, v0, v69
	v_add_f32_e32 v37, v74, v0
	s_waitcnt lgkmcnt(11)
	v_fma_f32 v74, -v240, v4, v38
	v_fma_f32 v75, -v241, v5, 0
	v_fma_f32 v0, -v242, v6, 0
	v_fma_f32 v69, -v243, v7, 0
	ds_read_b128 v[240:243], v2 offset:9568
	s_waitcnt lgkmcnt(11)
	v_fma_f32 v74, -v180, v8, v74
	v_fma_f32 v75, -v181, v9, v75
	v_fma_f32 v0, -v182, v10, v0
	v_fma_f32 v69, -v183, v11, v69
	ds_read_b128 v[180:183], v2 offset:9584
	s_waitcnt lgkmcnt(11)
; #define LAS __attribute__((address_space(3)))
; __device__ __forceinline__ void gdn_prep_unit(const Args& c, int ug, int l, LAS unsigned char* lds) {
;     ...
;         for (int i = 1; i < 64; ++i) {
;             float s0 = x[i], s1 = 0.f, s2 = 0.f, s3 = 0.f;
; #pragma unroll
;             for (int m4 = 0; m4 < i; m4 += 4) {
;                 const f32x4 mv = *(const LAS f32x4*)(Mz + i * 68 + m4);
;                 s0 -= mv.x * x[m4];
;                 if (m4 + 1 < i) s1 -= mv.y * x[m4 + 1];
;                 if (m4 + 2 < i) s2 -= mv.z * x[m4 + 2];
;                 if (m4 + 3 < i) s3 -= mv.w * x[m4 + 3];
;             }
;             const float s = (s0 + s1) + (s2 + s3);
;             x[i] = s;
	v_fma_f32 v74, -v70, v12, v74
	v_fma_f32 v75, -v71, v13, v75
	v_fma_f32 v0, -v72, v14, v0
	v_fma_f32 v69, -v73, v15, v69
	ds_read_b128 v[70:73], v2 offset:9600
	s_waitcnt lgkmcnt(11)
	v_fma_f32 v74, -v204, v16, v74
	v_fma_f32 v75, -v205, v17, v75
	v_fma_f32 v0, -v206, v18, v0
	v_fma_f32 v69, -v207, v19, v69
	ds_read_b128 v[204:207], v2 offset:9616
	s_waitcnt lgkmcnt(11)
	v_fma_f32 v74, -v208, v20, v74
	v_fma_f32 v75, -v209, v21, v75
	v_fma_f32 v0, -v210, v22, v0
	v_fma_f32 v69, -v211, v23, v69
	ds_read_b128 v[208:211], v2 offset:9632
	s_waitcnt lgkmcnt(11)
	v_fma_f32 v74, -v212, v24, v74
	v_fma_f32 v75, -v213, v25, v75
	v_fma_f32 v0, -v214, v26, v0
	v_fma_f32 v69, -v215, v27, v69
	ds_read_b128 v[212:215], v2 offset:9648
	s_waitcnt lgkmcnt(11)
	v_fma_f32 v74, -v216, v28, v74
	v_fma_f32 v75, -v217, v29, v75
	v_fma_f32 v0, -v218, v30, v0
	v_fma_f32 v69, -v219, v31, v69
	ds_read_b128 v[216:219], v2 offset:9792
	s_waitcnt lgkmcnt(11)
	v_fma_f32 v74, -v220, v32, v74
	v_fma_f32 v75, -v221, v33, v75
	v_fma_f32 v0, -v222, v34, v0
	v_fma_f32 v69, -v223, v35, v69
	ds_read_b128 v[220:223], v2 offset:9808
	s_waitcnt lgkmcnt(11)
	v_fma_f32 v74, -v224, v36, v74
	v_fma_f32 v75, -v225, v37, v75
	ds_read_b128 v[224:227], v2 offset:9824
	v_add_f32_e32 v74, v74, v75
	v_add_f32_e32 v0, v0, v69
	v_add_f32_e32 v38, v74, v0
	s_waitcnt lgkmcnt(11)
	v_fma_f32 v74, -v228, v4, v39
	v_fma_f32 v75, -v229, v5, 0
	v_fma_f32 v0, -v230, v6, 0
	v_fma_f32 v69, -v231, v7, 0
	ds_read_b128 v[228:231], v2 offset:9840
	s_waitcnt lgkmcnt(11)
	v_fma_f32 v74, -v232, v8, v74
	v_fma_f32 v75, -v233, v9, v75
	v_fma_f32 v0, -v234, v10, v0
	v_fma_f32 v69, -v235, v11, v69
	ds_read_b128 v[232:235], v2 offset:9856
	s_waitcnt lgkmcnt(11)
	v_fma_f32 v74, -v236, v12, v74
	v_fma_f32 v75, -v237, v13, v75
	v_fma_f32 v0, -v238, v14, v0
	v_fma_f32 v69, -v239, v15, v69
	ds_read_b128 v[236:239], v2 offset:9872
	s_waitcnt lgkmcnt(11)
	v_fma_f32 v74, -v240, v16, v74
	v_fma_f32 v75, -v241, v17, v75
	v_fma_f32 v0, -v242, v18, v0
	v_fma_f32 v69, -v243, v19, v69
	ds_read_b128 v[240:243], v2 offset:9888
	s_waitcnt lgkmcnt(11)
	v_fma_f32 v74, -v180, v20, v74
	v_fma_f32 v75, -v181, v21, v75
	v_fma_f32 v0, -v182, v22, v0
	v_fma_f32 v69, -v183, v23, v69
	ds_read_b128 v[180:183], v2 offset:9904
	s_waitcnt lgkmcnt(11)
	v_fma_f32 v74, -v70, v24, v74
	v_fma_f32 v75, -v71, v25, v75
	v_fma_f32 v0, -v72, v26, v0
	v_fma_f32 v69, -v73, v27, v69
	ds_read_b128 v[70:73], v2 offset:9920
	s_waitcnt lgkmcnt(11)
	v_fma_f32 v74, -v204, v28, v74
	v_fma_f32 v75, -v205, v29, v75
	v_fma_f32 v0, -v206, v30, v0
	v_fma_f32 v69, -v207, v31, v69
	ds_read_b128 v[204:207], v2 offset:10064
	s_waitcnt lgkmcnt(11)
	v_fma_f32 v74, -v208, v32, v74
	v_fma_f32 v75, -v209, v33, v75
	v_fma_f32 v0, -v210, v34, v0
	v_fma_f32 v69, -v211, v35, v69
	ds_read_b128 v[208:211], v2 offset:10080
	s_waitcnt lgkmcnt(11)
	v_fma_f32 v74, -v212, v36, v74
	v_fma_f32 v75, -v213, v37, v75
	v_fma_f32 v0, -v214, v38, v0
	ds_read_b128 v[212:215], v2 offset:10096
	v_add_f32_e32 v74, v74, v75
	v_add_f32_e32 v0, v0, v69
	v_add_f32_e32 v39, v74, v0
	s_waitcnt lgkmcnt(11)
	v_fma_f32 v74, -v216, v4, v40
	v_fma_f32 v75, -v217, v5, 0
	v_fma_f32 v0, -v218, v6, 0
	v_fma_f32 v69, -v219, v7, 0
	ds_read_b128 v[216:219], v2 offset:10112
	s_waitcnt lgkmcnt(11)
	v_fma_f32 v74, -v220, v8, v74
	v_fma_f32 v75, -v221, v9, v75
	v_fma_f32 v0, -v222, v10, v0
	v_fma_f32 v69, -v223, v11, v69
	ds_read_b128 v[220:223], v2 offset:10128
	s_waitcnt lgkmcnt(11)
	v_fma_f32 v74, -v224, v12, v74
	v_fma_f32 v75, -v225, v13, v75
	v_fma_f32 v0, -v226, v14, v0
	v_fma_f32 v69, -v227, v15, v69
	ds_read_b128 v[224:227], v2 offset:10144
	s_waitcnt lgkmcnt(11)
	v_fma_f32 v74, -v228, v16, v74
	v_fma_f32 v75, -v229, v17, v75
	v_fma_f32 v0, -v230, v18, v0
	v_fma_f32 v69, -v231, v19, v69
	ds_read_b128 v[228:231], v2 offset:10160
	s_waitcnt lgkmcnt(11)
	v_fma_f32 v74, -v232, v20, v74
	v_fma_f32 v75, -v233, v21, v75
	v_fma_f32 v0, -v234, v22, v0
	v_fma_f32 v69, -v235, v23, v69
	ds_read_b128 v[232:235], v2 offset:10176
	s_waitcnt lgkmcnt(11)
	v_fma_f32 v74, -v236, v24, v74
	v_fma_f32 v75, -v237, v25, v75
	v_fma_f32 v0, -v238, v26, v0
	v_fma_f32 v69, -v239, v27, v69
	ds_read_b128 v[236:239], v2 offset:10192
	s_waitcnt lgkmcnt(11)
	v_fma_f32 v74, -v240, v28, v74
	v_fma_f32 v75, -v241, v29, v75
	v_fma_f32 v0, -v242, v30, v0
	v_fma_f32 v69, -v243, v31, v69
	ds_read_b128 v[240:243], v2 offset:10208
	s_waitcnt lgkmcnt(11)
	v_fma_f32 v74, -v180, v32, v74
	v_fma_f32 v75, -v181, v33, v75
	v_fma_f32 v0, -v182, v34, v0
	v_fma_f32 v69, -v183, v35, v69
	ds_read_b128 v[180:183], v2 offset:10336
	s_waitcnt lgkmcnt(11)
	v_fma_f32 v74, -v70, v36, v74
	v_fma_f32 v75, -v71, v37, v75
	v_fma_f32 v0, -v72, v38, v0
	v_fma_f32 v69, -v73, v39, v69
	ds_read_b128 v[70:73], v2 offset:10352
	v_add_f32_e32 v74, v74, v75
	v_add_f32_e32 v0, v0, v69
	v_add_f32_e32 v40, v74, v0
	s_waitcnt lgkmcnt(11)
	v_fma_f32 v74, -v204, v4, v41
	v_fma_f32 v75, -v205, v5, 0
	v_fma_f32 v0, -v206, v6, 0
	v_fma_f32 v69, -v207, v7, 0
	ds_read_b128 v[204:207], v2 offset:10368
	s_waitcnt lgkmcnt(11)
	v_fma_f32 v74, -v208, v8, v74
	v_fma_f32 v75, -v209, v9, v75
	v_fma_f32 v0, -v210, v10, v0
	v_fma_f32 v69, -v211, v11, v69
	ds_read_b128 v[208:211], v2 offset:10384
	s_waitcnt lgkmcnt(11)
	v_fma_f32 v74, -v212, v12, v74
	v_fma_f32 v75, -v213, v13, v75
	v_fma_f32 v0, -v214, v14, v0
	v_fma_f32 v69, -v215, v15, v69
	ds_read_b128 v[212:215], v2 offset:10400
	s_waitcnt lgkmcnt(11)
	v_fma_f32 v74, -v216, v16, v74
	v_fma_f32 v75, -v217, v17, v75
	v_fma_f32 v0, -v218, v18, v0
	v_fma_f32 v69, -v219, v19, v69
	ds_read_b128 v[216:219], v2 offset:10416
	s_waitcnt lgkmcnt(11)
; #define LAS __attribute__((address_space(3)))
; __device__ __forceinline__ void gdn_prep_unit(const Args& c, int ug, int l, LAS unsigned char* lds) {
;     ...
;         for (int i = 1; i < 64; ++i) {
;             float s0 = x[i], s1 = 0.f, s2 = 0.f, s3 = 0.f;
; #pragma unroll
;             for (int m4 = 0; m4 < i; m4 += 4) {
;                 const f32x4 mv = *(const LAS f32x4*)(Mz + i * 68 + m4);
;                 s0 -= mv.x * x[m4];
;                 if (m4 + 1 < i) s1 -= mv.y * x[m4 + 1];
;                 if (m4 + 2 < i) s2 -= mv.z * x[m4 + 2];
;                 if (m4 + 3 < i) s3 -= mv.w * x[m4 + 3];
;             }
;             const float s = (s0 + s1) + (s2 + s3);
;             x[i] = s;
	v_fma_f32 v74, -v220, v20, v74
	v_fma_f32 v75, -v221, v21, v75
	v_fma_f32 v0, -v222, v22, v0
	v_fma_f32 v69, -v223, v23, v69
	ds_read_b128 v[220:223], v2 offset:10432
	s_waitcnt lgkmcnt(11)
	v_fma_f32 v74, -v224, v24, v74
	v_fma_f32 v75, -v225, v25, v75
	v_fma_f32 v0, -v226, v26, v0
	v_fma_f32 v69, -v227, v27, v69
	ds_read_b128 v[224:227], v2 offset:10448
	s_waitcnt lgkmcnt(11)
	v_fma_f32 v74, -v228, v28, v74
	v_fma_f32 v75, -v229, v29, v75
	v_fma_f32 v0, -v230, v30, v0
	v_fma_f32 v69, -v231, v31, v69
	ds_read_b128 v[228:231], v2 offset:10464
	s_waitcnt lgkmcnt(11)
	v_fma_f32 v74, -v232, v32, v74
	v_fma_f32 v75, -v233, v33, v75
	v_fma_f32 v0, -v234, v34, v0
	v_fma_f32 v69, -v235, v35, v69
	ds_read_b128 v[232:235], v2 offset:10480
	s_waitcnt lgkmcnt(11)
	v_fma_f32 v74, -v236, v36, v74
	v_fma_f32 v75, -v237, v37, v75
	v_fma_f32 v0, -v238, v38, v0
	v_fma_f32 v69, -v239, v39, v69
	ds_read_b128 v[236:239], v2 offset:10608
	s_waitcnt lgkmcnt(11)
	v_fma_f32 v74, -v240, v40, v74
	ds_read_b128 v[240:243], v2 offset:10624
	v_add_f32_e32 v74, v74, v75
	v_add_f32_e32 v0, v0, v69
	v_add_f32_e32 v41, v74, v0
	s_waitcnt lgkmcnt(11)
	v_fma_f32 v74, -v180, v4, v42
	v_fma_f32 v75, -v181, v5, 0
	v_fma_f32 v0, -v182, v6, 0
	v_fma_f32 v69, -v183, v7, 0
	ds_read_b128 v[180:183], v2 offset:10640
	s_waitcnt lgkmcnt(11)
	v_fma_f32 v74, -v70, v8, v74
	v_fma_f32 v75, -v71, v9, v75
	v_fma_f32 v0, -v72, v10, v0
	v_fma_f32 v69, -v73, v11, v69
	ds_read_b128 v[70:73], v2 offset:10656
	s_waitcnt lgkmcnt(11)
	v_fma_f32 v74, -v204, v12, v74
	v_fma_f32 v75, -v205, v13, v75
	v_fma_f32 v0, -v206, v14, v0
	v_fma_f32 v69, -v207, v15, v69
	ds_read_b128 v[204:207], v2 offset:10672
	s_waitcnt lgkmcnt(11)
	v_fma_f32 v74, -v208, v16, v74
	v_fma_f32 v75, -v209, v17, v75
	v_fma_f32 v0, -v210, v18, v0
	v_fma_f32 v69, -v211, v19, v69
	ds_read_b128 v[208:211], v2 offset:10688
	s_waitcnt lgkmcnt(11)
	v_fma_f32 v74, -v212, v20, v74
	v_fma_f32 v75, -v213, v21, v75
	v_fma_f32 v0, -v214, v22, v0
	v_fma_f32 v69, -v215, v23, v69
	ds_read_b128 v[212:215], v2 offset:10704
	s_waitcnt lgkmcnt(11)
	v_fma_f32 v74, -v216, v24, v74
	v_fma_f32 v75, -v217, v25, v75
	v_fma_f32 v0, -v218, v26, v0
	v_fma_f32 v69, -v219, v27, v69
	ds_read_b128 v[216:219], v2 offset:10720
	s_waitcnt lgkmcnt(11)
	v_fma_f32 v74, -v220, v28, v74
	v_fma_f32 v75, -v221, v29, v75
	v_fma_f32 v0, -v222, v30, v0
	v_fma_f32 v69, -v223, v31, v69
	ds_read_b128 v[220:223], v2 offset:10736
	s_waitcnt lgkmcnt(11)
	v_fma_f32 v74, -v224, v32, v74
	v_fma_f32 v75, -v225, v33, v75
	v_fma_f32 v0, -v226, v34, v0
	v_fma_f32 v69, -v227, v35, v69
	ds_read_b128 v[224:227], v2 offset:10752
	s_waitcnt lgkmcnt(11)
	v_fma_f32 v74, -v228, v36, v74
	v_fma_f32 v75, -v229, v37, v75
	v_fma_f32 v0, -v230, v38, v0
	v_fma_f32 v69, -v231, v39, v69
	ds_read_b128 v[228:231], v2 offset:10880
	s_waitcnt lgkmcnt(11)
	v_fma_f32 v74, -v232, v40, v74
	v_fma_f32 v75, -v233, v41, v75
	ds_read_b128 v[232:235], v2 offset:10896
	v_add_f32_e32 v74, v74, v75
	v_add_f32_e32 v0, v0, v69
	v_add_f32_e32 v42, v74, v0
	s_waitcnt lgkmcnt(11)
	v_fma_f32 v74, -v236, v4, v43
	v_fma_f32 v75, -v237, v5, 0
	v_fma_f32 v0, -v238, v6, 0
	v_fma_f32 v69, -v239, v7, 0
	ds_read_b128 v[236:239], v2 offset:10912
	s_waitcnt lgkmcnt(11)
	v_fma_f32 v74, -v240, v8, v74
	v_fma_f32 v75, -v241, v9, v75
	v_fma_f32 v0, -v242, v10, v0
	v_fma_f32 v69, -v243, v11, v69
	ds_read_b128 v[240:243], v2 offset:10928
	s_waitcnt lgkmcnt(11)
	v_fma_f32 v74, -v180, v12, v74
	v_fma_f32 v75, -v181, v13, v75
	v_fma_f32 v0, -v182, v14, v0
	v_fma_f32 v69, -v183, v15, v69
	ds_read_b128 v[180:183], v2 offset:10944
	s_waitcnt lgkmcnt(11)
	v_fma_f32 v74, -v70, v16, v74
	v_fma_f32 v75, -v71, v17, v75
	v_fma_f32 v0, -v72, v18, v0
	v_fma_f32 v69, -v73, v19, v69
	ds_read_b128 v[70:73], v2 offset:10960
	s_waitcnt lgkmcnt(11)
	v_fma_f32 v74, -v204, v20, v74
	v_fma_f32 v75, -v205, v21, v75
	v_fma_f32 v0, -v206, v22, v0
	v_fma_f32 v69, -v207, v23, v69
	ds_read_b128 v[204:207], v2 offset:10976
	s_waitcnt lgkmcnt(11)
	v_fma_f32 v74, -v208, v24, v74
	v_fma_f32 v75, -v209, v25, v75
	v_fma_f32 v0, -v210, v26, v0
	v_fma_f32 v69, -v211, v27, v69
	ds_read_b128 v[208:211], v2 offset:10992
	s_waitcnt lgkmcnt(11)
	v_fma_f32 v74, -v212, v28, v74
	v_fma_f32 v75, -v213, v29, v75
	v_fma_f32 v0, -v214, v30, v0
	v_fma_f32 v69, -v215, v31, v69
	ds_read_b128 v[212:215], v2 offset:11008
	s_waitcnt lgkmcnt(11)
	v_fma_f32 v74, -v216, v32, v74
	v_fma_f32 v75, -v217, v33, v75
	v_fma_f32 v0, -v218, v34, v0
	v_fma_f32 v69, -v219, v35, v69
	ds_read_b128 v[216:219], v2 offset:11024
	s_waitcnt lgkmcnt(11)
	v_fma_f32 v74, -v220, v36, v74
	v_fma_f32 v75, -v221, v37, v75
	v_fma_f32 v0, -v222, v38, v0
	v_fma_f32 v69, -v223, v39, v69
	ds_read_b128 v[220:223], v2 offset:11152
	s_waitcnt lgkmcnt(11)
	v_fma_f32 v74, -v224, v40, v74
	v_fma_f32 v75, -v225, v41, v75
	v_fma_f32 v0, -v226, v42, v0
	ds_read_b128 v[224:227], v2 offset:11168
	v_add_f32_e32 v74, v74, v75
	v_add_f32_e32 v0, v0, v69
	v_add_f32_e32 v43, v74, v0
	s_waitcnt lgkmcnt(11)
	v_fma_f32 v74, -v228, v4, v44
	v_fma_f32 v75, -v229, v5, 0
	v_fma_f32 v0, -v230, v6, 0
	v_fma_f32 v69, -v231, v7, 0
	ds_read_b128 v[228:231], v2 offset:11184
	s_waitcnt lgkmcnt(11)
	v_fma_f32 v74, -v232, v8, v74
	v_fma_f32 v75, -v233, v9, v75
	v_fma_f32 v0, -v234, v10, v0
	v_fma_f32 v69, -v235, v11, v69
	ds_read_b128 v[232:235], v2 offset:11200
	s_waitcnt lgkmcnt(11)
	v_fma_f32 v74, -v236, v12, v74
	v_fma_f32 v75, -v237, v13, v75
	v_fma_f32 v0, -v238, v14, v0
	v_fma_f32 v69, -v239, v15, v69
	ds_read_b128 v[236:239], v2 offset:11216
	s_waitcnt lgkmcnt(11)
; #define LAS __attribute__((address_space(3)))
; __device__ __forceinline__ void gdn_prep_unit(const Args& c, int ug, int l, LAS unsigned char* lds) {
;     ...
;         for (int i = 1; i < 64; ++i) {
;             float s0 = x[i], s1 = 0.f, s2 = 0.f, s3 = 0.f;
; #pragma unroll
;             for (int m4 = 0; m4 < i; m4 += 4) {
;                 const f32x4 mv = *(const LAS f32x4*)(Mz + i * 68 + m4);
;                 s0 -= mv.x * x[m4];
;                 if (m4 + 1 < i) s1 -= mv.y * x[m4 + 1];
;                 if (m4 + 2 < i) s2 -= mv.z * x[m4 + 2];
;                 if (m4 + 3 < i) s3 -= mv.w * x[m4 + 3];
;             }
;             const float s = (s0 + s1) + (s2 + s3);
;             x[i] = s;
	v_fma_f32 v74, -v240, v16, v74
	v_fma_f32 v75, -v241, v17, v75
	v_fma_f32 v0, -v242, v18, v0
	v_fma_f32 v69, -v243, v19, v69
	ds_read_b128 v[240:243], v2 offset:11232
	s_waitcnt lgkmcnt(11)
	v_fma_f32 v74, -v180, v20, v74
	v_fma_f32 v75, -v181, v21, v75
	v_fma_f32 v0, -v182, v22, v0
	v_fma_f32 v69, -v183, v23, v69
	ds_read_b128 v[180:183], v2 offset:11248
	s_waitcnt lgkmcnt(11)
	v_fma_f32 v74, -v70, v24, v74
	v_fma_f32 v75, -v71, v25, v75
	v_fma_f32 v0, -v72, v26, v0
	v_fma_f32 v69, -v73, v27, v69
	ds_read_b128 v[70:73], v2 offset:11264
	s_waitcnt lgkmcnt(11)
	v_fma_f32 v74, -v204, v28, v74
	v_fma_f32 v75, -v205, v29, v75
	v_fma_f32 v0, -v206, v30, v0
	v_fma_f32 v69, -v207, v31, v69
	ds_read_b128 v[204:207], v2 offset:11280
	s_waitcnt lgkmcnt(11)
	v_fma_f32 v74, -v208, v32, v74
	v_fma_f32 v75, -v209, v33, v75
	v_fma_f32 v0, -v210, v34, v0
	v_fma_f32 v69, -v211, v35, v69
	ds_read_b128 v[208:211], v2 offset:11296
	s_waitcnt lgkmcnt(11)
	v_fma_f32 v74, -v212, v36, v74
	v_fma_f32 v75, -v213, v37, v75
	v_fma_f32 v0, -v214, v38, v0
	v_fma_f32 v69, -v215, v39, v69
	ds_read_b128 v[212:215], v2 offset:11312
	s_waitcnt lgkmcnt(11)
	v_fma_f32 v74, -v216, v40, v74
	v_fma_f32 v75, -v217, v41, v75
	v_fma_f32 v0, -v218, v42, v0
	v_fma_f32 v69, -v219, v43, v69
	ds_read_b128 v[216:219], v2 offset:11424
	v_add_f32_e32 v74, v74, v75
	v_add_f32_e32 v0, v0, v69
	v_add_f32_e32 v44, v74, v0
	s_waitcnt lgkmcnt(11)
	v_fma_f32 v74, -v220, v4, v45
	v_fma_f32 v75, -v221, v5, 0
	v_fma_f32 v0, -v222, v6, 0
	v_fma_f32 v69, -v223, v7, 0
	ds_read_b128 v[220:223], v2 offset:11440
	s_waitcnt lgkmcnt(11)
	v_fma_f32 v74, -v224, v8, v74
	v_fma_f32 v75, -v225, v9, v75
	v_fma_f32 v0, -v226, v10, v0
	v_fma_f32 v69, -v227, v11, v69
	ds_read_b128 v[224:227], v2 offset:11456
	s_waitcnt lgkmcnt(11)
	v_fma_f32 v74, -v228, v12, v74
	v_fma_f32 v75, -v229, v13, v75
	v_fma_f32 v0, -v230, v14, v0
	v_fma_f32 v69, -v231, v15, v69
	ds_read_b128 v[228:231], v2 offset:11472
	s_waitcnt lgkmcnt(11)
	v_fma_f32 v74, -v232, v16, v74
	v_fma_f32 v75, -v233, v17, v75
	v_fma_f32 v0, -v234, v18, v0
	v_fma_f32 v69, -v235, v19, v69
	ds_read_b128 v[232:235], v2 offset:11488
	s_waitcnt lgkmcnt(11)
	v_fma_f32 v74, -v236, v20, v74
	v_fma_f32 v75, -v237, v21, v75
	v_fma_f32 v0, -v238, v22, v0
	v_fma_f32 v69, -v239, v23, v69
	ds_read_b128 v[236:239], v2 offset:11504
	s_waitcnt lgkmcnt(11)
	v_fma_f32 v74, -v240, v24, v74
	v_fma_f32 v75, -v241, v25, v75
	v_fma_f32 v0, -v242, v26, v0
	v_fma_f32 v69, -v243, v27, v69
	ds_read_b128 v[240:243], v2 offset:11520
	s_waitcnt lgkmcnt(11)
	v_fma_f32 v74, -v180, v28, v74
	v_fma_f32 v75, -v181, v29, v75
	v_fma_f32 v0, -v182, v30, v0
	v_fma_f32 v69, -v183, v31, v69
	ds_read_b128 v[180:183], v2 offset:11536
	s_waitcnt lgkmcnt(11)
	v_fma_f32 v74, -v70, v32, v74
	v_fma_f32 v75, -v71, v33, v75
	v_fma_f32 v0, -v72, v34, v0
	v_fma_f32 v69, -v73, v35, v69
	ds_read_b128 v[70:73], v2 offset:11552
	s_waitcnt lgkmcnt(11)
	v_fma_f32 v74, -v204, v36, v74
	v_fma_f32 v75, -v205, v37, v75
	v_fma_f32 v0, -v206, v38, v0
	v_fma_f32 v69, -v207, v39, v69
	ds_read_b128 v[204:207], v2 offset:11568
	s_waitcnt lgkmcnt(11)
	v_fma_f32 v74, -v208, v40, v74
	v_fma_f32 v75, -v209, v41, v75
	v_fma_f32 v0, -v210, v42, v0
	v_fma_f32 v69, -v211, v43, v69
	ds_read_b128 v[208:211], v2 offset:11584
	s_waitcnt lgkmcnt(11)
	v_fma_f32 v74, -v212, v44, v74
	ds_read_b128 v[212:215], v2 offset:11696
	v_add_f32_e32 v74, v74, v75
	v_add_f32_e32 v0, v0, v69
	v_add_f32_e32 v45, v74, v0
	s_waitcnt lgkmcnt(11)
	v_fma_f32 v74, -v216, v4, v46
	v_fma_f32 v75, -v217, v5, 0
	v_fma_f32 v0, -v218, v6, 0
	v_fma_f32 v69, -v219, v7, 0
	ds_read_b128 v[216:219], v2 offset:11712
	s_waitcnt lgkmcnt(11)
	v_fma_f32 v74, -v220, v8, v74
	v_fma_f32 v75, -v221, v9, v75
	v_fma_f32 v0, -v222, v10, v0
	v_fma_f32 v69, -v223, v11, v69
	ds_read_b128 v[220:223], v2 offset:11728
	s_waitcnt lgkmcnt(11)
	v_fma_f32 v74, -v224, v12, v74
	v_fma_f32 v75, -v225, v13, v75
	v_fma_f32 v0, -v226, v14, v0
	v_fma_f32 v69, -v227, v15, v69
	ds_read_b128 v[224:227], v2 offset:11744
	s_waitcnt lgkmcnt(11)
	v_fma_f32 v74, -v228, v16, v74
	v_fma_f32 v75, -v229, v17, v75
	v_fma_f32 v0, -v230, v18, v0
	v_fma_f32 v69, -v231, v19, v69
	ds_read_b128 v[228:231], v2 offset:11760
	s_waitcnt lgkmcnt(11)
	v_fma_f32 v74, -v232, v20, v74
	v_fma_f32 v75, -v233, v21, v75
	v_fma_f32 v0, -v234, v22, v0
	v_fma_f32 v69, -v235, v23, v69
	ds_read_b128 v[232:235], v2 offset:11776
	s_waitcnt lgkmcnt(11)
	v_fma_f32 v74, -v236, v24, v74
	v_fma_f32 v75, -v237, v25, v75
	v_fma_f32 v0, -v238, v26, v0
	v_fma_f32 v69, -v239, v27, v69
	ds_read_b128 v[236:239], v2 offset:11792
	s_waitcnt lgkmcnt(11)
	v_fma_f32 v74, -v240, v28, v74
	v_fma_f32 v75, -v241, v29, v75
	v_fma_f32 v0, -v242, v30, v0
	v_fma_f32 v69, -v243, v31, v69
	ds_read_b128 v[240:243], v2 offset:11808
	s_waitcnt lgkmcnt(11)
	v_fma_f32 v74, -v180, v32, v74
	v_fma_f32 v75, -v181, v33, v75
	v_fma_f32 v0, -v182, v34, v0
	v_fma_f32 v69, -v183, v35, v69
	ds_read_b128 v[180:183], v2 offset:11824
	s_waitcnt lgkmcnt(11)
	v_fma_f32 v74, -v70, v36, v74
	v_fma_f32 v75, -v71, v37, v75
	v_fma_f32 v0, -v72, v38, v0
	v_fma_f32 v69, -v73, v39, v69
	ds_read_b128 v[70:73], v2 offset:11840
	s_waitcnt lgkmcnt(11)
	v_fma_f32 v74, -v204, v40, v74
	v_fma_f32 v75, -v205, v41, v75
	v_fma_f32 v0, -v206, v42, v0
	v_fma_f32 v69, -v207, v43, v69
	ds_read_b128 v[204:207], v2 offset:11856
	s_waitcnt lgkmcnt(11)
	v_fma_f32 v74, -v208, v44, v74
	v_fma_f32 v75, -v209, v45, v75
	ds_read_b128 v[208:211], v2 offset:11968
	v_add_f32_e32 v74, v74, v75
	v_add_f32_e32 v0, v0, v69
	v_add_f32_e32 v46, v74, v0
	s_waitcnt lgkmcnt(11)
; #define LAS __attribute__((address_space(3)))
; __device__ __forceinline__ void gdn_prep_unit(const Args& c, int ug, int l, LAS unsigned char* lds) {
;     ...
;         for (int i = 1; i < 64; ++i) {
;             float s0 = x[i], s1 = 0.f, s2 = 0.f, s3 = 0.f;
; #pragma unroll
;             for (int m4 = 0; m4 < i; m4 += 4) {
;                 const f32x4 mv = *(const LAS f32x4*)(Mz + i * 68 + m4);
;                 s0 -= mv.x * x[m4];
;                 if (m4 + 1 < i) s1 -= mv.y * x[m4 + 1];
;                 if (m4 + 2 < i) s2 -= mv.z * x[m4 + 2];
;                 if (m4 + 3 < i) s3 -= mv.w * x[m4 + 3];
;             }
;             const float s = (s0 + s1) + (s2 + s3);
;             x[i] = s;
	v_fma_f32 v74, -v212, v4, v47
	v_fma_f32 v75, -v213, v5, 0
	v_fma_f32 v0, -v214, v6, 0
	v_fma_f32 v69, -v215, v7, 0
	ds_read_b128 v[212:215], v2 offset:11984
	s_waitcnt lgkmcnt(11)
	v_fma_f32 v74, -v216, v8, v74
	v_fma_f32 v75, -v217, v9, v75
	v_fma_f32 v0, -v218, v10, v0
	v_fma_f32 v69, -v219, v11, v69
	ds_read_b128 v[216:219], v2 offset:12000
	s_waitcnt lgkmcnt(11)
	v_fma_f32 v74, -v220, v12, v74
	v_fma_f32 v75, -v221, v13, v75
	v_fma_f32 v0, -v222, v14, v0
	v_fma_f32 v69, -v223, v15, v69
	ds_read_b128 v[220:223], v2 offset:12016
	s_waitcnt lgkmcnt(11)
	v_fma_f32 v74, -v224, v16, v74
	v_fma_f32 v75, -v225, v17, v75
	v_fma_f32 v0, -v226, v18, v0
	v_fma_f32 v69, -v227, v19, v69
	ds_read_b128 v[224:227], v2 offset:12032
	s_waitcnt lgkmcnt(11)
	v_fma_f32 v74, -v228, v20, v74
	v_fma_f32 v75, -v229, v21, v75
	v_fma_f32 v0, -v230, v22, v0
	v_fma_f32 v69, -v231, v23, v69
	ds_read_b128 v[228:231], v2 offset:12048
	s_waitcnt lgkmcnt(11)
	v_fma_f32 v74, -v232, v24, v74
	v_fma_f32 v75, -v233, v25, v75
	v_fma_f32 v0, -v234, v26, v0
	v_fma_f32 v69, -v235, v27, v69
	ds_read_b128 v[232:235], v2 offset:12064
	s_waitcnt lgkmcnt(11)
	v_fma_f32 v74, -v236, v28, v74
	v_fma_f32 v75, -v237, v29, v75
	v_fma_f32 v0, -v238, v30, v0
	v_fma_f32 v69, -v239, v31, v69
	ds_read_b128 v[236:239], v2 offset:12080
	s_waitcnt lgkmcnt(11)
	v_fma_f32 v74, -v240, v32, v74
	v_fma_f32 v75, -v241, v33, v75
	v_fma_f32 v0, -v242, v34, v0
	v_fma_f32 v69, -v243, v35, v69
	ds_read_b128 v[240:243], v2 offset:12096
	s_waitcnt lgkmcnt(11)
	v_fma_f32 v74, -v180, v36, v74
	v_fma_f32 v75, -v181, v37, v75
	v_fma_f32 v0, -v182, v38, v0
	v_fma_f32 v69, -v183, v39, v69
	ds_read_b128 v[180:183], v2 offset:12112
	s_waitcnt lgkmcnt(11)
	v_fma_f32 v74, -v70, v40, v74
	v_fma_f32 v75, -v71, v41, v75
	v_fma_f32 v0, -v72, v42, v0
	v_fma_f32 v69, -v73, v43, v69
	ds_read_b128 v[70:73], v2 offset:12128
	s_waitcnt lgkmcnt(11)
	v_fma_f32 v74, -v204, v44, v74
	v_fma_f32 v75, -v205, v45, v75
	v_fma_f32 v0, -v206, v46, v0
	ds_read_b128 v[204:207], v2 offset:12240
	v_add_f32_e32 v74, v74, v75
	v_add_f32_e32 v0, v0, v69
	v_add_f32_e32 v47, v74, v0
	s_waitcnt lgkmcnt(11)
	v_fma_f32 v74, -v208, v4, v48
	v_fma_f32 v75, -v209, v5, 0
	v_fma_f32 v0, -v210, v6, 0
	v_fma_f32 v69, -v211, v7, 0
	ds_read_b128 v[208:211], v2 offset:12256
	s_waitcnt lgkmcnt(11)
	v_fma_f32 v74, -v212, v8, v74
	v_fma_f32 v75, -v213, v9, v75
	v_fma_f32 v0, -v214, v10, v0
	v_fma_f32 v69, -v215, v11, v69
	ds_read_b128 v[212:215], v2 offset:12272
	s_waitcnt lgkmcnt(11)
	v_fma_f32 v74, -v216, v12, v74
	v_fma_f32 v75, -v217, v13, v75
	v_fma_f32 v0, -v218, v14, v0
	v_fma_f32 v69, -v219, v15, v69
	ds_read_b128 v[216:219], v2 offset:12288
	s_waitcnt lgkmcnt(11)
	v_fma_f32 v74, -v220, v16, v74
	v_fma_f32 v75, -v221, v17, v75
	v_fma_f32 v0, -v222, v18, v0
	v_fma_f32 v69, -v223, v19, v69
	ds_read_b128 v[220:223], v2 offset:12304
	s_waitcnt lgkmcnt(11)
	v_fma_f32 v74, -v224, v20, v74
	v_fma_f32 v75, -v225, v21, v75
	v_fma_f32 v0, -v226, v22, v0
	v_fma_f32 v69, -v227, v23, v69
	ds_read_b128 v[224:227], v2 offset:12320
	s_waitcnt lgkmcnt(11)
	v_fma_f32 v74, -v228, v24, v74
	v_fma_f32 v75, -v229, v25, v75
	v_fma_f32 v0, -v230, v26, v0
	v_fma_f32 v69, -v231, v27, v69
	ds_read_b128 v[228:231], v2 offset:12336
	s_waitcnt lgkmcnt(11)
	v_fma_f32 v74, -v232, v28, v74
	v_fma_f32 v75, -v233, v29, v75
	v_fma_f32 v0, -v234, v30, v0
	v_fma_f32 v69, -v235, v31, v69
	ds_read_b128 v[232:235], v2 offset:12352
	s_waitcnt lgkmcnt(11)
	v_fma_f32 v74, -v236, v32, v74
	v_fma_f32 v75, -v237, v33, v75
	v_fma_f32 v0, -v238, v34, v0
	v_fma_f32 v69, -v239, v35, v69
	ds_read_b128 v[236:239], v2 offset:12368
	s_waitcnt lgkmcnt(11)
	v_fma_f32 v74, -v240, v36, v74
	v_fma_f32 v75, -v241, v37, v75
	v_fma_f32 v0, -v242, v38, v0
	v_fma_f32 v69, -v243, v39, v69
	ds_read_b128 v[240:243], v2 offset:12384
	s_waitcnt lgkmcnt(11)
	v_fma_f32 v74, -v180, v40, v74
	v_fma_f32 v75, -v181, v41, v75
	v_fma_f32 v0, -v182, v42, v0
	v_fma_f32 v69, -v183, v43, v69
	ds_read_b128 v[180:183], v2 offset:12400
	s_waitcnt lgkmcnt(11)
	v_fma_f32 v74, -v70, v44, v74
	v_fma_f32 v75, -v71, v45, v75
	v_fma_f32 v0, -v72, v46, v0
	v_fma_f32 v69, -v73, v47, v69
	ds_read_b128 v[70:73], v2 offset:12416
	v_add_f32_e32 v74, v74, v75
	v_add_f32_e32 v0, v0, v69
	v_add_f32_e32 v48, v74, v0
	s_waitcnt lgkmcnt(11)
	v_fma_f32 v74, -v204, v4, v49
	v_fma_f32 v75, -v205, v5, 0
	v_fma_f32 v0, -v206, v6, 0
	v_fma_f32 v69, -v207, v7, 0
	ds_read_b128 v[204:207], v2 offset:12512
	s_waitcnt lgkmcnt(11)
	v_fma_f32 v74, -v208, v8, v74
	v_fma_f32 v75, -v209, v9, v75
	v_fma_f32 v0, -v210, v10, v0
	v_fma_f32 v69, -v211, v11, v69
	ds_read_b128 v[208:211], v2 offset:12528
	s_waitcnt lgkmcnt(11)
	v_fma_f32 v74, -v212, v12, v74
	v_fma_f32 v75, -v213, v13, v75
	v_fma_f32 v0, -v214, v14, v0
	v_fma_f32 v69, -v215, v15, v69
	ds_read_b128 v[212:215], v2 offset:12544
	s_waitcnt lgkmcnt(11)
	v_fma_f32 v74, -v216, v16, v74
	v_fma_f32 v75, -v217, v17, v75
	v_fma_f32 v0, -v218, v18, v0
	v_fma_f32 v69, -v219, v19, v69
	ds_read_b128 v[216:219], v2 offset:12560
	s_waitcnt lgkmcnt(11)
	v_fma_f32 v74, -v220, v20, v74
	v_fma_f32 v75, -v221, v21, v75
	v_fma_f32 v0, -v222, v22, v0
	v_fma_f32 v69, -v223, v23, v69
	ds_read_b128 v[220:223], v2 offset:12576
	s_waitcnt lgkmcnt(11)
	v_fma_f32 v74, -v224, v24, v74
	v_fma_f32 v75, -v225, v25, v75
	v_fma_f32 v0, -v226, v26, v0
	v_fma_f32 v69, -v227, v27, v69
	ds_read_b128 v[224:227], v2 offset:12592
	s_waitcnt lgkmcnt(11)
	v_fma_f32 v74, -v228, v28, v74
	v_fma_f32 v75, -v229, v29, v75
	v_fma_f32 v0, -v230, v30, v0
	v_fma_f32 v69, -v231, v31, v69
	ds_read_b128 v[228:231], v2 offset:12608
	s_waitcnt lgkmcnt(11)
; #define LAS __attribute__((address_space(3)))
; __device__ __forceinline__ void gdn_prep_unit(const Args& c, int ug, int l, LAS unsigned char* lds) {
;     ...
;         for (int i = 1; i < 64; ++i) {
;             float s0 = x[i], s1 = 0.f, s2 = 0.f, s3 = 0.f;
; #pragma unroll
;             for (int m4 = 0; m4 < i; m4 += 4) {
;                 const f32x4 mv = *(const LAS f32x4*)(Mz + i * 68 + m4);
;                 s0 -= mv.x * x[m4];
;                 if (m4 + 1 < i) s1 -= mv.y * x[m4 + 1];
;                 if (m4 + 2 < i) s2 -= mv.z * x[m4 + 2];
;                 if (m4 + 3 < i) s3 -= mv.w * x[m4 + 3];
;             }
;             const float s = (s0 + s1) + (s2 + s3);
;             x[i] = s;
	v_fma_f32 v74, -v232, v32, v74
	v_fma_f32 v75, -v233, v33, v75
	v_fma_f32 v0, -v234, v34, v0
	v_fma_f32 v69, -v235, v35, v69
	ds_read_b128 v[232:235], v2 offset:12624
	s_waitcnt lgkmcnt(11)
	v_fma_f32 v74, -v236, v36, v74
	v_fma_f32 v75, -v237, v37, v75
	v_fma_f32 v0, -v238, v38, v0
	v_fma_f32 v69, -v239, v39, v69
	ds_read_b128 v[236:239], v2 offset:12640
	s_waitcnt lgkmcnt(11)
	v_fma_f32 v74, -v240, v40, v74
	v_fma_f32 v75, -v241, v41, v75
	v_fma_f32 v0, -v242, v42, v0
	v_fma_f32 v69, -v243, v43, v69
	ds_read_b128 v[240:243], v2 offset:12656
	s_waitcnt lgkmcnt(11)
	v_fma_f32 v74, -v180, v44, v74
	v_fma_f32 v75, -v181, v45, v75
	v_fma_f32 v0, -v182, v46, v0
	v_fma_f32 v69, -v183, v47, v69
	ds_read_b128 v[180:183], v2 offset:12672
	s_waitcnt lgkmcnt(11)
	v_fma_f32 v74, -v70, v48, v74
	ds_read_b128 v[70:73], v2 offset:12688
	v_add_f32_e32 v74, v74, v75
	v_add_f32_e32 v0, v0, v69
	v_add_f32_e32 v49, v74, v0
	s_waitcnt lgkmcnt(11)
	v_fma_f32 v74, -v204, v4, v50
	v_fma_f32 v75, -v205, v5, 0
	v_fma_f32 v0, -v206, v6, 0
	v_fma_f32 v69, -v207, v7, 0
	ds_read_b128 v[204:207], v2 offset:12784
	s_waitcnt lgkmcnt(11)
	v_fma_f32 v74, -v208, v8, v74
	v_fma_f32 v75, -v209, v9, v75
	v_fma_f32 v0, -v210, v10, v0
	v_fma_f32 v69, -v211, v11, v69
	ds_read_b128 v[208:211], v2 offset:12800
	s_waitcnt lgkmcnt(11)
	v_fma_f32 v74, -v212, v12, v74
	v_fma_f32 v75, -v213, v13, v75
	v_fma_f32 v0, -v214, v14, v0
	v_fma_f32 v69, -v215, v15, v69
	ds_read_b128 v[212:215], v2 offset:12816
	s_waitcnt lgkmcnt(11)
	v_fma_f32 v74, -v216, v16, v74
	v_fma_f32 v75, -v217, v17, v75
	v_fma_f32 v0, -v218, v18, v0
	v_fma_f32 v69, -v219, v19, v69
	ds_read_b128 v[216:219], v2 offset:12832
	s_waitcnt lgkmcnt(11)
	v_fma_f32 v74, -v220, v20, v74
	v_fma_f32 v75, -v221, v21, v75
	v_fma_f32 v0, -v222, v22, v0
	v_fma_f32 v69, -v223, v23, v69
	ds_read_b128 v[220:223], v2 offset:12848
	s_waitcnt lgkmcnt(11)
	v_fma_f32 v74, -v224, v24, v74
	v_fma_f32 v75, -v225, v25, v75
	v_fma_f32 v0, -v226, v26, v0
	v_fma_f32 v69, -v227, v27, v69
	ds_read_b128 v[224:227], v2 offset:12864
	s_waitcnt lgkmcnt(11)
	v_fma_f32 v74, -v228, v28, v74
	v_fma_f32 v75, -v229, v29, v75
	v_fma_f32 v0, -v230, v30, v0
	v_fma_f32 v69, -v231, v31, v69
	ds_read_b128 v[228:231], v2 offset:12880
	s_waitcnt lgkmcnt(11)
	v_fma_f32 v74, -v232, v32, v74
	v_fma_f32 v75, -v233, v33, v75
	v_fma_f32 v0, -v234, v34, v0
	v_fma_f32 v69, -v235, v35, v69
	ds_read_b128 v[232:235], v2 offset:12896
	s_waitcnt lgkmcnt(11)
	v_fma_f32 v74, -v236, v36, v74
	v_fma_f32 v75, -v237, v37, v75
	v_fma_f32 v0, -v238, v38, v0
	v_fma_f32 v69, -v239, v39, v69
	ds_read_b128 v[236:239], v2 offset:12912
	s_waitcnt lgkmcnt(11)
	v_fma_f32 v74, -v240, v40, v74
	v_fma_f32 v75, -v241, v41, v75
	v_fma_f32 v0, -v242, v42, v0
	v_fma_f32 v69, -v243, v43, v69
	ds_read_b128 v[240:243], v2 offset:12928
	s_waitcnt lgkmcnt(11)
	v_fma_f32 v74, -v180, v44, v74
	v_fma_f32 v75, -v181, v45, v75
	v_fma_f32 v0, -v182, v46, v0
	v_fma_f32 v69, -v183, v47, v69
	ds_read_b128 v[180:183], v2 offset:12944
	s_waitcnt lgkmcnt(11)
	v_fma_f32 v74, -v70, v48, v74
	v_fma_f32 v75, -v71, v49, v75
	ds_read_b128 v[70:73], v2 offset:12960
	v_add_f32_e32 v74, v74, v75
	v_add_f32_e32 v0, v0, v69
	v_add_f32_e32 v50, v74, v0
	s_waitcnt lgkmcnt(11)
	v_fma_f32 v74, -v204, v4, v51
	v_fma_f32 v75, -v205, v5, 0
	v_fma_f32 v0, -v206, v6, 0
	v_fma_f32 v69, -v207, v7, 0
	ds_read_b128 v[204:207], v2 offset:13056
	s_waitcnt lgkmcnt(11)
	v_fma_f32 v74, -v208, v8, v74
	v_fma_f32 v75, -v209, v9, v75
	v_fma_f32 v0, -v210, v10, v0
	v_fma_f32 v69, -v211, v11, v69
	ds_read_b128 v[208:211], v2 offset:13072
	s_waitcnt lgkmcnt(11)
	v_fma_f32 v74, -v212, v12, v74
	v_fma_f32 v75, -v213, v13, v75
	v_fma_f32 v0, -v214, v14, v0
	v_fma_f32 v69, -v215, v15, v69
	ds_read_b128 v[212:215], v2 offset:13088
	s_waitcnt lgkmcnt(11)
	v_fma_f32 v74, -v216, v16, v74
	v_fma_f32 v75, -v217, v17, v75
	v_fma_f32 v0, -v218, v18, v0
	v_fma_f32 v69, -v219, v19, v69
	ds_read_b128 v[216:219], v2 offset:13104
	s_waitcnt lgkmcnt(11)
	v_fma_f32 v74, -v220, v20, v74
	v_fma_f32 v75, -v221, v21, v75
	v_fma_f32 v0, -v222, v22, v0
	v_fma_f32 v69, -v223, v23, v69
	ds_read_b128 v[220:223], v2 offset:13120
	s_waitcnt lgkmcnt(11)
	v_fma_f32 v74, -v224, v24, v74
	v_fma_f32 v75, -v225, v25, v75
	v_fma_f32 v0, -v226, v26, v0
	v_fma_f32 v69, -v227, v27, v69
	ds_read_b128 v[224:227], v2 offset:13136
	s_waitcnt lgkmcnt(11)
	v_fma_f32 v74, -v228, v28, v74
	v_fma_f32 v75, -v229, v29, v75
	v_fma_f32 v0, -v230, v30, v0
	v_fma_f32 v69, -v231, v31, v69
	ds_read_b128 v[228:231], v2 offset:13152
	s_waitcnt lgkmcnt(11)
	v_fma_f32 v74, -v232, v32, v74
	v_fma_f32 v75, -v233, v33, v75
	v_fma_f32 v0, -v234, v34, v0
	v_fma_f32 v69, -v235, v35, v69
	ds_read_b128 v[232:235], v2 offset:13168
	s_waitcnt lgkmcnt(11)
	v_fma_f32 v74, -v236, v36, v74
	v_fma_f32 v75, -v237, v37, v75
	v_fma_f32 v0, -v238, v38, v0
	v_fma_f32 v69, -v239, v39, v69
	ds_read_b128 v[236:239], v2 offset:13184
	s_waitcnt lgkmcnt(11)
	v_fma_f32 v74, -v240, v40, v74
	v_fma_f32 v75, -v241, v41, v75
	v_fma_f32 v0, -v242, v42, v0
	v_fma_f32 v69, -v243, v43, v69
	ds_read_b128 v[240:243], v2 offset:13200
	s_waitcnt lgkmcnt(11)
	v_fma_f32 v74, -v180, v44, v74
	v_fma_f32 v75, -v181, v45, v75
	v_fma_f32 v0, -v182, v46, v0
	v_fma_f32 v69, -v183, v47, v69
	ds_read_b128 v[180:183], v2 offset:13216
	s_waitcnt lgkmcnt(11)
	v_fma_f32 v74, -v70, v48, v74
	v_fma_f32 v75, -v71, v49, v75
	v_fma_f32 v0, -v72, v50, v0
	ds_read_b128 v[70:73], v2 offset:13232
	v_add_f32_e32 v74, v74, v75
	v_add_f32_e32 v0, v0, v69
	v_add_f32_e32 v51, v74, v0
	s_waitcnt lgkmcnt(11)
; #define LAS __attribute__((address_space(3)))
; __device__ __forceinline__ void gdn_prep_unit(const Args& c, int ug, int l, LAS unsigned char* lds) {
;     ...
;         for (int i = 1; i < 64; ++i) {
;             float s0 = x[i], s1 = 0.f, s2 = 0.f, s3 = 0.f;
; #pragma unroll
;             for (int m4 = 0; m4 < i; m4 += 4) {
;                 const f32x4 mv = *(const LAS f32x4*)(Mz + i * 68 + m4);
;                 s0 -= mv.x * x[m4];
;                 if (m4 + 1 < i) s1 -= mv.y * x[m4 + 1];
;                 if (m4 + 2 < i) s2 -= mv.z * x[m4 + 2];
;                 if (m4 + 3 < i) s3 -= mv.w * x[m4 + 3];
;             }
;             const float s = (s0 + s1) + (s2 + s3);
;             x[i] = s;
	v_fma_f32 v74, -v204, v4, v52
	v_fma_f32 v75, -v205, v5, 0
	v_fma_f32 v0, -v206, v6, 0
	v_fma_f32 v69, -v207, v7, 0
	ds_read_b128 v[204:207], v2 offset:13328
	s_waitcnt lgkmcnt(11)
	v_fma_f32 v74, -v208, v8, v74
	v_fma_f32 v75, -v209, v9, v75
	v_fma_f32 v0, -v210, v10, v0
	v_fma_f32 v69, -v211, v11, v69
	ds_read_b128 v[208:211], v2 offset:13344
	s_waitcnt lgkmcnt(11)
	v_fma_f32 v74, -v212, v12, v74
	v_fma_f32 v75, -v213, v13, v75
	v_fma_f32 v0, -v214, v14, v0
	v_fma_f32 v69, -v215, v15, v69
	ds_read_b128 v[212:215], v2 offset:13360
	s_waitcnt lgkmcnt(11)
	v_fma_f32 v74, -v216, v16, v74
	v_fma_f32 v75, -v217, v17, v75
	v_fma_f32 v0, -v218, v18, v0
	v_fma_f32 v69, -v219, v19, v69
	ds_read_b128 v[216:219], v2 offset:13376
	s_waitcnt lgkmcnt(11)
	v_fma_f32 v74, -v220, v20, v74
	v_fma_f32 v75, -v221, v21, v75
	v_fma_f32 v0, -v222, v22, v0
	v_fma_f32 v69, -v223, v23, v69
	ds_read_b128 v[220:223], v2 offset:13392
	s_waitcnt lgkmcnt(11)
	v_fma_f32 v74, -v224, v24, v74
	v_fma_f32 v75, -v225, v25, v75
	v_fma_f32 v0, -v226, v26, v0
	v_fma_f32 v69, -v227, v27, v69
	ds_read_b128 v[224:227], v2 offset:13408
	s_waitcnt lgkmcnt(11)
	v_fma_f32 v74, -v228, v28, v74
	v_fma_f32 v75, -v229, v29, v75
	v_fma_f32 v0, -v230, v30, v0
	v_fma_f32 v69, -v231, v31, v69
	ds_read_b128 v[228:231], v2 offset:13424
	s_waitcnt lgkmcnt(11)
	v_fma_f32 v74, -v232, v32, v74
	v_fma_f32 v75, -v233, v33, v75
	v_fma_f32 v0, -v234, v34, v0
	v_fma_f32 v69, -v235, v35, v69
	ds_read_b128 v[232:235], v2 offset:13440
	s_waitcnt lgkmcnt(11)
	v_fma_f32 v74, -v236, v36, v74
	v_fma_f32 v75, -v237, v37, v75
	v_fma_f32 v0, -v238, v38, v0
	v_fma_f32 v69, -v239, v39, v69
	ds_read_b128 v[236:239], v2 offset:13456
	s_waitcnt lgkmcnt(11)
	v_fma_f32 v74, -v240, v40, v74
	v_fma_f32 v75, -v241, v41, v75
	v_fma_f32 v0, -v242, v42, v0
	v_fma_f32 v69, -v243, v43, v69
	ds_read_b128 v[240:243], v2 offset:13472
	s_waitcnt lgkmcnt(11)
	v_fma_f32 v74, -v180, v44, v74
	v_fma_f32 v75, -v181, v45, v75
	v_fma_f32 v0, -v182, v46, v0
	v_fma_f32 v69, -v183, v47, v69
	ds_read_b128 v[180:183], v2 offset:13488
	s_waitcnt lgkmcnt(11)
	v_fma_f32 v74, -v70, v48, v74
	v_fma_f32 v75, -v71, v49, v75
	v_fma_f32 v0, -v72, v50, v0
	v_fma_f32 v69, -v73, v51, v69
	ds_read_b128 v[70:73], v2 offset:13504
	v_add_f32_e32 v74, v74, v75
	v_add_f32_e32 v0, v0, v69
	v_add_f32_e32 v52, v74, v0
	s_waitcnt lgkmcnt(11)
	v_fma_f32 v74, -v204, v4, v53
	v_fma_f32 v75, -v205, v5, 0
	v_fma_f32 v0, -v206, v6, 0
	v_fma_f32 v69, -v207, v7, 0
	ds_read_b128 v[204:207], v2 offset:13520
	s_waitcnt lgkmcnt(11)
	v_fma_f32 v74, -v208, v8, v74
	v_fma_f32 v75, -v209, v9, v75
	v_fma_f32 v0, -v210, v10, v0
	v_fma_f32 v69, -v211, v11, v69
	ds_read_b128 v[208:211], v2 offset:13600
	s_waitcnt lgkmcnt(11)
	v_fma_f32 v74, -v212, v12, v74
	v_fma_f32 v75, -v213, v13, v75
	v_fma_f32 v0, -v214, v14, v0
	v_fma_f32 v69, -v215, v15, v69
	ds_read_b128 v[212:215], v2 offset:13616
	s_waitcnt lgkmcnt(11)
	v_fma_f32 v74, -v216, v16, v74
	v_fma_f32 v75, -v217, v17, v75
	v_fma_f32 v0, -v218, v18, v0
	v_fma_f32 v69, -v219, v19, v69
	ds_read_b128 v[216:219], v2 offset:13632
	s_waitcnt lgkmcnt(11)
	v_fma_f32 v74, -v220, v20, v74
	v_fma_f32 v75, -v221, v21, v75
	v_fma_f32 v0, -v222, v22, v0
	v_fma_f32 v69, -v223, v23, v69
	ds_read_b128 v[220:223], v2 offset:13648
	s_waitcnt lgkmcnt(11)
	v_fma_f32 v74, -v224, v24, v74
	v_fma_f32 v75, -v225, v25, v75
	v_fma_f32 v0, -v226, v26, v0
	v_fma_f32 v69, -v227, v27, v69
	ds_read_b128 v[224:227], v2 offset:13664
	s_waitcnt lgkmcnt(11)
	v_fma_f32 v74, -v228, v28, v74
	v_fma_f32 v75, -v229, v29, v75
	v_fma_f32 v0, -v230, v30, v0
	v_fma_f32 v69, -v231, v31, v69
	ds_read_b128 v[228:231], v2 offset:13680
	s_waitcnt lgkmcnt(11)
	v_fma_f32 v74, -v232, v32, v74
	v_fma_f32 v75, -v233, v33, v75
	v_fma_f32 v0, -v234, v34, v0
	v_fma_f32 v69, -v235, v35, v69
	ds_read_b128 v[232:235], v2 offset:13696
	s_waitcnt lgkmcnt(11)
	v_fma_f32 v74, -v236, v36, v74
	v_fma_f32 v75, -v237, v37, v75
	v_fma_f32 v0, -v238, v38, v0
	v_fma_f32 v69, -v239, v39, v69
	ds_read_b128 v[236:239], v2 offset:13712
	s_waitcnt lgkmcnt(11)
	v_fma_f32 v74, -v240, v40, v74
	v_fma_f32 v75, -v241, v41, v75
	v_fma_f32 v0, -v242, v42, v0
	v_fma_f32 v69, -v243, v43, v69
	ds_read_b128 v[240:243], v2 offset:13728
	s_waitcnt lgkmcnt(11)
	v_fma_f32 v74, -v180, v44, v74
	v_fma_f32 v75, -v181, v45, v75
	v_fma_f32 v0, -v182, v46, v0
	v_fma_f32 v69, -v183, v47, v69
	ds_read_b128 v[180:183], v2 offset:13744
	s_waitcnt lgkmcnt(11)
	v_fma_f32 v74, -v70, v48, v74
	v_fma_f32 v75, -v71, v49, v75
	v_fma_f32 v0, -v72, v50, v0
	v_fma_f32 v69, -v73, v51, v69
	ds_read_b128 v[70:73], v2 offset:13760
	s_waitcnt lgkmcnt(11)
	v_fma_f32 v74, -v204, v52, v74
	ds_read_b128 v[204:207], v2 offset:13776
	v_add_f32_e32 v74, v74, v75
	v_add_f32_e32 v0, v0, v69
	v_add_f32_e32 v53, v74, v0
	s_waitcnt lgkmcnt(11)
	v_fma_f32 v74, -v208, v4, v54
	v_fma_f32 v75, -v209, v5, 0
	v_fma_f32 v0, -v210, v6, 0
	v_fma_f32 v69, -v211, v7, 0
	ds_read_b128 v[208:211], v2 offset:13792
	s_waitcnt lgkmcnt(11)
	v_fma_f32 v74, -v212, v8, v74
	v_fma_f32 v75, -v213, v9, v75
	v_fma_f32 v0, -v214, v10, v0
	v_fma_f32 v69, -v215, v11, v69
	ds_read_b128 v[212:215], v2 offset:13872
	s_waitcnt lgkmcnt(11)
	v_fma_f32 v74, -v216, v12, v74
	v_fma_f32 v75, -v217, v13, v75
	v_fma_f32 v0, -v218, v14, v0
	v_fma_f32 v69, -v219, v15, v69
	ds_read_b128 v[216:219], v2 offset:13888
	s_waitcnt lgkmcnt(11)
	v_fma_f32 v74, -v220, v16, v74
	v_fma_f32 v75, -v221, v17, v75
	v_fma_f32 v0, -v222, v18, v0
	v_fma_f32 v69, -v223, v19, v69
	ds_read_b128 v[220:223], v2 offset:13904
	s_waitcnt lgkmcnt(11)
; #define LAS __attribute__((address_space(3)))
; __device__ __forceinline__ void gdn_prep_unit(const Args& c, int ug, int l, LAS unsigned char* lds) {
;     ...
;         for (int i = 1; i < 64; ++i) {
;             float s0 = x[i], s1 = 0.f, s2 = 0.f, s3 = 0.f;
; #pragma unroll
;             for (int m4 = 0; m4 < i; m4 += 4) {
;                 const f32x4 mv = *(const LAS f32x4*)(Mz + i * 68 + m4);
;                 s0 -= mv.x * x[m4];
;                 if (m4 + 1 < i) s1 -= mv.y * x[m4 + 1];
;                 if (m4 + 2 < i) s2 -= mv.z * x[m4 + 2];
;                 if (m4 + 3 < i) s3 -= mv.w * x[m4 + 3];
;             }
;             const float s = (s0 + s1) + (s2 + s3);
;             x[i] = s;
	v_fma_f32 v74, -v224, v20, v74
	v_fma_f32 v75, -v225, v21, v75
	v_fma_f32 v0, -v226, v22, v0
	v_fma_f32 v69, -v227, v23, v69
	ds_read_b128 v[224:227], v2 offset:13920
	s_waitcnt lgkmcnt(11)
	v_fma_f32 v74, -v228, v24, v74
	v_fma_f32 v75, -v229, v25, v75
	v_fma_f32 v0, -v230, v26, v0
	v_fma_f32 v69, -v231, v27, v69
	ds_read_b128 v[228:231], v2 offset:13936
	s_waitcnt lgkmcnt(11)
	v_fma_f32 v74, -v232, v28, v74
	v_fma_f32 v75, -v233, v29, v75
	v_fma_f32 v0, -v234, v30, v0
	v_fma_f32 v69, -v235, v31, v69
	ds_read_b128 v[232:235], v2 offset:13952
	s_waitcnt lgkmcnt(11)
	v_fma_f32 v74, -v236, v32, v74
	v_fma_f32 v75, -v237, v33, v75
	v_fma_f32 v0, -v238, v34, v0
	v_fma_f32 v69, -v239, v35, v69
	ds_read_b128 v[236:239], v2 offset:13968
	s_waitcnt lgkmcnt(11)
	v_fma_f32 v74, -v240, v36, v74
	v_fma_f32 v75, -v241, v37, v75
	v_fma_f32 v0, -v242, v38, v0
	v_fma_f32 v69, -v243, v39, v69
	ds_read_b128 v[240:243], v2 offset:13984
	s_waitcnt lgkmcnt(11)
	v_fma_f32 v74, -v180, v40, v74
	v_fma_f32 v75, -v181, v41, v75
	v_fma_f32 v0, -v182, v42, v0
	v_fma_f32 v69, -v183, v43, v69
	ds_read_b128 v[180:183], v2 offset:14000
	s_waitcnt lgkmcnt(11)
	v_fma_f32 v74, -v70, v44, v74
	v_fma_f32 v75, -v71, v45, v75
	v_fma_f32 v0, -v72, v46, v0
	v_fma_f32 v69, -v73, v47, v69
	ds_read_b128 v[70:73], v2 offset:14016
	s_waitcnt lgkmcnt(11)
	v_fma_f32 v74, -v204, v48, v74
	v_fma_f32 v75, -v205, v49, v75
	v_fma_f32 v0, -v206, v50, v0
	v_fma_f32 v69, -v207, v51, v69
	ds_read_b128 v[204:207], v2 offset:14032
	s_waitcnt lgkmcnt(11)
	v_fma_f32 v74, -v208, v52, v74
	v_fma_f32 v75, -v209, v53, v75
	ds_read_b128 v[208:211], v2 offset:14048
	v_add_f32_e32 v74, v74, v75
	v_add_f32_e32 v0, v0, v69
	v_add_f32_e32 v54, v74, v0
	s_waitcnt lgkmcnt(11)
	v_fma_f32 v74, -v212, v4, v55
	v_fma_f32 v75, -v213, v5, 0
	v_fma_f32 v0, -v214, v6, 0
	v_fma_f32 v69, -v215, v7, 0
	ds_read_b128 v[212:215], v2 offset:14064
	s_waitcnt lgkmcnt(11)
	v_fma_f32 v74, -v216, v8, v74
	v_fma_f32 v75, -v217, v9, v75
	v_fma_f32 v0, -v218, v10, v0
	v_fma_f32 v69, -v219, v11, v69
	ds_read_b128 v[216:219], v2 offset:14144
	s_waitcnt lgkmcnt(11)
	v_fma_f32 v74, -v220, v12, v74
	v_fma_f32 v75, -v221, v13, v75
	v_fma_f32 v0, -v222, v14, v0
	v_fma_f32 v69, -v223, v15, v69
	ds_read_b128 v[220:223], v2 offset:14160
	s_waitcnt lgkmcnt(11)
	v_fma_f32 v74, -v224, v16, v74
	v_fma_f32 v75, -v225, v17, v75
	v_fma_f32 v0, -v226, v18, v0
	v_fma_f32 v69, -v227, v19, v69
	ds_read_b128 v[224:227], v2 offset:14176
	s_waitcnt lgkmcnt(11)
	v_fma_f32 v74, -v228, v20, v74
	v_fma_f32 v75, -v229, v21, v75
	v_fma_f32 v0, -v230, v22, v0
	v_fma_f32 v69, -v231, v23, v69
	ds_read_b128 v[228:231], v2 offset:14192
	s_waitcnt lgkmcnt(11)
	v_fma_f32 v74, -v232, v24, v74
	v_fma_f32 v75, -v233, v25, v75
	v_fma_f32 v0, -v234, v26, v0
	v_fma_f32 v69, -v235, v27, v69
	ds_read_b128 v[232:235], v2 offset:14208
	s_waitcnt lgkmcnt(11)
	v_fma_f32 v74, -v236, v28, v74
	v_fma_f32 v75, -v237, v29, v75
	v_fma_f32 v0, -v238, v30, v0
	v_fma_f32 v69, -v239, v31, v69
	ds_read_b128 v[236:239], v2 offset:14224
	s_waitcnt lgkmcnt(11)
	v_fma_f32 v74, -v240, v32, v74
	v_fma_f32 v75, -v241, v33, v75
	v_fma_f32 v0, -v242, v34, v0
	v_fma_f32 v69, -v243, v35, v69
	ds_read_b128 v[240:243], v2 offset:14240
	s_waitcnt lgkmcnt(11)
	v_fma_f32 v74, -v180, v36, v74
	v_fma_f32 v75, -v181, v37, v75
	v_fma_f32 v0, -v182, v38, v0
	v_fma_f32 v69, -v183, v39, v69
	ds_read_b128 v[180:183], v2 offset:14256
	s_waitcnt lgkmcnt(11)
	v_fma_f32 v74, -v70, v40, v74
	v_fma_f32 v75, -v71, v41, v75
	v_fma_f32 v0, -v72, v42, v0
	v_fma_f32 v69, -v73, v43, v69
	ds_read_b128 v[70:73], v2 offset:14272
	s_waitcnt lgkmcnt(11)
	v_fma_f32 v74, -v204, v44, v74
	v_fma_f32 v75, -v205, v45, v75
	v_fma_f32 v0, -v206, v46, v0
	v_fma_f32 v69, -v207, v47, v69
	ds_read_b128 v[204:207], v2 offset:14288
	s_waitcnt lgkmcnt(11)
	v_fma_f32 v74, -v208, v48, v74
	v_fma_f32 v75, -v209, v49, v75
	v_fma_f32 v0, -v210, v50, v0
	v_fma_f32 v69, -v211, v51, v69
	ds_read_b128 v[208:211], v2 offset:14304
	s_waitcnt lgkmcnt(11)
	v_fma_f32 v74, -v212, v52, v74
	v_fma_f32 v75, -v213, v53, v75
	v_fma_f32 v0, -v214, v54, v0
	ds_read_b128 v[212:215], v2 offset:14320
	v_add_f32_e32 v74, v74, v75
	v_add_f32_e32 v0, v0, v69
	v_add_f32_e32 v55, v74, v0
	s_waitcnt lgkmcnt(11)
	v_fma_f32 v74, -v216, v4, v56
	v_fma_f32 v75, -v217, v5, 0
	v_fma_f32 v0, -v218, v6, 0
	v_fma_f32 v69, -v219, v7, 0
	ds_read_b128 v[216:219], v2 offset:14336
	s_waitcnt lgkmcnt(11)
	v_fma_f32 v74, -v220, v8, v74
	v_fma_f32 v75, -v221, v9, v75
	v_fma_f32 v0, -v222, v10, v0
	v_fma_f32 v69, -v223, v11, v69
	ds_read_b128 v[220:223], v2 offset:14416
	s_waitcnt lgkmcnt(11)
	v_fma_f32 v74, -v224, v12, v74
	v_fma_f32 v75, -v225, v13, v75
	v_fma_f32 v0, -v226, v14, v0
	v_fma_f32 v69, -v227, v15, v69
	ds_read_b128 v[224:227], v2 offset:14432
	s_waitcnt lgkmcnt(11)
	v_fma_f32 v74, -v228, v16, v74
	v_fma_f32 v75, -v229, v17, v75
	v_fma_f32 v0, -v230, v18, v0
	v_fma_f32 v69, -v231, v19, v69
	ds_read_b128 v[228:231], v2 offset:14448
	s_waitcnt lgkmcnt(11)
	v_fma_f32 v74, -v232, v20, v74
	v_fma_f32 v75, -v233, v21, v75
	v_fma_f32 v0, -v234, v22, v0
	v_fma_f32 v69, -v235, v23, v69
	ds_read_b128 v[232:235], v2 offset:14464
	s_waitcnt lgkmcnt(11)
	v_fma_f32 v74, -v236, v24, v74
	v_fma_f32 v75, -v237, v25, v75
	v_fma_f32 v0, -v238, v26, v0
	v_fma_f32 v69, -v239, v27, v69
	ds_read_b128 v[236:239], v2 offset:14480
	s_waitcnt lgkmcnt(11)
	v_fma_f32 v74, -v240, v28, v74
	v_fma_f32 v75, -v241, v29, v75
	v_fma_f32 v0, -v242, v30, v0
	v_fma_f32 v69, -v243, v31, v69
	ds_read_b128 v[240:243], v2 offset:14496
	s_waitcnt lgkmcnt(11)
; #define LAS __attribute__((address_space(3)))
; __device__ __forceinline__ void gdn_prep_unit(const Args& c, int ug, int l, LAS unsigned char* lds) {
;     ...
;         for (int i = 1; i < 64; ++i) {
;             float s0 = x[i], s1 = 0.f, s2 = 0.f, s3 = 0.f;
; #pragma unroll
;             for (int m4 = 0; m4 < i; m4 += 4) {
;                 const f32x4 mv = *(const LAS f32x4*)(Mz + i * 68 + m4);
;                 s0 -= mv.x * x[m4];
;                 if (m4 + 1 < i) s1 -= mv.y * x[m4 + 1];
;                 if (m4 + 2 < i) s2 -= mv.z * x[m4 + 2];
;                 if (m4 + 3 < i) s3 -= mv.w * x[m4 + 3];
;             }
;             const float s = (s0 + s1) + (s2 + s3);
;             x[i] = s;
	v_fma_f32 v74, -v180, v32, v74
	v_fma_f32 v75, -v181, v33, v75
	v_fma_f32 v0, -v182, v34, v0
	v_fma_f32 v69, -v183, v35, v69
	ds_read_b128 v[180:183], v2 offset:14512
	s_waitcnt lgkmcnt(11)
	v_fma_f32 v74, -v70, v36, v74
	v_fma_f32 v75, -v71, v37, v75
	v_fma_f32 v0, -v72, v38, v0
	v_fma_f32 v69, -v73, v39, v69
	ds_read_b128 v[70:73], v2 offset:14528
	s_waitcnt lgkmcnt(11)
	v_fma_f32 v74, -v204, v40, v74
	v_fma_f32 v75, -v205, v41, v75
	v_fma_f32 v0, -v206, v42, v0
	v_fma_f32 v69, -v207, v43, v69
	ds_read_b128 v[204:207], v2 offset:14544
	s_waitcnt lgkmcnt(11)
	v_fma_f32 v74, -v208, v44, v74
	v_fma_f32 v75, -v209, v45, v75
	v_fma_f32 v0, -v210, v46, v0
	v_fma_f32 v69, -v211, v47, v69
	ds_read_b128 v[208:211], v2 offset:14560
	s_waitcnt lgkmcnt(11)
	v_fma_f32 v74, -v212, v48, v74
	v_fma_f32 v75, -v213, v49, v75
	v_fma_f32 v0, -v214, v50, v0
	v_fma_f32 v69, -v215, v51, v69
	ds_read_b128 v[212:215], v2 offset:14576
	s_waitcnt lgkmcnt(11)
	v_fma_f32 v74, -v216, v52, v74
	v_fma_f32 v75, -v217, v53, v75
	v_fma_f32 v0, -v218, v54, v0
	v_fma_f32 v69, -v219, v55, v69
	ds_read_b128 v[216:219], v2 offset:14592
	v_add_f32_e32 v74, v74, v75
	v_add_f32_e32 v0, v0, v69
	v_add_f32_e32 v56, v74, v0
	s_waitcnt lgkmcnt(11)
	v_fma_f32 v74, -v220, v4, v57
	v_fma_f32 v75, -v221, v5, 0
	v_fma_f32 v0, -v222, v6, 0
	v_fma_f32 v69, -v223, v7, 0
	ds_read_b128 v[220:223], v2 offset:14608
	s_waitcnt lgkmcnt(11)
	v_fma_f32 v74, -v224, v8, v74
	v_fma_f32 v75, -v225, v9, v75
	v_fma_f32 v0, -v226, v10, v0
	v_fma_f32 v69, -v227, v11, v69
	ds_read_b128 v[224:227], v2 offset:14624
	s_waitcnt lgkmcnt(11)
	v_fma_f32 v74, -v228, v12, v74
	v_fma_f32 v75, -v229, v13, v75
	v_fma_f32 v0, -v230, v14, v0
	v_fma_f32 v69, -v231, v15, v69
	ds_read_b128 v[228:231], v2 offset:14688
	s_waitcnt lgkmcnt(11)
	v_fma_f32 v74, -v232, v16, v74
	v_fma_f32 v75, -v233, v17, v75
	v_fma_f32 v0, -v234, v18, v0
	v_fma_f32 v69, -v235, v19, v69
	ds_read_b128 v[232:235], v2 offset:14704
	s_waitcnt lgkmcnt(11)
	v_fma_f32 v74, -v236, v20, v74
	v_fma_f32 v75, -v237, v21, v75
	v_fma_f32 v0, -v238, v22, v0
	v_fma_f32 v69, -v239, v23, v69
	ds_read_b128 v[236:239], v2 offset:14720
	s_waitcnt lgkmcnt(11)
	v_fma_f32 v74, -v240, v24, v74
	v_fma_f32 v75, -v241, v25, v75
	v_fma_f32 v0, -v242, v26, v0
	v_fma_f32 v69, -v243, v27, v69
	ds_read_b128 v[240:243], v2 offset:14736
	s_waitcnt lgkmcnt(11)
	v_fma_f32 v74, -v180, v28, v74
	v_fma_f32 v75, -v181, v29, v75
	v_fma_f32 v0, -v182, v30, v0
	v_fma_f32 v69, -v183, v31, v69
	ds_read_b128 v[180:183], v2 offset:14752
	s_waitcnt lgkmcnt(11)
	v_fma_f32 v74, -v70, v32, v74
	v_fma_f32 v75, -v71, v33, v75
	v_fma_f32 v0, -v72, v34, v0
	v_fma_f32 v69, -v73, v35, v69
	ds_read_b128 v[70:73], v2 offset:14768
	s_waitcnt lgkmcnt(11)
	v_fma_f32 v74, -v204, v36, v74
	v_fma_f32 v75, -v205, v37, v75
	v_fma_f32 v0, -v206, v38, v0
	v_fma_f32 v69, -v207, v39, v69
	ds_read_b128 v[204:207], v2 offset:14784
	s_waitcnt lgkmcnt(11)
	v_fma_f32 v74, -v208, v40, v74
	v_fma_f32 v75, -v209, v41, v75
	v_fma_f32 v0, -v210, v42, v0
	v_fma_f32 v69, -v211, v43, v69
	ds_read_b128 v[208:211], v2 offset:14800
	s_waitcnt lgkmcnt(11)
	v_fma_f32 v74, -v212, v44, v74
	v_fma_f32 v75, -v213, v45, v75
	v_fma_f32 v0, -v214, v46, v0
	v_fma_f32 v69, -v215, v47, v69
	ds_read_b128 v[212:215], v2 offset:14816
	s_waitcnt lgkmcnt(11)
	v_fma_f32 v74, -v216, v48, v74
	v_fma_f32 v75, -v217, v49, v75
	v_fma_f32 v0, -v218, v50, v0
	v_fma_f32 v69, -v219, v51, v69
	ds_read_b128 v[216:219], v2 offset:14832
	s_waitcnt lgkmcnt(11)
	v_fma_f32 v74, -v220, v52, v74
	v_fma_f32 v75, -v221, v53, v75
	v_fma_f32 v0, -v222, v54, v0
	v_fma_f32 v69, -v223, v55, v69
	ds_read_b128 v[220:223], v2 offset:14848
	s_waitcnt lgkmcnt(11)
	v_fma_f32 v74, -v224, v56, v74
	ds_read_b128 v[224:227], v2 offset:14864
	v_add_f32_e32 v74, v74, v75
	v_add_f32_e32 v0, v0, v69
	v_add_f32_e32 v57, v74, v0
	s_waitcnt lgkmcnt(11)
	v_fma_f32 v74, -v228, v4, v58
	v_fma_f32 v75, -v229, v5, 0
	v_fma_f32 v0, -v230, v6, 0
	v_fma_f32 v69, -v231, v7, 0
	ds_read_b128 v[228:231], v2 offset:14880
	s_waitcnt lgkmcnt(11)
	v_fma_f32 v74, -v232, v8, v74
	v_fma_f32 v75, -v233, v9, v75
	v_fma_f32 v0, -v234, v10, v0
	v_fma_f32 v69, -v235, v11, v69
	ds_read_b128 v[232:235], v2 offset:14896
	s_waitcnt lgkmcnt(11)
	v_fma_f32 v74, -v236, v12, v74
	v_fma_f32 v75, -v237, v13, v75
	v_fma_f32 v0, -v238, v14, v0
	v_fma_f32 v69, -v239, v15, v69
	ds_read_b128 v[236:239], v2 offset:14960
	s_waitcnt lgkmcnt(11)
	v_fma_f32 v74, -v240, v16, v74
	v_fma_f32 v75, -v241, v17, v75
	v_fma_f32 v0, -v242, v18, v0
	v_fma_f32 v69, -v243, v19, v69
	ds_read_b128 v[240:243], v2 offset:14976
	s_waitcnt lgkmcnt(11)
	v_fma_f32 v74, -v180, v20, v74
	v_fma_f32 v75, -v181, v21, v75
	v_fma_f32 v0, -v182, v22, v0
	v_fma_f32 v69, -v183, v23, v69
	ds_read_b128 v[180:183], v2 offset:14992
	s_waitcnt lgkmcnt(11)
	v_fma_f32 v74, -v70, v24, v74
	v_fma_f32 v75, -v71, v25, v75
	v_fma_f32 v0, -v72, v26, v0
	v_fma_f32 v69, -v73, v27, v69
	ds_read_b128 v[70:73], v2 offset:15008
	s_waitcnt lgkmcnt(11)
	v_fma_f32 v74, -v204, v28, v74
	v_fma_f32 v75, -v205, v29, v75
	v_fma_f32 v0, -v206, v30, v0
	v_fma_f32 v69, -v207, v31, v69
	ds_read_b128 v[204:207], v2 offset:15024
	s_waitcnt lgkmcnt(11)
	v_fma_f32 v74, -v208, v32, v74
	v_fma_f32 v75, -v209, v33, v75
	v_fma_f32 v0, -v210, v34, v0
	v_fma_f32 v69, -v211, v35, v69
	ds_read_b128 v[208:211], v2 offset:15040
	s_waitcnt lgkmcnt(11)
	v_fma_f32 v74, -v212, v36, v74
	v_fma_f32 v75, -v213, v37, v75
	v_fma_f32 v0, -v214, v38, v0
	v_fma_f32 v69, -v215, v39, v69
	ds_read_b128 v[212:215], v2 offset:15056
	s_waitcnt lgkmcnt(11)
; #define LAS __attribute__((address_space(3)))
; __device__ __forceinline__ void gdn_prep_unit(const Args& c, int ug, int l, LAS unsigned char* lds) {
;     ...
;         for (int i = 1; i < 64; ++i) {
;             float s0 = x[i], s1 = 0.f, s2 = 0.f, s3 = 0.f;
; #pragma unroll
;             for (int m4 = 0; m4 < i; m4 += 4) {
;                 const f32x4 mv = *(const LAS f32x4*)(Mz + i * 68 + m4);
;                 s0 -= mv.x * x[m4];
;                 if (m4 + 1 < i) s1 -= mv.y * x[m4 + 1];
;                 if (m4 + 2 < i) s2 -= mv.z * x[m4 + 2];
;                 if (m4 + 3 < i) s3 -= mv.w * x[m4 + 3];
;             }
;             const float s = (s0 + s1) + (s2 + s3);
;             x[i] = s;
	v_fma_f32 v74, -v216, v40, v74
	v_fma_f32 v75, -v217, v41, v75
	v_fma_f32 v0, -v218, v42, v0
	v_fma_f32 v69, -v219, v43, v69
	ds_read_b128 v[216:219], v2 offset:15072
	s_waitcnt lgkmcnt(11)
	v_fma_f32 v74, -v220, v44, v74
	v_fma_f32 v75, -v221, v45, v75
	v_fma_f32 v0, -v222, v46, v0
	v_fma_f32 v69, -v223, v47, v69
	ds_read_b128 v[220:223], v2 offset:15088
	s_waitcnt lgkmcnt(11)
	v_fma_f32 v74, -v224, v48, v74
	v_fma_f32 v75, -v225, v49, v75
	v_fma_f32 v0, -v226, v50, v0
	v_fma_f32 v69, -v227, v51, v69
	ds_read_b128 v[224:227], v2 offset:15104
	s_waitcnt lgkmcnt(11)
	v_fma_f32 v74, -v228, v52, v74
	v_fma_f32 v75, -v229, v53, v75
	v_fma_f32 v0, -v230, v54, v0
	v_fma_f32 v69, -v231, v55, v69
	ds_read_b128 v[228:231], v2 offset:15120
	s_waitcnt lgkmcnt(11)
	v_fma_f32 v74, -v232, v56, v74
	v_fma_f32 v75, -v233, v57, v75
	ds_read_b128 v[232:235], v2 offset:15136
	v_add_f32_e32 v74, v74, v75
	v_add_f32_e32 v0, v0, v69
	v_add_f32_e32 v58, v74, v0
	s_waitcnt lgkmcnt(11)
	v_fma_f32 v74, -v236, v4, v59
	v_fma_f32 v75, -v237, v5, 0
	v_fma_f32 v0, -v238, v6, 0
	v_fma_f32 v69, -v239, v7, 0
	ds_read_b128 v[236:239], v2 offset:15152
	s_waitcnt lgkmcnt(11)
	v_fma_f32 v74, -v240, v8, v74
	v_fma_f32 v75, -v241, v9, v75
	v_fma_f32 v0, -v242, v10, v0
	v_fma_f32 v69, -v243, v11, v69
	ds_read_b128 v[240:243], v2 offset:15168
	s_waitcnt lgkmcnt(11)
	v_fma_f32 v74, -v180, v12, v74
	v_fma_f32 v75, -v181, v13, v75
	v_fma_f32 v0, -v182, v14, v0
	v_fma_f32 v69, -v183, v15, v69
	ds_read_b128 v[180:183], v2 offset:15232
	s_waitcnt lgkmcnt(11)
	v_fma_f32 v74, -v70, v16, v74
	v_fma_f32 v75, -v71, v17, v75
	v_fma_f32 v0, -v72, v18, v0
	v_fma_f32 v69, -v73, v19, v69
	ds_read_b128 v[70:73], v2 offset:15248
	s_waitcnt lgkmcnt(11)
	v_fma_f32 v74, -v204, v20, v74
	v_fma_f32 v75, -v205, v21, v75
	v_fma_f32 v0, -v206, v22, v0
	v_fma_f32 v69, -v207, v23, v69
	ds_read_b128 v[204:207], v2 offset:15264
	s_waitcnt lgkmcnt(11)
	v_fma_f32 v74, -v208, v24, v74
	v_fma_f32 v75, -v209, v25, v75
	v_fma_f32 v0, -v210, v26, v0
	v_fma_f32 v69, -v211, v27, v69
	ds_read_b128 v[208:211], v2 offset:15280
	s_waitcnt lgkmcnt(11)
	v_fma_f32 v74, -v212, v28, v74
	v_fma_f32 v75, -v213, v29, v75
	v_fma_f32 v0, -v214, v30, v0
	v_fma_f32 v69, -v215, v31, v69
	ds_read_b128 v[212:215], v2 offset:15296
	s_waitcnt lgkmcnt(11)
	v_fma_f32 v74, -v216, v32, v74
	v_fma_f32 v75, -v217, v33, v75
	v_fma_f32 v0, -v218, v34, v0
	v_fma_f32 v69, -v219, v35, v69
	ds_read_b128 v[216:219], v2 offset:15312
	s_waitcnt lgkmcnt(11)
	v_fma_f32 v74, -v220, v36, v74
	v_fma_f32 v75, -v221, v37, v75
	v_fma_f32 v0, -v222, v38, v0
	v_fma_f32 v69, -v223, v39, v69
	ds_read_b128 v[220:223], v2 offset:15328
	s_waitcnt lgkmcnt(11)
	v_fma_f32 v74, -v224, v40, v74
	v_fma_f32 v75, -v225, v41, v75
	v_fma_f32 v0, -v226, v42, v0
	v_fma_f32 v69, -v227, v43, v69
	ds_read_b128 v[224:227], v2 offset:15344
	s_waitcnt lgkmcnt(11)
	v_fma_f32 v74, -v228, v44, v74
	v_fma_f32 v75, -v229, v45, v75
	v_fma_f32 v0, -v230, v46, v0
	v_fma_f32 v69, -v231, v47, v69
	ds_read_b128 v[228:231], v2 offset:15360
	s_waitcnt lgkmcnt(11)
	v_fma_f32 v74, -v232, v48, v74
	v_fma_f32 v75, -v233, v49, v75
	v_fma_f32 v0, -v234, v50, v0
	v_fma_f32 v69, -v235, v51, v69
	ds_read_b128 v[232:235], v2 offset:15376
	s_waitcnt lgkmcnt(11)
	v_fma_f32 v74, -v236, v52, v74
	v_fma_f32 v75, -v237, v53, v75
	v_fma_f32 v0, -v238, v54, v0
	v_fma_f32 v69, -v239, v55, v69
	ds_read_b128 v[236:239], v2 offset:15392
	s_waitcnt lgkmcnt(11)
	v_fma_f32 v74, -v240, v56, v74
	v_fma_f32 v75, -v241, v57, v75
	v_fma_f32 v0, -v242, v58, v0
	ds_read_b128 v[240:243], v2 offset:15408
	v_add_f32_e32 v74, v74, v75
	v_add_f32_e32 v0, v0, v69
	v_add_f32_e32 v59, v74, v0
	s_waitcnt lgkmcnt(11)
	v_fma_f32 v74, -v180, v4, v60
	v_fma_f32 v75, -v181, v5, 0
	v_fma_f32 v0, -v182, v6, 0
	v_fma_f32 v69, -v183, v7, 0
	ds_read_b128 v[180:183], v2 offset:15424
	s_waitcnt lgkmcnt(11)
	v_fma_f32 v74, -v70, v8, v74
	v_fma_f32 v75, -v71, v9, v75
	v_fma_f32 v0, -v72, v10, v0
	v_fma_f32 v69, -v73, v11, v69
	ds_read_b128 v[70:73], v2 offset:15440
	s_waitcnt lgkmcnt(11)
	v_fma_f32 v74, -v204, v12, v74
	v_fma_f32 v75, -v205, v13, v75
	v_fma_f32 v0, -v206, v14, v0
	v_fma_f32 v69, -v207, v15, v69
	ds_read_b128 v[204:207], v2 offset:15504
	s_waitcnt lgkmcnt(11)
	v_fma_f32 v74, -v208, v16, v74
	v_fma_f32 v75, -v209, v17, v75
	v_fma_f32 v0, -v210, v18, v0
	v_fma_f32 v69, -v211, v19, v69
	ds_read_b128 v[208:211], v2 offset:15520
	s_waitcnt lgkmcnt(11)
	v_fma_f32 v74, -v212, v20, v74
	v_fma_f32 v75, -v213, v21, v75
	v_fma_f32 v0, -v214, v22, v0
	v_fma_f32 v69, -v215, v23, v69
	ds_read_b128 v[212:215], v2 offset:15536
	s_waitcnt lgkmcnt(11)
	v_fma_f32 v74, -v216, v24, v74
	v_fma_f32 v75, -v217, v25, v75
	v_fma_f32 v0, -v218, v26, v0
	v_fma_f32 v69, -v219, v27, v69
	ds_read_b128 v[216:219], v2 offset:15552
	s_waitcnt lgkmcnt(11)
	v_fma_f32 v74, -v220, v28, v74
	v_fma_f32 v75, -v221, v29, v75
	v_fma_f32 v0, -v222, v30, v0
	v_fma_f32 v69, -v223, v31, v69
	ds_read_b128 v[220:223], v2 offset:15568
	s_waitcnt lgkmcnt(11)
	v_fma_f32 v74, -v224, v32, v74
	v_fma_f32 v75, -v225, v33, v75
	v_fma_f32 v0, -v226, v34, v0
	v_fma_f32 v69, -v227, v35, v69
	ds_read_b128 v[224:227], v2 offset:15584
	s_waitcnt lgkmcnt(11)
	v_fma_f32 v74, -v228, v36, v74
	v_fma_f32 v75, -v229, v37, v75
	v_fma_f32 v0, -v230, v38, v0
	v_fma_f32 v69, -v231, v39, v69
	ds_read_b128 v[228:231], v2 offset:15600
	s_waitcnt lgkmcnt(11)
	v_fma_f32 v74, -v232, v40, v74
	v_fma_f32 v75, -v233, v41, v75
	v_fma_f32 v0, -v234, v42, v0
	v_fma_f32 v69, -v235, v43, v69
	ds_read_b128 v[232:235], v2 offset:15616
	s_waitcnt lgkmcnt(11)
; #define LAS __attribute__((address_space(3)))
; __device__ __forceinline__ void gdn_prep_unit(const Args& c, int ug, int l, LAS unsigned char* lds) {
;     ...
;         for (int i = 1; i < 64; ++i) {
;             float s0 = x[i], s1 = 0.f, s2 = 0.f, s3 = 0.f;
; #pragma unroll
;             for (int m4 = 0; m4 < i; m4 += 4) {
;                 const f32x4 mv = *(const LAS f32x4*)(Mz + i * 68 + m4);
;                 s0 -= mv.x * x[m4];
;                 if (m4 + 1 < i) s1 -= mv.y * x[m4 + 1];
;                 if (m4 + 2 < i) s2 -= mv.z * x[m4 + 2];
;                 if (m4 + 3 < i) s3 -= mv.w * x[m4 + 3];
;             }
;             const float s = (s0 + s1) + (s2 + s3);
;             x[i] = s;
	v_fma_f32 v74, -v236, v44, v74
	v_fma_f32 v75, -v237, v45, v75
	v_fma_f32 v0, -v238, v46, v0
	v_fma_f32 v69, -v239, v47, v69
	ds_read_b128 v[236:239], v2 offset:15632
	s_waitcnt lgkmcnt(11)
	v_fma_f32 v74, -v240, v48, v74
	v_fma_f32 v75, -v241, v49, v75
	v_fma_f32 v0, -v242, v50, v0
	v_fma_f32 v69, -v243, v51, v69
	ds_read_b128 v[240:243], v2 offset:15648
	s_waitcnt lgkmcnt(11)
	v_fma_f32 v74, -v180, v52, v74
	v_fma_f32 v75, -v181, v53, v75
	v_fma_f32 v0, -v182, v54, v0
	v_fma_f32 v69, -v183, v55, v69
	ds_read_b128 v[180:183], v2 offset:15664
	s_waitcnt lgkmcnt(11)
	v_fma_f32 v74, -v70, v56, v74
	v_fma_f32 v75, -v71, v57, v75
	v_fma_f32 v0, -v72, v58, v0
	v_fma_f32 v69, -v73, v59, v69
	ds_read_b128 v[70:73], v2 offset:15680
	v_add_f32_e32 v74, v74, v75
	v_add_f32_e32 v0, v0, v69
	v_add_f32_e32 v60, v74, v0
	s_waitcnt lgkmcnt(11)
	v_fma_f32 v74, -v204, v4, v61
	v_fma_f32 v75, -v205, v5, 0
	v_fma_f32 v0, -v206, v6, 0
	v_fma_f32 v69, -v207, v7, 0
	ds_read_b128 v[204:207], v2 offset:15696
	s_waitcnt lgkmcnt(11)
	v_fma_f32 v74, -v208, v8, v74
	v_fma_f32 v75, -v209, v9, v75
	v_fma_f32 v0, -v210, v10, v0
	v_fma_f32 v69, -v211, v11, v69
	ds_read_b128 v[208:211], v2 offset:15712
	s_waitcnt lgkmcnt(11)
	v_fma_f32 v74, -v212, v12, v74
	v_fma_f32 v75, -v213, v13, v75
	v_fma_f32 v0, -v214, v14, v0
	v_fma_f32 v69, -v215, v15, v69
	ds_read_b128 v[212:215], v2 offset:15728
	s_waitcnt lgkmcnt(11)
	v_fma_f32 v74, -v216, v16, v74
	v_fma_f32 v75, -v217, v17, v75
	v_fma_f32 v0, -v218, v18, v0
	v_fma_f32 v69, -v219, v19, v69
	ds_read_b128 v[216:219], v2 offset:15776
	s_waitcnt lgkmcnt(11)
	v_fma_f32 v74, -v220, v20, v74
	v_fma_f32 v75, -v221, v21, v75
	v_fma_f32 v0, -v222, v22, v0
	v_fma_f32 v69, -v223, v23, v69
	ds_read_b128 v[220:223], v2 offset:15792
	s_waitcnt lgkmcnt(11)
	v_fma_f32 v74, -v224, v24, v74
	v_fma_f32 v75, -v225, v25, v75
	v_fma_f32 v0, -v226, v26, v0
	v_fma_f32 v69, -v227, v27, v69
	ds_read_b128 v[224:227], v2 offset:15808
	s_waitcnt lgkmcnt(11)
	v_fma_f32 v74, -v228, v28, v74
	v_fma_f32 v75, -v229, v29, v75
	v_fma_f32 v0, -v230, v30, v0
	v_fma_f32 v69, -v231, v31, v69
	ds_read_b128 v[228:231], v2 offset:15824
	s_waitcnt lgkmcnt(11)
	v_fma_f32 v74, -v232, v32, v74
	v_fma_f32 v75, -v233, v33, v75
	v_fma_f32 v0, -v234, v34, v0
	v_fma_f32 v69, -v235, v35, v69
	ds_read_b128 v[232:235], v2 offset:15840
	s_waitcnt lgkmcnt(11)
	v_fma_f32 v74, -v236, v36, v74
	v_fma_f32 v75, -v237, v37, v75
	v_fma_f32 v0, -v238, v38, v0
	v_fma_f32 v69, -v239, v39, v69
	ds_read_b128 v[236:239], v2 offset:15856
	s_waitcnt lgkmcnt(11)
	v_fma_f32 v74, -v240, v40, v74
	v_fma_f32 v75, -v241, v41, v75
	v_fma_f32 v0, -v242, v42, v0
	v_fma_f32 v69, -v243, v43, v69
	ds_read_b128 v[240:243], v2 offset:15872
	s_waitcnt lgkmcnt(11)
	v_fma_f32 v74, -v180, v44, v74
	v_fma_f32 v75, -v181, v45, v75
	v_fma_f32 v0, -v182, v46, v0
	v_fma_f32 v69, -v183, v47, v69
	ds_read_b128 v[180:183], v2 offset:15888
	s_waitcnt lgkmcnt(11)
	v_fma_f32 v74, -v70, v48, v74
	v_fma_f32 v75, -v71, v49, v75
	v_fma_f32 v0, -v72, v50, v0
	v_fma_f32 v69, -v73, v51, v69
	ds_read_b128 v[70:73], v2 offset:15904
	s_waitcnt lgkmcnt(11)
	v_fma_f32 v74, -v204, v52, v74
	v_fma_f32 v75, -v205, v53, v75
	v_fma_f32 v0, -v206, v54, v0
	v_fma_f32 v69, -v207, v55, v69
	ds_read_b128 v[204:207], v2 offset:15920
	s_waitcnt lgkmcnt(11)
	v_fma_f32 v74, -v208, v56, v74
	v_fma_f32 v75, -v209, v57, v75
	v_fma_f32 v0, -v210, v58, v0
	v_fma_f32 v69, -v211, v59, v69
	ds_read_b128 v[208:211], v2 offset:15936
	s_waitcnt lgkmcnt(11)
	v_fma_f32 v74, -v212, v60, v74
	ds_read_b128 v[212:215], v2 offset:15952
	v_add_f32_e32 v74, v74, v75
	v_add_f32_e32 v0, v0, v69
	v_add_f32_e32 v61, v74, v0
	s_waitcnt lgkmcnt(11)
	v_fma_f32 v74, -v216, v4, v62
	v_fma_f32 v75, -v217, v5, 0
	v_fma_f32 v0, -v218, v6, 0
	v_fma_f32 v69, -v219, v7, 0
	ds_read_b128 v[216:219], v2 offset:15968
	s_waitcnt lgkmcnt(11)
	v_fma_f32 v74, -v220, v8, v74
	v_fma_f32 v75, -v221, v9, v75
	v_fma_f32 v0, -v222, v10, v0
	v_fma_f32 v69, -v223, v11, v69
	ds_read_b128 v[220:223], v2 offset:15984
	s_waitcnt lgkmcnt(11)
	v_fma_f32 v74, -v224, v12, v74
	v_fma_f32 v75, -v225, v13, v75
	v_fma_f32 v0, -v226, v14, v0
	v_fma_f32 v69, -v227, v15, v69
	ds_read_b128 v[224:227], v2 offset:16000
	s_waitcnt lgkmcnt(11)
	v_fma_f32 v74, -v228, v16, v74
	v_fma_f32 v75, -v229, v17, v75
	v_fma_f32 v0, -v230, v18, v0
	v_fma_f32 v69, -v231, v19, v69
	ds_read_b128 v[228:231], v2 offset:16048
	s_waitcnt lgkmcnt(11)
	v_fma_f32 v74, -v232, v20, v74
	v_fma_f32 v75, -v233, v21, v75
	v_fma_f32 v0, -v234, v22, v0
	v_fma_f32 v69, -v235, v23, v69
	ds_read_b128 v[232:235], v2 offset:16064
	s_waitcnt lgkmcnt(11)
	v_fma_f32 v74, -v236, v24, v74
	v_fma_f32 v75, -v237, v25, v75
	v_fma_f32 v0, -v238, v26, v0
	v_fma_f32 v69, -v239, v27, v69
	ds_read_b128 v[236:239], v2 offset:16080
	s_waitcnt lgkmcnt(11)
	v_fma_f32 v74, -v240, v28, v74
	v_fma_f32 v75, -v241, v29, v75
	v_fma_f32 v0, -v242, v30, v0
	v_fma_f32 v69, -v243, v31, v69
	ds_read_b128 v[240:243], v2 offset:16096
	s_waitcnt lgkmcnt(11)
	v_fma_f32 v74, -v180, v32, v74
	v_fma_f32 v75, -v181, v33, v75
	v_fma_f32 v0, -v182, v34, v0
	v_fma_f32 v69, -v183, v35, v69
	ds_read_b128 v[180:183], v2 offset:16112
	s_waitcnt lgkmcnt(11)
	v_fma_f32 v74, -v70, v36, v74
	v_fma_f32 v75, -v71, v37, v75
	v_fma_f32 v0, -v72, v38, v0
	v_fma_f32 v69, -v73, v39, v69
	ds_read_b128 v[70:73], v2 offset:16128
	s_waitcnt lgkmcnt(11)
	v_fma_f32 v74, -v204, v40, v74
	v_fma_f32 v75, -v205, v41, v75
	v_fma_f32 v0, -v206, v42, v0
	v_fma_f32 v69, -v207, v43, v69
	ds_read_b128 v[204:207], v2 offset:16144
	s_waitcnt lgkmcnt(11)
; #define LAS __attribute__((address_space(3)))
; __device__ __forceinline__ void gdn_prep_unit(const Args& c, int ug, int l, LAS unsigned char* lds) {
;     ...
;         for (int i = 1; i < 64; ++i) {
;             float s0 = x[i], s1 = 0.f, s2 = 0.f, s3 = 0.f;
; #pragma unroll
;             for (int m4 = 0; m4 < i; m4 += 4) {
;                 const f32x4 mv = *(const LAS f32x4*)(Mz + i * 68 + m4);
;                 s0 -= mv.x * x[m4];
;                 if (m4 + 1 < i) s1 -= mv.y * x[m4 + 1];
;                 if (m4 + 2 < i) s2 -= mv.z * x[m4 + 2];
;                 if (m4 + 3 < i) s3 -= mv.w * x[m4 + 3];
;             }
;             const float s = (s0 + s1) + (s2 + s3);
;             x[i] = s;
	v_fma_f32 v74, -v208, v44, v74
	v_fma_f32 v75, -v209, v45, v75
	v_fma_f32 v0, -v210, v46, v0
	v_fma_f32 v69, -v211, v47, v69
	ds_read_b128 v[208:211], v2 offset:16160
	s_waitcnt lgkmcnt(11)
	v_fma_f32 v74, -v212, v48, v74
	v_fma_f32 v75, -v213, v49, v75
	v_fma_f32 v0, -v214, v50, v0
	v_fma_f32 v69, -v215, v51, v69
	ds_read_b128 v[212:215], v2 offset:16176
	s_waitcnt lgkmcnt(11)
	v_fma_f32 v74, -v216, v52, v74
	v_fma_f32 v75, -v217, v53, v75
	v_fma_f32 v0, -v218, v54, v0
	v_fma_f32 v69, -v219, v55, v69
	ds_read_b128 v[216:219], v2 offset:16192
	s_waitcnt lgkmcnt(11)
	v_fma_f32 v74, -v220, v56, v74
	v_fma_f32 v75, -v221, v57, v75
	v_fma_f32 v0, -v222, v58, v0
	v_fma_f32 v69, -v223, v59, v69
	ds_read_b128 v[220:223], v2 offset:16208
	s_waitcnt lgkmcnt(11)
	v_fma_f32 v74, -v224, v60, v74
	v_fma_f32 v75, -v225, v61, v75
	ds_read_b128 v[224:227], v2 offset:16224
	v_add_f32_e32 v74, v74, v75
	v_add_f32_e32 v0, v0, v69
	v_add_f32_e32 v62, v74, v0
	s_waitcnt lgkmcnt(11)
	v_fma_f32 v74, -v228, v4, v63
	v_fma_f32 v75, -v229, v5, 0
	v_fma_f32 v0, -v230, v6, 0
	v_fma_f32 v69, -v231, v7, 0
	ds_read_b128 v[228:231], v2 offset:16240
	s_waitcnt lgkmcnt(11)
	v_fma_f32 v74, -v232, v8, v74
	v_fma_f32 v75, -v233, v9, v75
	v_fma_f32 v0, -v234, v10, v0
	v_fma_f32 v69, -v235, v11, v69
	ds_read_b128 v[232:235], v2 offset:16256
	s_waitcnt lgkmcnt(11)
	v_fma_f32 v74, -v236, v12, v74
	v_fma_f32 v75, -v237, v13, v75
	v_fma_f32 v0, -v238, v14, v0
	v_fma_f32 v69, -v239, v15, v69
	ds_read_b128 v[236:239], v2 offset:16272
	s_waitcnt lgkmcnt(11)
	v_fma_f32 v74, -v240, v16, v74
	v_fma_f32 v75, -v241, v17, v75
	v_fma_f32 v0, -v242, v18, v0
	v_fma_f32 v69, -v243, v19, v69
	ds_read_b128 v[240:243], v2 offset:16320
	s_waitcnt lgkmcnt(11)
	v_fma_f32 v74, -v180, v20, v74
	v_fma_f32 v75, -v181, v21, v75
	v_fma_f32 v0, -v182, v22, v0
	v_fma_f32 v69, -v183, v23, v69
	ds_read_b128 v[180:183], v2 offset:16336
	s_waitcnt lgkmcnt(11)
	v_fma_f32 v74, -v70, v24, v74
	v_fma_f32 v75, -v71, v25, v75
	v_fma_f32 v0, -v72, v26, v0
	v_fma_f32 v69, -v73, v27, v69
	ds_read_b128 v[70:73], v2 offset:16352
	s_waitcnt lgkmcnt(11)
	v_fma_f32 v74, -v204, v28, v74
	v_fma_f32 v75, -v205, v29, v75
	v_fma_f32 v0, -v206, v30, v0
	v_fma_f32 v69, -v207, v31, v69
	ds_read_b128 v[204:207], v2 offset:16368
	s_waitcnt lgkmcnt(11)
	v_fma_f32 v74, -v208, v32, v74
	v_fma_f32 v75, -v209, v33, v75
	v_fma_f32 v0, -v210, v34, v0
	v_fma_f32 v69, -v211, v35, v69
	ds_read_b128 v[208:211], v2 offset:16384
	s_waitcnt lgkmcnt(11)
	v_fma_f32 v74, -v212, v36, v74
	v_fma_f32 v75, -v213, v37, v75
	v_fma_f32 v0, -v214, v38, v0
	v_fma_f32 v69, -v215, v39, v69
	ds_read_b128 v[212:215], v2 offset:16400
	s_waitcnt lgkmcnt(11)
	v_fma_f32 v74, -v216, v40, v74
	v_fma_f32 v75, -v217, v41, v75
	v_fma_f32 v0, -v218, v42, v0
	v_fma_f32 v69, -v219, v43, v69
	ds_read_b128 v[216:219], v2 offset:16416
	s_waitcnt lgkmcnt(11)
	v_fma_f32 v74, -v220, v44, v74
	v_fma_f32 v75, -v221, v45, v75
	v_fma_f32 v0, -v222, v46, v0
	v_fma_f32 v69, -v223, v47, v69
	ds_read_b128 v[220:223], v2 offset:16432
	s_waitcnt lgkmcnt(11)
	v_fma_f32 v74, -v224, v48, v74
	v_fma_f32 v75, -v225, v49, v75
	v_fma_f32 v0, -v226, v50, v0
	v_fma_f32 v69, -v227, v51, v69
	ds_read_b128 v[224:227], v2 offset:16448
	s_waitcnt lgkmcnt(11)
	v_fma_f32 v74, -v228, v52, v74
	v_fma_f32 v75, -v229, v53, v75
	v_fma_f32 v0, -v230, v54, v0
	v_fma_f32 v69, -v231, v55, v69
	ds_read_b128 v[228:231], v2 offset:16464
	s_waitcnt lgkmcnt(11)
	v_fma_f32 v74, -v232, v56, v74
	v_fma_f32 v75, -v233, v57, v75
	v_fma_f32 v0, -v234, v58, v0
	v_fma_f32 v69, -v235, v59, v69
	ds_read_b128 v[232:235], v2 offset:16480
	s_waitcnt lgkmcnt(11)
	v_fma_f32 v74, -v236, v60, v74
	v_fma_f32 v75, -v237, v61, v75
	v_fma_f32 v0, -v238, v62, v0
	ds_read_b128 v[236:239], v2 offset:16496
	v_add_f32_e32 v74, v74, v75
	v_add_f32_e32 v0, v0, v69
	v_add_f32_e32 v63, v74, v0
	s_waitcnt lgkmcnt(11)
	v_fma_f32 v74, -v240, v4, v64
	v_fma_f32 v75, -v241, v5, 0
	v_fma_f32 v0, -v242, v6, 0
	v_fma_f32 v69, -v243, v7, 0
	ds_read_b128 v[240:243], v2 offset:16512
	s_waitcnt lgkmcnt(11)
	v_fma_f32 v74, -v180, v8, v74
	v_fma_f32 v75, -v181, v9, v75
	v_fma_f32 v0, -v182, v10, v0
	v_fma_f32 v69, -v183, v11, v69
	ds_read_b128 v[180:183], v2 offset:16528
	s_waitcnt lgkmcnt(11)
	v_fma_f32 v74, -v70, v12, v74
	v_fma_f32 v75, -v71, v13, v75
	v_fma_f32 v0, -v72, v14, v0
	v_fma_f32 v69, -v73, v15, v69
	ds_read_b128 v[70:73], v2 offset:16544
	s_waitcnt lgkmcnt(11)
	v_fma_f32 v74, -v204, v16, v74
	v_fma_f32 v75, -v205, v17, v75
	v_fma_f32 v0, -v206, v18, v0
	v_fma_f32 v69, -v207, v19, v69
	ds_read_b128 v[204:207], v2 offset:16592
	s_waitcnt lgkmcnt(11)
	v_fma_f32 v74, -v208, v20, v74
	v_fma_f32 v75, -v209, v21, v75
	v_fma_f32 v0, -v210, v22, v0
	v_fma_f32 v69, -v211, v23, v69
	ds_read_b128 v[208:211], v2 offset:16608
	s_waitcnt lgkmcnt(11)
	v_fma_f32 v74, -v212, v24, v74
	v_fma_f32 v75, -v213, v25, v75
	v_fma_f32 v0, -v214, v26, v0
	v_fma_f32 v69, -v215, v27, v69
	ds_read_b128 v[212:215], v2 offset:16624
	s_waitcnt lgkmcnt(11)
	v_fma_f32 v74, -v216, v28, v74
	v_fma_f32 v75, -v217, v29, v75
	v_fma_f32 v0, -v218, v30, v0
	v_fma_f32 v69, -v219, v31, v69
	ds_read_b128 v[216:219], v2 offset:16640
	s_waitcnt lgkmcnt(11)
	v_fma_f32 v74, -v220, v32, v74
	v_fma_f32 v75, -v221, v33, v75
	v_fma_f32 v0, -v222, v34, v0
	v_fma_f32 v69, -v223, v35, v69
	ds_read_b128 v[220:223], v2 offset:16656
	s_waitcnt lgkmcnt(11)
	v_fma_f32 v74, -v224, v36, v74
	v_fma_f32 v75, -v225, v37, v75
	v_fma_f32 v0, -v226, v38, v0
	v_fma_f32 v69, -v227, v39, v69
	ds_read_b128 v[224:227], v2 offset:16672
	s_waitcnt lgkmcnt(11)
; #define LAS __attribute__((address_space(3)))
; __device__ __forceinline__ void gdn_prep_unit(const Args& c, int ug, int l, LAS unsigned char* lds) {
;     ...
;         for (int i = 1; i < 64; ++i) {
;             float s0 = x[i], s1 = 0.f, s2 = 0.f, s3 = 0.f;
; #pragma unroll
;             for (int m4 = 0; m4 < i; m4 += 4) {
;                 const f32x4 mv = *(const LAS f32x4*)(Mz + i * 68 + m4);
;                 s0 -= mv.x * x[m4];
;                 if (m4 + 1 < i) s1 -= mv.y * x[m4 + 1];
;                 if (m4 + 2 < i) s2 -= mv.z * x[m4 + 2];
;                 if (m4 + 3 < i) s3 -= mv.w * x[m4 + 3];
;             }
;             const float s = (s0 + s1) + (s2 + s3);
;             x[i] = s;
	v_fma_f32 v74, -v228, v40, v74
	v_fma_f32 v75, -v229, v41, v75
	v_fma_f32 v0, -v230, v42, v0
	v_fma_f32 v69, -v231, v43, v69
	ds_read_b128 v[228:231], v2 offset:16688
	s_waitcnt lgkmcnt(11)
	v_fma_f32 v74, -v232, v44, v74
	v_fma_f32 v75, -v233, v45, v75
	v_fma_f32 v0, -v234, v46, v0
	v_fma_f32 v69, -v235, v47, v69
	ds_read_b128 v[232:235], v2 offset:16704
	s_waitcnt lgkmcnt(11)
	v_fma_f32 v74, -v236, v48, v74
	v_fma_f32 v75, -v237, v49, v75
	v_fma_f32 v0, -v238, v50, v0
	v_fma_f32 v69, -v239, v51, v69
	ds_read_b128 v[236:239], v2 offset:16720
	s_waitcnt lgkmcnt(11)
	v_fma_f32 v74, -v240, v52, v74
	v_fma_f32 v75, -v241, v53, v75
	v_fma_f32 v0, -v242, v54, v0
	v_fma_f32 v69, -v243, v55, v69
	ds_read_b128 v[240:243], v2 offset:16736
	s_waitcnt lgkmcnt(11)
	v_fma_f32 v74, -v180, v56, v74
	v_fma_f32 v75, -v181, v57, v75
	v_fma_f32 v0, -v182, v58, v0
	v_fma_f32 v69, -v183, v59, v69
	ds_read_b128 v[180:183], v2 offset:16752
	s_waitcnt lgkmcnt(11)
	v_fma_f32 v74, -v70, v60, v74
	v_fma_f32 v75, -v71, v61, v75
	v_fma_f32 v0, -v72, v62, v0
	v_fma_f32 v69, -v73, v63, v69
	ds_read_b128 v[70:73], v2 offset:16768
	v_add_f32_e32 v74, v74, v75
	v_add_f32_e32 v0, v0, v69
	v_add_f32_e32 v64, v74, v0
	s_waitcnt lgkmcnt(11)
	v_fma_f32 v74, -v204, v4, v65
	v_fma_f32 v75, -v205, v5, 0
	v_fma_f32 v0, -v206, v6, 0
	v_fma_f32 v69, -v207, v7, 0
	ds_read_b128 v[204:207], v2 offset:16784
	s_waitcnt lgkmcnt(11)
	v_fma_f32 v74, -v208, v8, v74
	v_fma_f32 v75, -v209, v9, v75
	v_fma_f32 v0, -v210, v10, v0
	v_fma_f32 v69, -v211, v11, v69
	ds_read_b128 v[208:211], v2 offset:16800
	s_waitcnt lgkmcnt(11)
	v_fma_f32 v74, -v212, v12, v74
	v_fma_f32 v75, -v213, v13, v75
	v_fma_f32 v0, -v214, v14, v0
	v_fma_f32 v69, -v215, v15, v69
	ds_read_b128 v[212:215], v2 offset:16816
	s_waitcnt lgkmcnt(11)
	v_fma_f32 v74, -v216, v16, v74
	v_fma_f32 v75, -v217, v17, v75
	v_fma_f32 v0, -v218, v18, v0
	v_fma_f32 v69, -v219, v19, v69
	ds_read_b128 v[216:219], v2 offset:16832
	s_waitcnt lgkmcnt(11)
	v_fma_f32 v74, -v220, v20, v74
	v_fma_f32 v75, -v221, v21, v75
	v_fma_f32 v0, -v222, v22, v0
	v_fma_f32 v69, -v223, v23, v69
	ds_read_b128 v[220:223], v2 offset:16864
	s_waitcnt lgkmcnt(11)
	v_fma_f32 v74, -v224, v24, v74
	v_fma_f32 v75, -v225, v25, v75
	v_fma_f32 v0, -v226, v26, v0
	v_fma_f32 v69, -v227, v27, v69
	ds_read_b128 v[224:227], v2 offset:16880
	s_waitcnt lgkmcnt(11)
	v_fma_f32 v74, -v228, v28, v74
	v_fma_f32 v75, -v229, v29, v75
	v_fma_f32 v0, -v230, v30, v0
	v_fma_f32 v69, -v231, v31, v69
	ds_read_b128 v[228:231], v2 offset:16896
	s_waitcnt lgkmcnt(11)
	v_fma_f32 v74, -v232, v32, v74
	v_fma_f32 v75, -v233, v33, v75
	v_fma_f32 v0, -v234, v34, v0
	v_fma_f32 v69, -v235, v35, v69
	ds_read_b128 v[232:235], v2 offset:16912
	s_waitcnt lgkmcnt(11)
	v_fma_f32 v74, -v236, v36, v74
	v_fma_f32 v75, -v237, v37, v75
	v_fma_f32 v0, -v238, v38, v0
	v_fma_f32 v69, -v239, v39, v69
	ds_read_b128 v[236:239], v2 offset:16928
	s_waitcnt lgkmcnt(11)
	v_fma_f32 v74, -v240, v40, v74
	v_fma_f32 v75, -v241, v41, v75
	v_fma_f32 v0, -v242, v42, v0
	v_fma_f32 v69, -v243, v43, v69
	ds_read_b128 v[240:243], v2 offset:16944
	s_waitcnt lgkmcnt(11)
	v_fma_f32 v74, -v180, v44, v74
	v_fma_f32 v75, -v181, v45, v75
	v_fma_f32 v0, -v182, v46, v0
	v_fma_f32 v69, -v183, v47, v69
	ds_read_b128 v[180:183], v2 offset:16960
	s_waitcnt lgkmcnt(11)
	v_fma_f32 v74, -v70, v48, v74
	v_fma_f32 v75, -v71, v49, v75
	v_fma_f32 v0, -v72, v50, v0
	v_fma_f32 v69, -v73, v51, v69
	ds_read_b128 v[70:73], v2 offset:16976
	s_waitcnt lgkmcnt(11)
	v_fma_f32 v74, -v204, v52, v74
	v_fma_f32 v75, -v205, v53, v75
	v_fma_f32 v0, -v206, v54, v0
	v_fma_f32 v69, -v207, v55, v69
	ds_read_b128 v[204:207], v2 offset:16992
	s_waitcnt lgkmcnt(11)
	v_fma_f32 v74, -v208, v56, v74
	v_fma_f32 v75, -v209, v57, v75
	v_fma_f32 v0, -v210, v58, v0
	v_fma_f32 v69, -v211, v59, v69
	ds_read_b128 v[208:211], v2 offset:17008
	s_waitcnt lgkmcnt(11)
	v_fma_f32 v74, -v212, v60, v74
	v_fma_f32 v75, -v213, v61, v75
	v_fma_f32 v0, -v214, v62, v0
	v_fma_f32 v69, -v215, v63, v69
	ds_read_b128 v[212:215], v2 offset:17024
	s_waitcnt lgkmcnt(11)
	v_fma_f32 v74, -v216, v64, v74
	ds_read_b128 v[216:219], v2 offset:17040
	v_add_f32_e32 v74, v74, v75
	v_add_f32_e32 v0, v0, v69
	v_add_f32_e32 v65, v74, v0
	s_waitcnt lgkmcnt(11)
	v_fma_f32 v74, -v220, v4, v66
	v_fma_f32 v75, -v221, v5, 0
	v_fma_f32 v0, -v222, v6, 0
	v_fma_f32 v69, -v223, v7, 0
	ds_read_b128 v[220:223], v2 offset:17056
	s_waitcnt lgkmcnt(11)
	v_fma_f32 v74, -v224, v8, v74
	v_fma_f32 v75, -v225, v9, v75
	v_fma_f32 v0, -v226, v10, v0
	v_fma_f32 v69, -v227, v11, v69
	ds_read_b128 v[224:227], v2 offset:17072
	s_waitcnt lgkmcnt(11)
	v_fma_f32 v74, -v228, v12, v74
	v_fma_f32 v75, -v229, v13, v75
	v_fma_f32 v0, -v230, v14, v0
	v_fma_f32 v69, -v231, v15, v69
	ds_read_b128 v[228:231], v2 offset:17088
	s_waitcnt lgkmcnt(11)
	v_fma_f32 v74, -v232, v16, v74
	v_fma_f32 v75, -v233, v17, v75
	v_fma_f32 v0, -v234, v18, v0
	v_fma_f32 v69, -v235, v19, v69
	ds_read_b128 v[232:235], v2 offset:17104
	s_waitcnt lgkmcnt(11)
	v_fma_f32 v74, -v236, v20, v74
	v_fma_f32 v75, -v237, v21, v75
	v_fma_f32 v0, -v238, v22, v0
	v_fma_f32 v69, -v239, v23, v69
	ds_read_b128 v[236:239], v2 offset:17136
	s_waitcnt lgkmcnt(11)
	v_fma_f32 v74, -v240, v24, v74
	v_fma_f32 v75, -v241, v25, v75
	v_fma_f32 v0, -v242, v26, v0
	v_fma_f32 v69, -v243, v27, v69
	ds_read_b128 v[240:243], v2 offset:17152
	s_waitcnt lgkmcnt(11)
	v_fma_f32 v74, -v180, v28, v74
	v_fma_f32 v75, -v181, v29, v75
	v_fma_f32 v0, -v182, v30, v0
	v_fma_f32 v69, -v183, v31, v69
	ds_read_b128 v[180:183], v2 offset:17168
	s_waitcnt lgkmcnt(11)
; #define LAS __attribute__((address_space(3)))
; __device__ __forceinline__ unsigned pk2(float lo, float hi) { f32x2_t v = {lo, hi}; bf16x2_t b = __builtin_convertvector(v, bf16x2_t); return __builtin_bit_cast(unsigned, b); }
; __device__ __forceinline__ void gdn_prep_unit(const Args& c, int ug, int l, LAS unsigned char* lds) {
;     ...
;         for (int i = 1; i < 64; ++i) {
;             float s0 = x[i], s1 = 0.f, s2 = 0.f, s3 = 0.f;
; #pragma unroll
;             for (int m4 = 0; m4 < i; m4 += 4) {
;                 const f32x4 mv = *(const LAS f32x4*)(Mz + i * 68 + m4);
;                 s0 -= mv.x * x[m4];
;                 if (m4 + 1 < i) s1 -= mv.y * x[m4 + 1];
;                 if (m4 + 2 < i) s2 -= mv.z * x[m4 + 2];
;                 if (m4 + 3 < i) s3 -= mv.w * x[m4 + 3];
;             }
;             const float s = (s0 + s1) + (s2 + s3);
;             x[i] = s;
;         }
;         if (!isw) {
;             bf16* ut = ((bf16*)(wsl + WS_H)) + (size_t)ug * 8192 + col * 64;
; #pragma unroll
;             for (int i = 0; i < 64; i += 8) { u32x4v o; o.x = pk2(x[i], x[i + 1]); o.y = pk2(x[i + 2], x[i + 3]); o.z = pk2(x[i + 4], x[i + 5]); o.w = pk2(x[i + 6], x[i + 7]); *(u32x4v*)(ut + i) = o; }
	v_fma_f32 v74, -v70, v32, v74
	v_fma_f32 v75, -v71, v33, v75
	v_fma_f32 v0, -v72, v34, v0
	v_fma_f32 v69, -v73, v35, v69
	ds_read_b128 v[70:73], v2 offset:17184
	s_waitcnt lgkmcnt(11)
	v_fma_f32 v74, -v204, v36, v74
	v_fma_f32 v75, -v205, v37, v75
	v_fma_f32 v0, -v206, v38, v0
	v_fma_f32 v69, -v207, v39, v69
	ds_read_b128 v[204:207], v2 offset:17200
	s_waitcnt lgkmcnt(11)
	v_fma_f32 v74, -v208, v40, v74
	v_fma_f32 v75, -v209, v41, v75
	v_fma_f32 v0, -v210, v42, v0
	v_fma_f32 v69, -v211, v43, v69
	ds_read_b128 v[208:211], v2 offset:17216
	s_waitcnt lgkmcnt(11)
	v_fma_f32 v74, -v212, v44, v74
	v_fma_f32 v75, -v213, v45, v75
	v_fma_f32 v0, -v214, v46, v0
	v_fma_f32 v69, -v215, v47, v69
	ds_read_b128 v[212:215], v2 offset:17232
	s_waitcnt lgkmcnt(11)
	v_fma_f32 v74, -v216, v48, v74
	v_fma_f32 v75, -v217, v49, v75
	v_fma_f32 v0, -v218, v50, v0
	v_fma_f32 v69, -v219, v51, v69
	ds_read_b128 v[216:219], v2 offset:17248
	s_waitcnt lgkmcnt(11)
	v_fma_f32 v74, -v220, v52, v74
	v_fma_f32 v75, -v221, v53, v75
	v_fma_f32 v0, -v222, v54, v0
	v_fma_f32 v69, -v223, v55, v69
	ds_read_b128 v[220:223], v2 offset:17264
	s_waitcnt lgkmcnt(11)
	v_fma_f32 v74, -v224, v56, v74
	v_fma_f32 v75, -v225, v57, v75
	v_fma_f32 v0, -v226, v58, v0
	v_fma_f32 v69, -v227, v59, v69
	ds_read_b128 v[224:227], v2 offset:17280
	s_waitcnt lgkmcnt(11)
	v_fma_f32 v74, -v228, v60, v74
	v_fma_f32 v75, -v229, v61, v75
	v_fma_f32 v0, -v230, v62, v0
	v_fma_f32 v69, -v231, v63, v69
	ds_read_b128 v[228:231], v2 offset:17296
	s_waitcnt lgkmcnt(11)
	v_fma_f32 v74, -v232, v64, v74
	v_fma_f32 v75, -v233, v65, v75
	ds_read_b128 v[232:235], v2 offset:17312
	v_add_f32_e32 v74, v74, v75
	v_add_f32_e32 v0, v0, v69
	v_add_f32_e32 v66, v74, v0
	s_waitcnt lgkmcnt(11)
	v_fma_f32 v74, -v236, v4, v67
	v_fma_f32 v75, -v237, v5, 0
	v_fma_f32 v0, -v238, v6, 0
	v_fma_f32 v69, -v239, v7, 0
	ds_read_b128 v[236:239], v2 offset:17328
	s_waitcnt lgkmcnt(11)
	v_fma_f32 v74, -v240, v8, v74
	v_fma_f32 v75, -v241, v9, v75
	v_fma_f32 v0, -v242, v10, v0
	v_fma_f32 v69, -v243, v11, v69
	ds_read_b128 v[240:243], v2 offset:17344
	s_waitcnt lgkmcnt(11)
	v_fma_f32 v74, -v180, v12, v74
	v_fma_f32 v75, -v181, v13, v75
	v_fma_f32 v0, -v182, v14, v0
	v_fma_f32 v69, -v183, v15, v69
	ds_read_b128 v[180:183], v2 offset:17360
	s_waitcnt lgkmcnt(11)
	v_fma_f32 v74, -v70, v16, v74
	v_fma_f32 v75, -v71, v17, v75
	v_fma_f32 v0, -v72, v18, v0
	v_fma_f32 v69, -v73, v19, v69
	ds_read_b128 v[70:73], v2 offset:17376
	s_waitcnt lgkmcnt(11)
	v_fma_f32 v74, -v204, v20, v74
	v_fma_f32 v75, -v205, v21, v75
	v_fma_f32 v0, -v206, v22, v0
	v_fma_f32 v69, -v207, v23, v69
	s_waitcnt lgkmcnt(10)
	v_fma_f32 v74, -v208, v24, v74
	v_fma_f32 v75, -v209, v25, v75
	v_fma_f32 v0, -v210, v26, v0
	v_fma_f32 v69, -v211, v27, v69
	s_waitcnt lgkmcnt(9)
	v_fma_f32 v74, -v212, v28, v74
	v_fma_f32 v75, -v213, v29, v75
	v_fma_f32 v0, -v214, v30, v0
	v_fma_f32 v69, -v215, v31, v69
	s_waitcnt lgkmcnt(8)
	v_fma_f32 v74, -v216, v32, v74
	v_fma_f32 v75, -v217, v33, v75
	v_fma_f32 v0, -v218, v34, v0
	v_fma_f32 v69, -v219, v35, v69
	s_waitcnt lgkmcnt(7)
	v_fma_f32 v74, -v220, v36, v74
	v_fma_f32 v75, -v221, v37, v75
	v_fma_f32 v0, -v222, v38, v0
	v_fma_f32 v69, -v223, v39, v69
	s_waitcnt lgkmcnt(6)
	v_fma_f32 v74, -v224, v40, v74
	v_fma_f32 v75, -v225, v41, v75
	v_fma_f32 v0, -v226, v42, v0
	v_fma_f32 v69, -v227, v43, v69
	s_waitcnt lgkmcnt(5)
	v_fma_f32 v74, -v228, v44, v74
	v_fma_f32 v75, -v229, v45, v75
	v_fma_f32 v0, -v230, v46, v0
	v_fma_f32 v69, -v231, v47, v69
	s_waitcnt lgkmcnt(4)
	v_fma_f32 v74, -v232, v48, v74
	v_fma_f32 v75, -v233, v49, v75
	v_fma_f32 v0, -v234, v50, v0
	v_fma_f32 v69, -v235, v51, v69
	s_waitcnt lgkmcnt(3)
	v_fma_f32 v74, -v236, v52, v74
	v_fma_f32 v75, -v237, v53, v75
	v_fma_f32 v0, -v238, v54, v0
	v_fma_f32 v69, -v239, v55, v69
	s_waitcnt lgkmcnt(2)
	v_fma_f32 v74, -v240, v56, v74
	v_fma_f32 v75, -v241, v57, v75
	v_fma_f32 v0, -v242, v58, v0
	v_fma_f32 v69, -v243, v59, v69
	s_waitcnt lgkmcnt(1)
	v_fma_f32 v74, -v180, v60, v74
	v_fma_f32 v75, -v181, v61, v75
	v_fma_f32 v0, -v182, v62, v0
	v_fma_f32 v69, -v183, v63, v69
	s_waitcnt lgkmcnt(0)
	v_fma_f32 v74, -v70, v64, v74
	v_fma_f32 v75, -v71, v65, v75
	v_fma_f32 v0, -v72, v66, v0
	v_add_f32_e32 v74, v74, v75
	v_add_f32_e32 v0, v0, v69
	v_add_f32_e32 v67, v74, v0
	v_and_b32_e32 v74, 0x7f, v149
	v_mov_b32_e32 v75, 0
	s_cmp_eq_u32 s2, 0
	s_cbranch_scc0 .Lgdn4_wstore
	v_lshlrev_b32_e32 v74, 7, v74
	v_lshl_add_u64 v[70:71], s[42:43], 0, v[74:75]
	v_lshl_add_u64 v[70:71], v[70:71], 0, s[10:11]
	v_cvt_pk_bf16_f32 v204, v4, v5
	v_cvt_pk_bf16_f32 v205, v6, v7
	v_cvt_pk_bf16_f32 v206, v8, v9
	v_cvt_pk_bf16_f32 v207, v10, v11
	global_store_dwordx4 v[70:71], v[204:207], off
	v_cvt_pk_bf16_f32 v208, v12, v13
	v_cvt_pk_bf16_f32 v209, v14, v15
	v_cvt_pk_bf16_f32 v210, v16, v17
	v_cvt_pk_bf16_f32 v211, v18, v19
	global_store_dwordx4 v[70:71], v[208:211], off offset:16
	v_cvt_pk_bf16_f32 v212, v20, v21
	v_cvt_pk_bf16_f32 v213, v22, v23
	v_cvt_pk_bf16_f32 v214, v24, v25
	v_cvt_pk_bf16_f32 v215, v26, v27
	global_store_dwordx4 v[70:71], v[212:215], off offset:32
	v_cvt_pk_bf16_f32 v216, v28, v29
	v_cvt_pk_bf16_f32 v217, v30, v31
	v_cvt_pk_bf16_f32 v218, v32, v33
	v_cvt_pk_bf16_f32 v219, v34, v35
	global_store_dwordx4 v[70:71], v[216:219], off offset:48
	v_cvt_pk_bf16_f32 v220, v36, v37
	v_cvt_pk_bf16_f32 v221, v38, v39
	v_cvt_pk_bf16_f32 v222, v40, v41
	v_cvt_pk_bf16_f32 v223, v42, v43
	global_store_dwordx4 v[70:71], v[220:223], off offset:64
	v_cvt_pk_bf16_f32 v224, v44, v45
	v_cvt_pk_bf16_f32 v225, v46, v47
	v_cvt_pk_bf16_f32 v226, v48, v49
	v_cvt_pk_bf16_f32 v227, v50, v51
	global_store_dwordx4 v[70:71], v[224:227], off offset:80
	v_cvt_pk_bf16_f32 v228, v52, v53
	v_cvt_pk_bf16_f32 v229, v54, v55
	v_cvt_pk_bf16_f32 v230, v56, v57
	v_cvt_pk_bf16_f32 v231, v58, v59
	global_store_dwordx4 v[70:71], v[228:231], off offset:96
	v_cvt_pk_bf16_f32 v232, v60, v61
	v_cvt_pk_bf16_f32 v233, v62, v63
	v_cvt_pk_bf16_f32 v234, v64, v65
	v_cvt_pk_bf16_f32 v235, v66, v67
	global_store_dwordx4 v[70:71], v[232:235], off offset:112
	s_branch .Lgdn4_done
; __device__ __forceinline__ unsigned f2bf(float f) { return pk2(f, f) & 0xffffu; }
; __device__ __forceinline__ void gdn_prep_unit(const Args& c, int ug, int l, LAS unsigned char* lds) {
;     ...
;         } else {
;             bf16* gw = ((bf16*)(wsl + WS_H + 16 * MiB)) + (size_t)ug * 8192 + col;
; #pragma unroll
;             for (int i = 0; i < 64; ++i) gw[i * 128] = (bf16)f2bf(x[i]);
;         }
.Lgdn4_wstore:
	v_lshlrev_b32_e32 v74, 1, v74
	v_lshl_add_u64 v[72:73], s[42:43], 0, v[74:75]
	s_add_u32 s0, s10, 0x1000000
	s_addc_u32 s1, s11, 0
	v_lshl_add_u64 v[72:73], v[72:73], 0, s[0:1]
	s_mov_b64 s[0:1], 0x1000
	v_cvt_pk_bf16_f32 v204, v4, v4
	global_store_short v[72:73], v204, off
	v_cvt_pk_bf16_f32 v205, v5, v5
	global_store_short v[72:73], v205, off offset:256
	v_cvt_pk_bf16_f32 v206, v6, v6
	global_store_short v[72:73], v206, off offset:512
	v_cvt_pk_bf16_f32 v207, v7, v7
	global_store_short v[72:73], v207, off offset:768
	v_cvt_pk_bf16_f32 v208, v8, v8
	global_store_short v[72:73], v208, off offset:1024
	v_cvt_pk_bf16_f32 v209, v9, v9
	global_store_short v[72:73], v209, off offset:1280
	v_cvt_pk_bf16_f32 v210, v10, v10
	global_store_short v[72:73], v210, off offset:1536
	v_cvt_pk_bf16_f32 v211, v11, v11
	global_store_short v[72:73], v211, off offset:1792
	v_cvt_pk_bf16_f32 v212, v12, v12
	global_store_short v[72:73], v212, off offset:2048
	v_cvt_pk_bf16_f32 v213, v13, v13
	global_store_short v[72:73], v213, off offset:2304
	v_cvt_pk_bf16_f32 v214, v14, v14
	global_store_short v[72:73], v214, off offset:2560
	v_cvt_pk_bf16_f32 v215, v15, v15
	global_store_short v[72:73], v215, off offset:2816
	v_cvt_pk_bf16_f32 v216, v16, v16
	global_store_short v[72:73], v216, off offset:3072
	v_cvt_pk_bf16_f32 v217, v17, v17
	global_store_short v[72:73], v217, off offset:3328
	v_cvt_pk_bf16_f32 v218, v18, v18
	global_store_short v[72:73], v218, off offset:3584
	v_cvt_pk_bf16_f32 v219, v19, v19
	global_store_short v[72:73], v219, off offset:3840
	v_lshl_add_u64 v[72:73], v[72:73], 0, s[0:1]
	v_cvt_pk_bf16_f32 v204, v20, v20
	global_store_short v[72:73], v204, off
	v_cvt_pk_bf16_f32 v205, v21, v21
	global_store_short v[72:73], v205, off offset:256
	v_cvt_pk_bf16_f32 v206, v22, v22
	global_store_short v[72:73], v206, off offset:512
	v_cvt_pk_bf16_f32 v207, v23, v23
	global_store_short v[72:73], v207, off offset:768
	v_cvt_pk_bf16_f32 v208, v24, v24
	global_store_short v[72:73], v208, off offset:1024
	v_cvt_pk_bf16_f32 v209, v25, v25
	global_store_short v[72:73], v209, off offset:1280
	v_cvt_pk_bf16_f32 v210, v26, v26
	global_store_short v[72:73], v210, off offset:1536
	v_cvt_pk_bf16_f32 v211, v27, v27
	global_store_short v[72:73], v211, off offset:1792
	v_cvt_pk_bf16_f32 v212, v28, v28
	global_store_short v[72:73], v212, off offset:2048
	v_cvt_pk_bf16_f32 v213, v29, v29
	global_store_short v[72:73], v213, off offset:2304
	v_cvt_pk_bf16_f32 v214, v30, v30
	global_store_short v[72:73], v214, off offset:2560
	v_cvt_pk_bf16_f32 v215, v31, v31
	global_store_short v[72:73], v215, off offset:2816
	v_cvt_pk_bf16_f32 v216, v32, v32
	global_store_short v[72:73], v216, off offset:3072
	v_cvt_pk_bf16_f32 v217, v33, v33
	global_store_short v[72:73], v217, off offset:3328
	v_cvt_pk_bf16_f32 v218, v34, v34
	global_store_short v[72:73], v218, off offset:3584
	v_cvt_pk_bf16_f32 v219, v35, v35
	global_store_short v[72:73], v219, off offset:3840
	v_lshl_add_u64 v[72:73], v[72:73], 0, s[0:1]
	v_cvt_pk_bf16_f32 v204, v36, v36
	global_store_short v[72:73], v204, off
	v_cvt_pk_bf16_f32 v205, v37, v37
	global_store_short v[72:73], v205, off offset:256
	v_cvt_pk_bf16_f32 v206, v38, v38
	global_store_short v[72:73], v206, off offset:512
	v_cvt_pk_bf16_f32 v207, v39, v39
	global_store_short v[72:73], v207, off offset:768
	v_cvt_pk_bf16_f32 v208, v40, v40
	global_store_short v[72:73], v208, off offset:1024
	v_cvt_pk_bf16_f32 v209, v41, v41
	global_store_short v[72:73], v209, off offset:1280
	v_cvt_pk_bf16_f32 v210, v42, v42
	global_store_short v[72:73], v210, off offset:1536
	v_cvt_pk_bf16_f32 v211, v43, v43
	global_store_short v[72:73], v211, off offset:1792
	v_cvt_pk_bf16_f32 v212, v44, v44
	global_store_short v[72:73], v212, off offset:2048
	v_cvt_pk_bf16_f32 v213, v45, v45
	global_store_short v[72:73], v213, off offset:2304
	v_cvt_pk_bf16_f32 v214, v46, v46
	global_store_short v[72:73], v214, off offset:2560
	v_cvt_pk_bf16_f32 v215, v47, v47
	global_store_short v[72:73], v215, off offset:2816
	v_cvt_pk_bf16_f32 v216, v48, v48
	global_store_short v[72:73], v216, off offset:3072
	v_cvt_pk_bf16_f32 v217, v49, v49
	global_store_short v[72:73], v217, off offset:3328
	v_cvt_pk_bf16_f32 v218, v50, v50
	global_store_short v[72:73], v218, off offset:3584
	v_cvt_pk_bf16_f32 v219, v51, v51
	global_store_short v[72:73], v219, off offset:3840
	v_lshl_add_u64 v[72:73], v[72:73], 0, s[0:1]
	v_cvt_pk_bf16_f32 v204, v52, v52
	global_store_short v[72:73], v204, off
	v_cvt_pk_bf16_f32 v205, v53, v53
	global_store_short v[72:73], v205, off offset:256
	v_cvt_pk_bf16_f32 v206, v54, v54
	global_store_short v[72:73], v206, off offset:512
	v_cvt_pk_bf16_f32 v207, v55, v55
	global_store_short v[72:73], v207, off offset:768
	v_cvt_pk_bf16_f32 v208, v56, v56
	global_store_short v[72:73], v208, off offset:1024
	v_cvt_pk_bf16_f32 v209, v57, v57
	global_store_short v[72:73], v209, off offset:1280
	v_cvt_pk_bf16_f32 v210, v58, v58
	global_store_short v[72:73], v210, off offset:1536
	v_cvt_pk_bf16_f32 v211, v59, v59
	global_store_short v[72:73], v211, off offset:1792
	v_cvt_pk_bf16_f32 v212, v60, v60
	global_store_short v[72:73], v212, off offset:2048
	v_cvt_pk_bf16_f32 v213, v61, v61
	global_store_short v[72:73], v213, off offset:2304
	v_cvt_pk_bf16_f32 v214, v62, v62
	global_store_short v[72:73], v214, off offset:2560
	v_cvt_pk_bf16_f32 v215, v63, v63
	global_store_short v[72:73], v215, off offset:2816
	v_cvt_pk_bf16_f32 v216, v64, v64
	global_store_short v[72:73], v216, off offset:3072
	v_cvt_pk_bf16_f32 v217, v65, v65
	global_store_short v[72:73], v217, off offset:3328
	v_cvt_pk_bf16_f32 v218, v66, v66
	global_store_short v[72:73], v218, off offset:3584
	v_cvt_pk_bf16_f32 v219, v67, v67
	global_store_short v[72:73], v219, off offset:3840
.Lgdn4_done:
	s_branch .LBB0_623
.LBB0_923:
	s_waitcnt vmcnt(0)
	v_readlane_b32 s22, v253, 48
	v_readlane_b32 s12, v247, 29
	s_barrier
